# GEMM K-loops: B0 fragment reads of phases 1 and 5 issued one phase earlier to balance LDS traffic, with DMA bounds for the other wave group
# baseline (speedup 1.0000x reference)
; #define PG8_STAGE(bufoff, gbase, voff) do { _Pragma("unroll") for (int _i = 0; _i < 2; ++_i) \
;     __builtin_amdgcn_global_load_lds((const unsigned*)((const char*)(gbase) + (voff)[_i]), (LAS unsigned*)(lds + (bufoff) + ldsw + _i * 8192), 16, 0, 0); } while (0)
; #define PG8_LDA(dst, b, h) do { _Pragma("unroll") for (int m = 0; m < 4; ++m) _Pragma("unroll") for (int k = 0; k < 2; ++k) dst[m][k] = *(const LAS bf16x8*)(lds + PG8_SA(b, h) + aoff + m * 2048 + k * 1024); } while (0)
; #define PG8_LDB(dst, b, h) do { _Pragma("unroll") for (int n = 0; n < 2; ++n) _Pragma("unroll") for (int k = 0; k < 2; ++k) dst[n][k] = *(const LAS bf16x8*)(lds + PG8_SB(b, h) + boff + n * 2048 + k * 1024); } while (0)
; #define PG8_MMA(ai, bj, At, Bt) do { __builtin_amdgcn_s_setprio(1); _Pragma("unroll") for (int m = 0; m < 4; ++m) _Pragma("unroll") for (int n = 0; n < 2; ++n) _Pragma("unroll") for (int k = 0; k < 2; ++k) \
;     acc[ai][bj][m][n] = __builtin_amdgcn_mfma_f32_16x16x32_bf16(Bt[n][k], At[m][k], acc[ai][bj][m][n], 0, 0, 0); __builtin_amdgcn_s_setprio(0); } while (0)
; #define PG8_WAIT_L(n) asm volatile("s_waitcnt lgkmcnt(" #n ")" ::: "memory")
; #define PG8_BAR __builtin_amdgcn_s_barrier()
; #define PG8_SCHED __builtin_amdgcn_sched_barrier(0)
; template <class Epi, class Sched>
; DI void gemm_phase(LAS unsigned char* lds, const Gemm g, const Sched& S, const Epi& E) {
;     ...
;     for (int t = 0; t < nt; t += 2) {
;       const bool last = (t == nt - 2);
;       const char* a1 = cA + (size_t)(t + 1) * kstep;
;       const char* a2 = last ? nA : cA + (size_t)(t + 2) * kstep; const char* b2 = last ? nB : cB + (size_t)(t + 2) * kstep;
;       const char* a3 = a2 + kstep; const char* b3 = b2 + kstep;
;       PG8_LDB(B0, 0, 0); PG8_SCHED; PG8_LDA(At, 0, 0); PG8_STAGE(PG8_SA(1, 1), a1 + hstep, voffA);
;       PG8_WAIT_L(8); PG8_BAR; PG8_WAIT_L(0); PG8_MMA(0, 0, At, B0); PG8_BAR; PG8_SCHED;
;       PG8_LDB(B1, 0, 1); PG8_STAGE(PG8_SB(0, 0), b2, voffB);
;       PG8_BAR; PG8_WAIT_L(0); PG8_MMA(0, 1, At, B1); PG8_BAR;
;     ...
; #pragma unroll
;     for (int a = 0; a < 2; ++a)
; #pragma unroll
;       for (int b = 0; b < 2; ++b)
; #pragma unroll
;         for (int m = 0; m < 4; ++m)
; #pragma unroll
;           for (int n = 0; n < 2; ++n) acc[a][b][m][n] = (f32x4){0.f, 0.f, 0.f, 0.f};
;     cur = nxt; cA = nA; cB = nB; ++ui;
.LBB0_369:
	v_readlane_b32 s18, v239, 44
	v_readlane_b32 s19, v239, 45
	s_ashr_i32 s15, s14, 31
	s_mov_b32 s50, -2
	v_mov_b64_e32 v[0:1], s[18:19]
	v_cmp_lt_i64_e32 vcc, s[16:17], v[0:1]
	s_lshl_b64 s[16:17], s[14:15], 19
	s_add_u32 s16, s35, s16
	s_addc_u32 s17, s38, s17
	s_and_b64 s[18:19], vcc, exec
	s_cselect_b32 s15, s17, s3
	s_cselect_b32 s29, s16, s2
	s_ashr_i32 s13, s12, 31
	s_lshl_b64 s[18:19], s[12:13], 19
	s_add_u32 s18, s24, s18
	s_addc_u32 s19, s39, s19
	s_and_b64 s[20:21], vcc, exec
	s_cselect_b32 s13, s19, s5
	s_cselect_b32 s36, s18, s4
	s_add_u32 s2, s2, 0x40080
	s_addc_u32 s3, s3, 0
	s_add_u32 s37, s4, 0x100
	v_mov_b32_e32 v0, 0
	s_addc_u32 s49, s5, 0
	v_mov_b32_e32 v1, v0
	v_mov_b64_e32 v[2:3], v[0:1]
	v_mov_b64_e32 v[4:5], v[0:1]
	v_mov_b64_e32 v[6:7], v[0:1]
	v_mov_b64_e32 v[8:9], v[0:1]
	v_mov_b64_e32 v[10:11], v[0:1]
	v_mov_b64_e32 v[12:13], v[0:1]
	v_mov_b64_e32 v[14:15], v[0:1]
	v_mov_b64_e32 v[16:17], v[0:1]
	v_mov_b64_e32 v[18:19], v[0:1]
	v_mov_b64_e32 v[20:21], v[0:1]
	v_mov_b64_e32 v[22:23], v[0:1]
	v_mov_b64_e32 v[24:25], v[0:1]
	v_mov_b64_e32 v[26:27], v[0:1]
	v_mov_b64_e32 v[28:29], v[0:1]
	v_mov_b64_e32 v[30:31], v[0:1]
	v_mov_b64_e32 v[32:33], v[0:1]
	v_mov_b64_e32 v[34:35], v[0:1]
	v_mov_b64_e32 v[36:37], v[0:1]
	v_mov_b64_e32 v[38:39], v[0:1]
	v_mov_b64_e32 v[40:41], v[0:1]
	v_mov_b64_e32 v[42:43], v[0:1]
	v_mov_b64_e32 v[44:45], v[0:1]
	v_mov_b64_e32 v[46:47], v[0:1]
	v_mov_b64_e32 v[48:49], v[0:1]
	v_mov_b64_e32 v[50:51], v[0:1]
	v_mov_b64_e32 v[52:53], v[0:1]
	v_mov_b64_e32 v[54:55], v[0:1]
	v_mov_b64_e32 v[56:57], v[0:1]
	v_mov_b64_e32 v[58:59], v[0:1]
	v_mov_b64_e32 v[60:61], v[0:1]
	v_mov_b64_e32 v[62:63], v[0:1]
	v_mov_b64_e32 v[64:65], v[0:1]
	v_mov_b64_e32 v[66:67], v[0:1]
	v_mov_b64_e32 v[68:69], v[0:1]
	v_mov_b64_e32 v[70:71], v[0:1]
	v_mov_b64_e32 v[72:73], v[0:1]
	v_mov_b64_e32 v[74:75], v[0:1]
	v_mov_b64_e32 v[76:77], v[0:1]
	v_mov_b64_e32 v[78:79], v[0:1]
	v_mov_b64_e32 v[80:81], v[0:1]
	v_mov_b64_e32 v[82:83], v[0:1]
	v_mov_b64_e32 v[84:85], v[0:1]
	v_mov_b64_e32 v[86:87], v[0:1]
	v_mov_b64_e32 v[88:89], v[0:1]
	v_mov_b64_e32 v[90:91], v[0:1]
	v_mov_b64_e32 v[92:93], v[0:1]
	v_mov_b64_e32 v[94:95], v[0:1]
	v_mov_b64_e32 v[96:97], v[0:1]
	v_mov_b64_e32 v[98:99], v[0:1]
	v_mov_b64_e32 v[100:101], v[0:1]
	v_mov_b64_e32 v[102:103], v[0:1]
	v_mov_b64_e32 v[104:105], v[0:1]
	v_mov_b64_e32 v[106:107], v[0:1]
	v_mov_b64_e32 v[108:109], v[0:1]
	v_mov_b64_e32 v[110:111], v[0:1]
	v_mov_b64_e32 v[112:113], v[0:1]
	v_mov_b64_e32 v[114:115], v[0:1]
	v_mov_b64_e32 v[116:117], v[0:1]
	v_mov_b64_e32 v[118:119], v[0:1]
	v_mov_b64_e32 v[120:121], v[0:1]
	v_mov_b64_e32 v[122:123], v[0:1]
	v_mov_b64_e32 v[124:125], v[0:1]
	v_mov_b64_e32 v[126:127], v[0:1]
	v_add_u32_e32 v228, 0x10000, v155
	v_add_u32_e32 v229, 0x14000, v155
	v_add_u32_e32 v230, 0x18000, v155
	v_add_u32_e32 v231, 0x1c000, v155
	ds_read_b128 v[128:131], v228
	ds_read_b128 v[146:149], v228 offset:1024
	ds_read_b128 v[150:153], v228 offset:2048
	ds_read_b128 v[160:163], v228 offset:3072
.LBB0_370:
	s_add_u32 s4, s2, 0xfffc0080
	s_addc_u32 s5, s3, -1
	s_add_i32 s51, 0, 0x10000
	s_cmp_eq_u32 s50, 12
	s_cselect_b32 s21, s15, s5
	s_cselect_b32 s20, s29, s4
	s_cselect_b32 s5, s13, s49
	s_cselect_b32 s4, s36, s37
	s_add_i32 m0, s40, 0xc000
	ds_read_b128 v[164:167], v158
	ds_read_b128 v[168:171], v158 offset:1024
	ds_read_b128 v[172:175], v158 offset:2048
	ds_read_b128 v[176:179], v158 offset:3072
	ds_read_b128 v[196:199], v158 offset:4096
	ds_read_b128 v[200:203], v158 offset:5120
	ds_read_b128 v[204:207], v158 offset:6144
	ds_read_b128 v[208:211], v158 offset:7168
	global_load_lds_dwordx4 v140, s[2:3]
	s_add_i32 m0, s40, 0xe000
	s_nop 0
	global_load_lds_dwordx4 v142, s[2:3]
	s_waitcnt lgkmcnt(8)
	s_barrier
	s_waitcnt lgkmcnt(0)
	v_mfma_f32_16x16x32_bf16 v[124:127], v[128:131], v[164:167], v[124:127]
	v_mfma_f32_16x16x32_bf16 v[120:123], v[150:153], v[164:167], v[120:123]
	v_mfma_f32_16x16x32_bf16 v[108:111], v[128:131], v[172:175], v[108:111]
	v_mfma_f32_16x16x32_bf16 v[104:107], v[150:153], v[172:175], v[104:107]
	v_mfma_f32_16x16x32_bf16 v[92:95], v[128:131], v[196:199], v[92:95]
	v_mfma_f32_16x16x32_bf16 v[88:91], v[150:153], v[196:199], v[88:91]
	v_mfma_f32_16x16x32_bf16 v[76:79], v[128:131], v[204:207], v[76:79]
	v_mfma_f32_16x16x32_bf16 v[72:75], v[150:153], v[204:207], v[72:75]
	v_mfma_f32_16x16x32_bf16 v[124:127], v[146:149], v[168:171], v[124:127]
	v_mfma_f32_16x16x32_bf16 v[120:123], v[160:163], v[168:171], v[120:123]
	v_mfma_f32_16x16x32_bf16 v[108:111], v[146:149], v[176:179], v[108:111]
	v_mfma_f32_16x16x32_bf16 v[104:107], v[160:163], v[176:179], v[104:107]
	v_mfma_f32_16x16x32_bf16 v[92:95], v[146:149], v[200:203], v[92:95]
	v_mfma_f32_16x16x32_bf16 v[88:91], v[160:163], v[200:203], v[88:91]
	v_mfma_f32_16x16x32_bf16 v[76:79], v[146:149], v[208:211], v[76:79]
	v_mfma_f32_16x16x32_bf16 v[72:75], v[160:163], v[208:211], v[72:75]
	s_barrier
	s_add_i32 s54, 0, 0x14000
	s_add_i32 s51, s51, s34
	s_add_u32 vcc_lo, s4, s0
	s_addc_u32 vcc_hi, s5, s1
	s_mov_b32 m0, s51
	ds_read_b128 v[212:215], v229
	ds_read_b128 v[216:219], v229 offset:1024
	ds_read_b128 v[220:223], v229 offset:2048
	ds_read_b128 v[224:227], v229 offset:3072
	global_load_lds_dwordx4 v136, s[4:5]
	s_add_i32 m0, s51, 0x2000
	s_nop 0
	global_load_lds_dwordx4 v132, s[4:5]
	s_barrier
; #define PG8_STAGE(bufoff, gbase, voff) do { _Pragma("unroll") for (int _i = 0; _i < 2; ++_i) \
;     __builtin_amdgcn_global_load_lds((const unsigned*)((const char*)(gbase) + (voff)[_i]), (LAS unsigned*)(lds + (bufoff) + ldsw + _i * 8192), 16, 0, 0); } while (0)
; #define PG8_LDA(dst, b, h) do { _Pragma("unroll") for (int m = 0; m < 4; ++m) _Pragma("unroll") for (int k = 0; k < 2; ++k) dst[m][k] = *(const LAS bf16x8*)(lds + PG8_SA(b, h) + aoff + m * 2048 + k * 1024); } while (0)
; #define PG8_LDB(dst, b, h) do { _Pragma("unroll") for (int n = 0; n < 2; ++n) _Pragma("unroll") for (int k = 0; k < 2; ++k) dst[n][k] = *(const LAS bf16x8*)(lds + PG8_SB(b, h) + boff + n * 2048 + k * 1024); } while (0)
; #define PG8_MMA(ai, bj, At, Bt) do { __builtin_amdgcn_s_setprio(1); _Pragma("unroll") for (int m = 0; m < 4; ++m) _Pragma("unroll") for (int n = 0; n < 2; ++n) _Pragma("unroll") for (int k = 0; k < 2; ++k) \
;     acc[ai][bj][m][n] = __builtin_amdgcn_mfma_f32_16x16x32_bf16(Bt[n][k], At[m][k], acc[ai][bj][m][n], 0, 0, 0); __builtin_amdgcn_s_setprio(0); } while (0)
; #define PG8_WAIT_V(n) asm volatile("s_waitcnt vmcnt(" #n ")" ::: "memory")
; #define PG8_WAIT_L(n) asm volatile("s_waitcnt lgkmcnt(" #n ")" ::: "memory")
; #define PG8_BAR __builtin_amdgcn_s_barrier()
; #define PG8_SCHED __builtin_amdgcn_sched_barrier(0)
; template <class Epi, class Sched>
; DI void gemm_phase(LAS unsigned char* lds, const Gemm g, const Sched& S, const Epi& E) {
;     ...
;       PG8_LDB(B1, 0, 1); PG8_STAGE(PG8_SB(0, 0), b2, voffB);
;       PG8_BAR; PG8_WAIT_L(0); PG8_MMA(0, 1, At, B1); PG8_BAR;
;       PG8_LDA(At, 0, 1); PG8_STAGE(PG8_SA(0, 0), a2, voffA);
;       PG8_BAR; PG8_WAIT_L(0); PG8_MMA(1, 0, At, B0); PG8_BAR; PG8_SCHED;
;       PG8_STAGE(PG8_SB(0, 1), b2 + hstep, voffB);
;       PG8_WAIT_V(6); PG8_BAR; PG8_MMA(1, 1, At, B1); PG8_BAR;
;       PG8_LDB(B0, 1, 0); PG8_SCHED; PG8_LDA(At, 1, 0); PG8_STAGE(PG8_SA(0, 1), a2 + hstep, voffA);
;       PG8_WAIT_L(8); PG8_BAR; PG8_WAIT_L(0); PG8_MMA(0, 0, At, B0); PG8_BAR; PG8_SCHED;
	s_waitcnt lgkmcnt(0)
	v_mfma_f32_16x16x32_bf16 v[116:119], v[212:215], v[164:167], v[116:119]
	v_mfma_f32_16x16x32_bf16 v[112:115], v[220:223], v[164:167], v[112:115]
	v_mfma_f32_16x16x32_bf16 v[100:103], v[212:215], v[172:175], v[100:103]
	v_mfma_f32_16x16x32_bf16 v[96:99], v[220:223], v[172:175], v[96:99]
	v_mfma_f32_16x16x32_bf16 v[84:87], v[212:215], v[196:199], v[84:87]
	v_mfma_f32_16x16x32_bf16 v[80:83], v[220:223], v[196:199], v[80:83]
	v_mfma_f32_16x16x32_bf16 v[68:71], v[212:215], v[204:207], v[68:71]
	v_mfma_f32_16x16x32_bf16 v[64:67], v[220:223], v[204:207], v[64:67]
	v_mfma_f32_16x16x32_bf16 v[116:119], v[216:219], v[168:171], v[116:119]
	v_mfma_f32_16x16x32_bf16 v[112:115], v[224:227], v[168:171], v[112:115]
	v_mfma_f32_16x16x32_bf16 v[100:103], v[216:219], v[176:179], v[100:103]
	v_mfma_f32_16x16x32_bf16 v[96:99], v[224:227], v[176:179], v[96:99]
	v_mfma_f32_16x16x32_bf16 v[84:87], v[216:219], v[200:203], v[84:87]
	v_mfma_f32_16x16x32_bf16 v[80:83], v[224:227], v[200:203], v[80:83]
	v_mfma_f32_16x16x32_bf16 v[68:71], v[216:219], v[208:211], v[68:71]
	v_mfma_f32_16x16x32_bf16 v[64:67], v[224:227], v[208:211], v[64:67]
	s_mov_b32 m0, s40
	s_add_u32 s100, s20, s0
	s_addc_u32 s101, s21, s1
	s_barrier
	ds_read_b128 v[164:167], v158 offset:16384
	ds_read_b128 v[168:171], v158 offset:17408
	ds_read_b128 v[172:175], v158 offset:18432
	ds_read_b128 v[176:179], v158 offset:19456
	ds_read_b128 v[196:199], v158 offset:20480
	ds_read_b128 v[200:203], v158 offset:21504
	ds_read_b128 v[204:207], v158 offset:22528
	ds_read_b128 v[208:211], v158 offset:23552
	global_load_lds_dwordx4 v138, s[20:21]
	s_mov_b32 m0, s41
	s_nop 0
	global_load_lds_dwordx4 v134, s[20:21]
	s_barrier
	s_waitcnt lgkmcnt(0)
	v_mfma_f32_16x16x32_bf16 v[60:63], v[128:131], v[164:167], v[60:63]
	v_mfma_f32_16x16x32_bf16 v[56:59], v[150:153], v[164:167], v[56:59]
	v_mfma_f32_16x16x32_bf16 v[44:47], v[128:131], v[172:175], v[44:47]
	v_mfma_f32_16x16x32_bf16 v[40:43], v[150:153], v[172:175], v[40:43]
	v_mfma_f32_16x16x32_bf16 v[28:31], v[128:131], v[196:199], v[28:31]
	v_mfma_f32_16x16x32_bf16 v[24:27], v[150:153], v[196:199], v[24:27]
	v_mfma_f32_16x16x32_bf16 v[12:15], v[128:131], v[204:207], v[12:15]
	v_mfma_f32_16x16x32_bf16 v[8:11], v[150:153], v[204:207], v[8:11]
	v_mfma_f32_16x16x32_bf16 v[60:63], v[146:149], v[168:171], v[60:63]
	v_mfma_f32_16x16x32_bf16 v[56:59], v[160:163], v[168:171], v[56:59]
	v_mfma_f32_16x16x32_bf16 v[44:47], v[146:149], v[176:179], v[44:47]
	v_mfma_f32_16x16x32_bf16 v[40:43], v[160:163], v[176:179], v[40:43]
	v_mfma_f32_16x16x32_bf16 v[28:31], v[146:149], v[200:203], v[28:31]
	v_mfma_f32_16x16x32_bf16 v[24:27], v[160:163], v[200:203], v[24:27]
	v_mfma_f32_16x16x32_bf16 v[12:15], v[146:149], v[208:211], v[12:15]
	v_mfma_f32_16x16x32_bf16 v[8:11], v[160:163], v[208:211], v[8:11]
	s_waitcnt vmcnt(8)
	s_barrier
	s_add_u32 s52, s4, 0x40000
	s_addc_u32 s53, s5, 0
	s_add_i32 s51, s54, s34
	s_mov_b32 m0, s51
	s_nop 0
	global_load_lds_dwordx4 v136, s[52:53]
	s_add_i32 m0, s51, 0x2000
	s_nop 0
	global_load_lds_dwordx4 v132, s[52:53]
	s_waitcnt vmcnt(6)
	s_barrier
	ds_read_b128 v[128:131], v230
	ds_read_b128 v[146:149], v230 offset:1024
	ds_read_b128 v[150:153], v230 offset:2048
	ds_read_b128 v[160:163], v230 offset:3072
	v_mfma_f32_16x16x32_bf16 v[52:55], v[212:215], v[164:167], v[52:55]
	v_mfma_f32_16x16x32_bf16 v[48:51], v[220:223], v[164:167], v[48:51]
	v_mfma_f32_16x16x32_bf16 v[36:39], v[212:215], v[172:175], v[36:39]
	v_mfma_f32_16x16x32_bf16 v[32:35], v[220:223], v[172:175], v[32:35]
	v_mfma_f32_16x16x32_bf16 v[20:23], v[212:215], v[196:199], v[20:23]
	v_mfma_f32_16x16x32_bf16 v[16:19], v[220:223], v[196:199], v[16:19]
	v_mfma_f32_16x16x32_bf16 v[4:7], v[212:215], v[204:207], v[4:7]
	v_mfma_f32_16x16x32_bf16 v[0:3], v[220:223], v[204:207], v[0:3]
	v_mfma_f32_16x16x32_bf16 v[52:55], v[216:219], v[168:171], v[52:55]
	v_mfma_f32_16x16x32_bf16 v[48:51], v[224:227], v[168:171], v[48:51]
	v_mfma_f32_16x16x32_bf16 v[36:39], v[216:219], v[176:179], v[36:39]
	v_mfma_f32_16x16x32_bf16 v[32:35], v[224:227], v[176:179], v[32:35]
	v_mfma_f32_16x16x32_bf16 v[20:23], v[216:219], v[200:203], v[20:23]
	v_mfma_f32_16x16x32_bf16 v[16:19], v[224:227], v[200:203], v[16:19]
	v_mfma_f32_16x16x32_bf16 v[4:7], v[216:219], v[208:211], v[4:7]
	v_mfma_f32_16x16x32_bf16 v[0:3], v[224:227], v[208:211], v[0:3]
	s_add_i32 s51, 0, 0x18000
	s_barrier
	s_add_u32 s20, s20, 0x40000
	s_addc_u32 s21, s21, 0
	s_mov_b32 m0, s42
	ds_read_b128 v[164:167], v158 offset:32768
	ds_read_b128 v[168:171], v158 offset:33792
	ds_read_b128 v[172:175], v158 offset:34816
	ds_read_b128 v[176:179], v158 offset:35840
	ds_read_b128 v[196:199], v158 offset:36864
	ds_read_b128 v[200:203], v158 offset:37888
	ds_read_b128 v[204:207], v158 offset:38912
	ds_read_b128 v[208:211], v158 offset:39936
	global_load_lds_dwordx4 v138, s[20:21]
	s_mov_b32 m0, s43
	s_nop 0
	global_load_lds_dwordx4 v134, s[20:21]
	s_waitcnt lgkmcnt(8)
	s_barrier
	s_waitcnt lgkmcnt(0)
	v_mfma_f32_16x16x32_bf16 v[124:127], v[128:131], v[164:167], v[124:127]
	v_mfma_f32_16x16x32_bf16 v[120:123], v[150:153], v[164:167], v[120:123]
	v_mfma_f32_16x16x32_bf16 v[108:111], v[128:131], v[172:175], v[108:111]
	v_mfma_f32_16x16x32_bf16 v[104:107], v[150:153], v[172:175], v[104:107]
	v_mfma_f32_16x16x32_bf16 v[92:95], v[128:131], v[196:199], v[92:95]
	v_mfma_f32_16x16x32_bf16 v[88:91], v[150:153], v[196:199], v[88:91]
	v_mfma_f32_16x16x32_bf16 v[76:79], v[128:131], v[204:207], v[76:79]
	v_mfma_f32_16x16x32_bf16 v[72:75], v[150:153], v[204:207], v[72:75]
	v_mfma_f32_16x16x32_bf16 v[124:127], v[146:149], v[168:171], v[124:127]
	v_mfma_f32_16x16x32_bf16 v[120:123], v[160:163], v[168:171], v[120:123]
	v_mfma_f32_16x16x32_bf16 v[108:111], v[146:149], v[176:179], v[108:111]
	v_mfma_f32_16x16x32_bf16 v[104:107], v[160:163], v[176:179], v[104:107]
	v_mfma_f32_16x16x32_bf16 v[92:95], v[146:149], v[200:203], v[92:95]
	v_mfma_f32_16x16x32_bf16 v[88:91], v[160:163], v[200:203], v[88:91]
	v_mfma_f32_16x16x32_bf16 v[76:79], v[146:149], v[208:211], v[76:79]
	v_mfma_f32_16x16x32_bf16 v[72:75], v[160:163], v[208:211], v[72:75]
	s_barrier
; #define PG8_STAGE(bufoff, gbase, voff) do { _Pragma("unroll") for (int _i = 0; _i < 2; ++_i) \
;     __builtin_amdgcn_global_load_lds((const unsigned*)((const char*)(gbase) + (voff)[_i]), (LAS unsigned*)(lds + (bufoff) + ldsw + _i * 8192), 16, 0, 0); } while (0)
; #define PG8_LDA(dst, b, h) do { _Pragma("unroll") for (int m = 0; m < 4; ++m) _Pragma("unroll") for (int k = 0; k < 2; ++k) dst[m][k] = *(const LAS bf16x8*)(lds + PG8_SA(b, h) + aoff + m * 2048 + k * 1024); } while (0)
; #define PG8_LDB(dst, b, h) do { _Pragma("unroll") for (int n = 0; n < 2; ++n) _Pragma("unroll") for (int k = 0; k < 2; ++k) dst[n][k] = *(const LAS bf16x8*)(lds + PG8_SB(b, h) + boff + n * 2048 + k * 1024); } while (0)
; #define PG8_MMA(ai, bj, At, Bt) do { __builtin_amdgcn_s_setprio(1); _Pragma("unroll") for (int m = 0; m < 4; ++m) _Pragma("unroll") for (int n = 0; n < 2; ++n) _Pragma("unroll") for (int k = 0; k < 2; ++k) \
;     acc[ai][bj][m][n] = __builtin_amdgcn_mfma_f32_16x16x32_bf16(Bt[n][k], At[m][k], acc[ai][bj][m][n], 0, 0, 0); __builtin_amdgcn_s_setprio(0); } while (0)
; #define PG8_BAR __builtin_amdgcn_s_barrier()
; template <class Epi, class Sched>
; DI void gemm_phase(LAS unsigned char* lds, const Gemm g, const Sched& S, const Epi& E) {
;     ...
;       PG8_LDB(B1, 1, 1); PG8_STAGE(PG8_SB(1, 0), b3, voffB);
;       PG8_BAR; PG8_WAIT_L(0); PG8_MMA(0, 1, At, B1); PG8_BAR;
;       PG8_LDA(At, 1, 1); PG8_STAGE(PG8_SA(1, 0), a3, voffA);
;       PG8_BAR; PG8_WAIT_L(0); PG8_MMA(1, 0, At, B0); PG8_BAR; PG8_SCHED;
;       PG8_STAGE(PG8_SB(1, 1), b3 + hstep, voffB);
;       PG8_WAIT_V(6); PG8_BAR; PG8_MMA(1, 1, At, B1); PG8_BAR;
;     }
;     E(acc, cur, wr, wc, fr, fq);
;   DI void operator()(const f32x4 (&acc)[2][2][4][2], const pg8::Unit& u, int wr, int wc, int fr_, int fq_) const {
;     ...
;             } else if (EPI == EPI_CIN) {
;               if (n == 0) {
;                 const int gb = u.pn * 256 + bj * 128 + wc * 32;
;                 const int f8 = gb + 8 * fq;
;                 const f32x4 v1 = acc[ai][bj][m][1];
;                 if (gb < 1024) st_bf8((u16*)(big + O_QD) + (size_t)token * 1024 + f8, v, v1, rinv * (0.125f * LOG2E));
;                 else if (gb < 2048) st_bf8((u16*)(big + O_KD) + (size_t)token * 1024 + (f8 - 1024), v, v1, rinv);
;                 else st_bf8((u16*)(big + O_VDT) + (size_t)token * 1024 + (f8 - 2048), v, v1, rinv);
;               }
	s_add_i32 s20, 0, 0x1c000
	s_add_i32 s21, s51, s34
	s_mov_b32 m0, s21
	ds_read_b128 v[212:215], v231
	ds_read_b128 v[216:219], v231 offset:1024
	ds_read_b128 v[220:223], v231 offset:2048
	ds_read_b128 v[224:227], v231 offset:3072
	global_load_lds_dwordx4 v136, vcc
	s_add_i32 m0, s21, 0x2000
	s_nop 0
	global_load_lds_dwordx4 v132, vcc
	s_barrier
	s_waitcnt lgkmcnt(0)
	v_mfma_f32_16x16x32_bf16 v[116:119], v[212:215], v[164:167], v[116:119]
	v_mfma_f32_16x16x32_bf16 v[112:115], v[220:223], v[164:167], v[112:115]
	v_mfma_f32_16x16x32_bf16 v[100:103], v[212:215], v[172:175], v[100:103]
	v_mfma_f32_16x16x32_bf16 v[96:99], v[220:223], v[172:175], v[96:99]
	v_mfma_f32_16x16x32_bf16 v[84:87], v[212:215], v[196:199], v[84:87]
	v_mfma_f32_16x16x32_bf16 v[80:83], v[220:223], v[196:199], v[80:83]
	v_mfma_f32_16x16x32_bf16 v[68:71], v[212:215], v[204:207], v[68:71]
	v_mfma_f32_16x16x32_bf16 v[64:67], v[220:223], v[204:207], v[64:67]
	v_mfma_f32_16x16x32_bf16 v[116:119], v[216:219], v[168:171], v[116:119]
	v_mfma_f32_16x16x32_bf16 v[112:115], v[224:227], v[168:171], v[112:115]
	v_mfma_f32_16x16x32_bf16 v[100:103], v[216:219], v[176:179], v[100:103]
	v_mfma_f32_16x16x32_bf16 v[96:99], v[224:227], v[176:179], v[96:99]
	v_mfma_f32_16x16x32_bf16 v[84:87], v[216:219], v[200:203], v[84:87]
	v_mfma_f32_16x16x32_bf16 v[80:83], v[224:227], v[200:203], v[80:83]
	v_mfma_f32_16x16x32_bf16 v[68:71], v[216:219], v[208:211], v[68:71]
	v_mfma_f32_16x16x32_bf16 v[64:67], v[224:227], v[208:211], v[64:67]
	s_mov_b32 m0, s46
	s_barrier
	ds_read_b128 v[164:167], v158 offset:49152
	ds_read_b128 v[168:171], v158 offset:50176
	ds_read_b128 v[172:175], v158 offset:51200
	ds_read_b128 v[176:179], v158 offset:52224
	ds_read_b128 v[196:199], v158 offset:53248
	ds_read_b128 v[200:203], v158 offset:54272
	ds_read_b128 v[204:207], v158 offset:55296
	ds_read_b128 v[208:211], v158 offset:56320
	global_load_lds_dwordx4 v138, s[100:101]
	s_mov_b32 m0, s47
	s_nop 0
	global_load_lds_dwordx4 v134, s[100:101]
	s_barrier
	s_waitcnt lgkmcnt(0)
	v_mfma_f32_16x16x32_bf16 v[60:63], v[128:131], v[164:167], v[60:63]
	v_mfma_f32_16x16x32_bf16 v[56:59], v[150:153], v[164:167], v[56:59]
	v_mfma_f32_16x16x32_bf16 v[44:47], v[128:131], v[172:175], v[44:47]
	v_mfma_f32_16x16x32_bf16 v[40:43], v[150:153], v[172:175], v[40:43]
	v_mfma_f32_16x16x32_bf16 v[28:31], v[128:131], v[196:199], v[28:31]
	v_mfma_f32_16x16x32_bf16 v[24:27], v[150:153], v[196:199], v[24:27]
	v_mfma_f32_16x16x32_bf16 v[12:15], v[128:131], v[204:207], v[12:15]
	v_mfma_f32_16x16x32_bf16 v[8:11], v[150:153], v[204:207], v[8:11]
	v_mfma_f32_16x16x32_bf16 v[60:63], v[146:149], v[168:171], v[60:63]
	v_mfma_f32_16x16x32_bf16 v[56:59], v[160:163], v[168:171], v[56:59]
	v_mfma_f32_16x16x32_bf16 v[44:47], v[146:149], v[176:179], v[44:47]
	v_mfma_f32_16x16x32_bf16 v[40:43], v[160:163], v[176:179], v[40:43]
	v_mfma_f32_16x16x32_bf16 v[28:31], v[146:149], v[200:203], v[28:31]
	v_mfma_f32_16x16x32_bf16 v[24:27], v[160:163], v[200:203], v[24:27]
	v_mfma_f32_16x16x32_bf16 v[12:15], v[146:149], v[208:211], v[12:15]
	v_mfma_f32_16x16x32_bf16 v[8:11], v[160:163], v[208:211], v[8:11]
	s_waitcnt vmcnt(8)
	s_barrier
	s_add_u32 s4, s4, 0x40080
	s_addc_u32 s5, s5, 0
	s_add_i32 s20, s20, s34
	s_mov_b32 m0, s20
	s_nop 0
	global_load_lds_dwordx4 v136, s[4:5]
	s_add_i32 m0, s20, 0x2000
	s_nop 0
	global_load_lds_dwordx4 v132, s[4:5]
	s_waitcnt vmcnt(6)
	s_barrier
	ds_read_b128 v[128:131], v228
	ds_read_b128 v[146:149], v228 offset:1024
	ds_read_b128 v[150:153], v228 offset:2048
	ds_read_b128 v[160:163], v228 offset:3072
	v_mfma_f32_16x16x32_bf16 v[52:55], v[212:215], v[164:167], v[52:55]
	v_mfma_f32_16x16x32_bf16 v[48:51], v[220:223], v[164:167], v[48:51]
	v_mfma_f32_16x16x32_bf16 v[36:39], v[212:215], v[172:175], v[36:39]
	v_mfma_f32_16x16x32_bf16 v[32:35], v[220:223], v[172:175], v[32:35]
	v_mfma_f32_16x16x32_bf16 v[20:23], v[212:215], v[196:199], v[20:23]
	v_mfma_f32_16x16x32_bf16 v[16:19], v[220:223], v[196:199], v[16:19]
	v_mfma_f32_16x16x32_bf16 v[4:7], v[212:215], v[204:207], v[4:7]
	v_mfma_f32_16x16x32_bf16 v[0:3], v[220:223], v[204:207], v[0:3]
	v_mfma_f32_16x16x32_bf16 v[52:55], v[216:219], v[168:171], v[52:55]
	v_mfma_f32_16x16x32_bf16 v[48:51], v[224:227], v[168:171], v[48:51]
	v_mfma_f32_16x16x32_bf16 v[36:39], v[216:219], v[176:179], v[36:39]
	v_mfma_f32_16x16x32_bf16 v[32:35], v[224:227], v[176:179], v[32:35]
	v_mfma_f32_16x16x32_bf16 v[20:23], v[216:219], v[200:203], v[20:23]
	v_mfma_f32_16x16x32_bf16 v[16:19], v[224:227], v[200:203], v[16:19]
	v_mfma_f32_16x16x32_bf16 v[4:7], v[216:219], v[208:211], v[4:7]
	v_mfma_f32_16x16x32_bf16 v[0:3], v[224:227], v[208:211], v[0:3]
	s_add_i32 s50, s50, 2
	s_add_u32 s2, s2, 0x100
	s_addc_u32 s3, s3, 0
	s_add_u32 s37, s37, 0x100
	s_addc_u32 s49, s49, 0
	s_cmp_gt_u32 s50, 13
	s_barrier
	s_cbranch_scc0 .LBB0_370
	s_waitcnt lgkmcnt(0)
	v_mov_b32_e32 v128, v182
	s_lshl_b32 s2, s22, 10
	v_and_or_b32 v160, v128, 15, s44
	v_lshrrev_b32_e32 v128, 1, v128
	s_add_i32 s2, s2, 0
	v_and_b32_e32 v146, 24, v128
	v_lshl_add_u32 v128, v160, 2, s2
	v_add_u32_e32 v159, 0x20000, v128
	s_lshl_b32 s13, s28, 8
	s_lshl_b32 s3, s23, 8
	ds_read_b32 v154, v159
	v_add_u32_e32 v150, s13, v160
	s_or_b32 s20, s3, s45
	v_ashrrev_i32_e32 v151, 31, v150
	s_cmpk_gt_i32 s20, 0x3ff
	v_lshlrev_b64 v[128:129], 11, v[150:151]
	v_or_b32_e32 v148, s20, v146
	s_cselect_b64 s[4:5], -1, 0
	s_cmpk_gt_u32 s3, 0x7ff
	s_cselect_b64 s[2:3], -1, 0
	v_mov_b32_e32 v144, v148
	v_lshl_add_u64 v[152:153], s[10:11], 0, v[128:129]
	s_mov_b64 s[22:23], -1
	s_and_b64 vcc, exec, s[4:5]
	s_cbranch_vccz .LBB0_377
	s_waitcnt lgkmcnt(0)
	v_pk_mul_f32 v[128:129], v[124:125], v[154:155] op_sel_hi:[1,0]
	v_pk_mul_f32 v[130:131], v[126:127], v[154:155] op_sel_hi:[1,0]
	v_cvt_pk_bf16_f32 v128, v128, v129
	v_cvt_pk_bf16_f32 v129, v130, v131
	v_pk_mul_f32 v[130:131], v[120:121], v[154:155] op_sel_hi:[1,0]
	v_pk_mul_f32 v[162:163], v[122:123], v[154:155] op_sel_hi:[1,0]
	v_lshl_add_u64 v[156:157], v[144:145], 1, v[152:153]
	v_cvt_pk_bf16_f32 v130, v130, v131
	v_cvt_pk_bf16_f32 v131, v162, v163
	s_and_b64 vcc, exec, s[2:3]
	s_cbranch_vccz .LBB0_374
	v_add_co_u32_e32 v162, vcc, 0x7fff000, v156
	s_mov_b64 s[22:23], 0
	s_nop 0
	v_addc_co_u32_e32 v163, vcc, 0, v157, vcc
	global_store_dwordx4 v[162:163], v[128:131], off

; #define PG8_STAGE(bufoff, gbase, voff) do { _Pragma("unroll") for (int _i = 0; _i < 2; ++_i) \
;     __builtin_amdgcn_global_load_lds((const unsigned*)((const char*)(gbase) + (voff)[_i]), (LAS unsigned*)(lds + (bufoff) + ldsw + _i * 8192), 16, 0, 0); } while (0)
; #define PG8_LDA(dst, b, h) do { _Pragma("unroll") for (int m = 0; m < 4; ++m) _Pragma("unroll") for (int k = 0; k < 2; ++k) dst[m][k] = *(const LAS bf16x8*)(lds + PG8_SA(b, h) + aoff + m * 2048 + k * 1024); } while (0)
; #define PG8_LDB(dst, b, h) do { _Pragma("unroll") for (int n = 0; n < 2; ++n) _Pragma("unroll") for (int k = 0; k < 2; ++k) dst[n][k] = *(const LAS bf16x8*)(lds + PG8_SB(b, h) + boff + n * 2048 + k * 1024); } while (0)
; #define PG8_MMA(ai, bj, At, Bt) do { __builtin_amdgcn_s_setprio(1); _Pragma("unroll") for (int m = 0; m < 4; ++m) _Pragma("unroll") for (int n = 0; n < 2; ++n) _Pragma("unroll") for (int k = 0; k < 2; ++k) \
;     acc[ai][bj][m][n] = __builtin_amdgcn_mfma_f32_16x16x32_bf16(Bt[n][k], At[m][k], acc[ai][bj][m][n], 0, 0, 0); __builtin_amdgcn_s_setprio(0); } while (0)
; #define PG8_WAIT_L(n) asm volatile("s_waitcnt lgkmcnt(" #n ")" ::: "memory")
; #define PG8_BAR __builtin_amdgcn_s_barrier()
; #define PG8_SCHED __builtin_amdgcn_sched_barrier(0)
; template <class Epi, class Sched>
; DI void gemm_phase(LAS unsigned char* lds, const Gemm g, const Sched& S, const Epi& E) {
;     ...
;     for (int t = 0; t < nt; t += 2) {
;       const bool last = (t == nt - 2);
;       const char* a1 = cA + (size_t)(t + 1) * kstep;
;       const char* a2 = last ? nA : cA + (size_t)(t + 2) * kstep; const char* b2 = last ? nB : cB + (size_t)(t + 2) * kstep;
;       const char* a3 = a2 + kstep; const char* b3 = b2 + kstep;
;       PG8_LDB(B0, 0, 0); PG8_SCHED; PG8_LDA(At, 0, 0); PG8_STAGE(PG8_SA(1, 1), a1 + hstep, voffA);
;       PG8_WAIT_L(8); PG8_BAR; PG8_WAIT_L(0); PG8_MMA(0, 0, At, B0); PG8_BAR; PG8_SCHED;
;       PG8_LDB(B1, 0, 1); PG8_STAGE(PG8_SB(0, 0), b2, voffB);
;       PG8_BAR; PG8_WAIT_L(0); PG8_MMA(0, 1, At, B1); PG8_BAR;
;     ...
; #pragma unroll
;     for (int a = 0; a < 2; ++a)
; #pragma unroll
;       for (int b = 0; b < 2; ++b)
; #pragma unroll
;         for (int m = 0; m < 4; ++m)
; #pragma unroll
;           for (int n = 0; n < 2; ++n) acc[a][b][m][n] = (f32x4){0.f, 0.f, 0.f, 0.f};
;     cur = nxt; cA = nA; cB = nB; ++ui;
.LBB0_688:
	v_readlane_b32 s18, v238, 51
	v_readlane_b32 s19, v238, 52
	s_ashr_i32 s13, s12, 31
	s_mov_b32 s41, -2
	v_mov_b64_e32 v[0:1], s[18:19]
	v_cmp_lt_i64_e32 vcc, s[16:17], v[0:1]
	s_lshl_b64 s[16:17], s[12:13], 19
	s_add_u32 s16, s53, s16
	s_addc_u32 s17, s54, s17
	s_and_b64 s[18:19], vcc, exec
	s_cselect_b32 s13, s17, s21
	s_cselect_b32 s37, s16, s20
	s_ashr_i32 s15, s14, 31
	s_lshl_b64 s[18:19], s[14:15], 19
	s_add_u32 s18, s24, s18
	s_addc_u32 s19, s55, s19
	s_and_b64 s[28:29], vcc, exec
	s_cselect_b32 s15, s19, s23
	s_cselect_b32 s38, s18, s22
	s_add_u32 s20, s20, 0x40080
	s_addc_u32 s21, s21, 0
	s_add_u32 s39, s22, 0x100
	v_mov_b32_e32 v0, 0
	s_addc_u32 s40, s23, 0
	v_mov_b32_e32 v1, v0
	v_mov_b64_e32 v[2:3], v[0:1]
	v_mov_b64_e32 v[4:5], v[0:1]
	v_mov_b64_e32 v[6:7], v[0:1]
	v_mov_b64_e32 v[8:9], v[0:1]
	v_mov_b64_e32 v[10:11], v[0:1]
	v_mov_b64_e32 v[12:13], v[0:1]
	v_mov_b64_e32 v[14:15], v[0:1]
	v_mov_b64_e32 v[16:17], v[0:1]
	v_mov_b64_e32 v[18:19], v[0:1]
	v_mov_b64_e32 v[20:21], v[0:1]
	v_mov_b64_e32 v[22:23], v[0:1]
	v_mov_b64_e32 v[24:25], v[0:1]
	v_mov_b64_e32 v[26:27], v[0:1]
	v_mov_b64_e32 v[28:29], v[0:1]
	v_mov_b64_e32 v[30:31], v[0:1]
	v_mov_b64_e32 v[32:33], v[0:1]
	v_mov_b64_e32 v[34:35], v[0:1]
	v_mov_b64_e32 v[36:37], v[0:1]
	v_mov_b64_e32 v[38:39], v[0:1]
	v_mov_b64_e32 v[40:41], v[0:1]
	v_mov_b64_e32 v[42:43], v[0:1]
	v_mov_b64_e32 v[44:45], v[0:1]
	v_mov_b64_e32 v[46:47], v[0:1]
	v_mov_b64_e32 v[48:49], v[0:1]
	v_mov_b64_e32 v[50:51], v[0:1]
	v_mov_b64_e32 v[52:53], v[0:1]
	v_mov_b64_e32 v[54:55], v[0:1]
	v_mov_b64_e32 v[56:57], v[0:1]
	v_mov_b64_e32 v[58:59], v[0:1]
	v_mov_b64_e32 v[60:61], v[0:1]
	v_mov_b64_e32 v[62:63], v[0:1]
	v_mov_b64_e32 v[64:65], v[0:1]
	v_mov_b64_e32 v[66:67], v[0:1]
	v_mov_b64_e32 v[68:69], v[0:1]
	v_mov_b64_e32 v[70:71], v[0:1]
	v_mov_b64_e32 v[72:73], v[0:1]
	v_mov_b64_e32 v[74:75], v[0:1]
	v_mov_b64_e32 v[76:77], v[0:1]
	v_mov_b64_e32 v[78:79], v[0:1]
	v_mov_b64_e32 v[80:81], v[0:1]
	v_mov_b64_e32 v[82:83], v[0:1]
	v_mov_b64_e32 v[84:85], v[0:1]
	v_mov_b64_e32 v[86:87], v[0:1]
	v_mov_b64_e32 v[88:89], v[0:1]
	v_mov_b64_e32 v[90:91], v[0:1]
	v_mov_b64_e32 v[92:93], v[0:1]
	v_mov_b64_e32 v[94:95], v[0:1]
	v_mov_b64_e32 v[96:97], v[0:1]
	v_mov_b64_e32 v[98:99], v[0:1]
	v_mov_b64_e32 v[100:101], v[0:1]
	v_mov_b64_e32 v[102:103], v[0:1]
	v_mov_b64_e32 v[104:105], v[0:1]
	v_mov_b64_e32 v[106:107], v[0:1]
	v_mov_b64_e32 v[108:109], v[0:1]
	v_mov_b64_e32 v[110:111], v[0:1]
	v_mov_b64_e32 v[112:113], v[0:1]
	v_mov_b64_e32 v[114:115], v[0:1]
	v_mov_b64_e32 v[116:117], v[0:1]
	v_mov_b64_e32 v[118:119], v[0:1]
	v_mov_b64_e32 v[120:121], v[0:1]
	v_mov_b64_e32 v[122:123], v[0:1]
	v_mov_b64_e32 v[124:125], v[0:1]
	v_mov_b64_e32 v[126:127], v[0:1]
	v_add_u32_e32 v222, 0x10000, v196
	v_add_u32_e32 v223, 0x14000, v196
	v_add_u32_e32 v224, 0x18000, v196
	v_add_u32_e32 v225, 0x1c000, v196
	ds_read_b128 v[128:131], v222
	ds_read_b128 v[132:135], v222 offset:1024
	ds_read_b128 v[150:153], v222 offset:2048
	ds_read_b128 v[154:157], v222 offset:3072
.LBB0_689:
	s_add_u32 s22, s20, 0xfffc0080
	s_addc_u32 s23, s21, -1
	s_add_i32 s42, 0, 0x10000
	s_cmp_eq_u32 s41, 12
	s_cselect_b32 s29, s13, s23
	s_cselect_b32 s28, s37, s22
	s_cselect_b32 s23, s15, s40
	s_cselect_b32 s22, s38, s39
	s_add_i32 m0, s56, 0xc000
	ds_read_b128 v[158:161], v197
	ds_read_b128 v[162:165], v197 offset:1024
	ds_read_b128 v[166:169], v197 offset:2048
	ds_read_b128 v[170:173], v197 offset:3072
	ds_read_b128 v[174:177], v197 offset:4096
	ds_read_b128 v[178:181], v197 offset:5120
	ds_read_b128 v[198:201], v197 offset:6144
	ds_read_b128 v[202:205], v197 offset:7168
	global_load_lds_dwordx4 v146, s[20:21]
	s_add_i32 m0, s56, 0xe000
	s_nop 0
	global_load_lds_dwordx4 v148, s[20:21]
	s_waitcnt lgkmcnt(8)
	s_barrier
	s_waitcnt lgkmcnt(0)
	v_mfma_f32_16x16x32_bf16 v[124:127], v[128:131], v[158:161], v[124:127]
	v_mfma_f32_16x16x32_bf16 v[120:123], v[150:153], v[158:161], v[120:123]
	v_mfma_f32_16x16x32_bf16 v[108:111], v[128:131], v[166:169], v[108:111]
	v_mfma_f32_16x16x32_bf16 v[104:107], v[150:153], v[166:169], v[104:107]
	v_mfma_f32_16x16x32_bf16 v[92:95], v[128:131], v[174:177], v[92:95]
	v_mfma_f32_16x16x32_bf16 v[88:91], v[150:153], v[174:177], v[88:91]
	v_mfma_f32_16x16x32_bf16 v[76:79], v[128:131], v[198:201], v[76:79]
	v_mfma_f32_16x16x32_bf16 v[72:75], v[150:153], v[198:201], v[72:75]
	v_mfma_f32_16x16x32_bf16 v[124:127], v[132:135], v[162:165], v[124:127]
	v_mfma_f32_16x16x32_bf16 v[120:123], v[154:157], v[162:165], v[120:123]
	v_mfma_f32_16x16x32_bf16 v[108:111], v[132:135], v[170:173], v[108:111]
	v_mfma_f32_16x16x32_bf16 v[104:107], v[154:157], v[170:173], v[104:107]
	v_mfma_f32_16x16x32_bf16 v[92:95], v[132:135], v[178:181], v[92:95]
	v_mfma_f32_16x16x32_bf16 v[88:91], v[154:157], v[178:181], v[88:91]
	v_mfma_f32_16x16x32_bf16 v[76:79], v[132:135], v[202:205], v[76:79]
	v_mfma_f32_16x16x32_bf16 v[72:75], v[154:157], v[202:205], v[72:75]
	s_barrier
	s_add_i32 s44, 0, 0x14000
	s_add_i32 s42, s42, s52
	s_add_u32 vcc_lo, s22, s0
	s_addc_u32 vcc_hi, s23, s1
	s_mov_b32 m0, s42
	ds_read_b128 v[206:209], v223
	ds_read_b128 v[210:213], v223 offset:1024
	ds_read_b128 v[214:217], v223 offset:2048
	ds_read_b128 v[218:221], v223 offset:3072
	global_load_lds_dwordx4 v140, s[22:23]
	s_add_i32 m0, s42, 0x2000
	s_nop 0
	global_load_lds_dwordx4 v136, s[22:23]
	s_barrier
; #define PG8_STAGE(bufoff, gbase, voff) do { _Pragma("unroll") for (int _i = 0; _i < 2; ++_i) \
;     __builtin_amdgcn_global_load_lds((const unsigned*)((const char*)(gbase) + (voff)[_i]), (LAS unsigned*)(lds + (bufoff) + ldsw + _i * 8192), 16, 0, 0); } while (0)
; #define PG8_LDA(dst, b, h) do { _Pragma("unroll") for (int m = 0; m < 4; ++m) _Pragma("unroll") for (int k = 0; k < 2; ++k) dst[m][k] = *(const LAS bf16x8*)(lds + PG8_SA(b, h) + aoff + m * 2048 + k * 1024); } while (0)
; #define PG8_LDB(dst, b, h) do { _Pragma("unroll") for (int n = 0; n < 2; ++n) _Pragma("unroll") for (int k = 0; k < 2; ++k) dst[n][k] = *(const LAS bf16x8*)(lds + PG8_SB(b, h) + boff + n * 2048 + k * 1024); } while (0)
; #define PG8_MMA(ai, bj, At, Bt) do { __builtin_amdgcn_s_setprio(1); _Pragma("unroll") for (int m = 0; m < 4; ++m) _Pragma("unroll") for (int n = 0; n < 2; ++n) _Pragma("unroll") for (int k = 0; k < 2; ++k) \
;     acc[ai][bj][m][n] = __builtin_amdgcn_mfma_f32_16x16x32_bf16(Bt[n][k], At[m][k], acc[ai][bj][m][n], 0, 0, 0); __builtin_amdgcn_s_setprio(0); } while (0)
; #define PG8_WAIT_V(n) asm volatile("s_waitcnt vmcnt(" #n ")" ::: "memory")
; #define PG8_WAIT_L(n) asm volatile("s_waitcnt lgkmcnt(" #n ")" ::: "memory")
; #define PG8_BAR __builtin_amdgcn_s_barrier()
; #define PG8_SCHED __builtin_amdgcn_sched_barrier(0)
; template <class Epi, class Sched>
; DI void gemm_phase(LAS unsigned char* lds, const Gemm g, const Sched& S, const Epi& E) {
;     ...
;       PG8_LDB(B1, 0, 1); PG8_STAGE(PG8_SB(0, 0), b2, voffB);
;       PG8_BAR; PG8_WAIT_L(0); PG8_MMA(0, 1, At, B1); PG8_BAR;
;       PG8_LDA(At, 0, 1); PG8_STAGE(PG8_SA(0, 0), a2, voffA);
;       PG8_BAR; PG8_WAIT_L(0); PG8_MMA(1, 0, At, B0); PG8_BAR; PG8_SCHED;
;       PG8_STAGE(PG8_SB(0, 1), b2 + hstep, voffB);
;       PG8_WAIT_V(6); PG8_BAR; PG8_MMA(1, 1, At, B1); PG8_BAR;
;       PG8_LDB(B0, 1, 0); PG8_SCHED; PG8_LDA(At, 1, 0); PG8_STAGE(PG8_SA(0, 1), a2 + hstep, voffA);
;       PG8_WAIT_L(8); PG8_BAR; PG8_WAIT_L(0); PG8_MMA(0, 0, At, B0); PG8_BAR; PG8_SCHED;
	s_waitcnt lgkmcnt(0)
	v_mfma_f32_16x16x32_bf16 v[116:119], v[206:209], v[158:161], v[116:119]
	v_mfma_f32_16x16x32_bf16 v[112:115], v[214:217], v[158:161], v[112:115]
	v_mfma_f32_16x16x32_bf16 v[100:103], v[206:209], v[166:169], v[100:103]
	v_mfma_f32_16x16x32_bf16 v[96:99], v[214:217], v[166:169], v[96:99]
	v_mfma_f32_16x16x32_bf16 v[84:87], v[206:209], v[174:177], v[84:87]
	v_mfma_f32_16x16x32_bf16 v[80:83], v[214:217], v[174:177], v[80:83]
	v_mfma_f32_16x16x32_bf16 v[68:71], v[206:209], v[198:201], v[68:71]
	v_mfma_f32_16x16x32_bf16 v[64:67], v[214:217], v[198:201], v[64:67]
	v_mfma_f32_16x16x32_bf16 v[116:119], v[210:213], v[162:165], v[116:119]
	v_mfma_f32_16x16x32_bf16 v[112:115], v[218:221], v[162:165], v[112:115]
	v_mfma_f32_16x16x32_bf16 v[100:103], v[210:213], v[170:173], v[100:103]
	v_mfma_f32_16x16x32_bf16 v[96:99], v[218:221], v[170:173], v[96:99]
	v_mfma_f32_16x16x32_bf16 v[84:87], v[210:213], v[178:181], v[84:87]
	v_mfma_f32_16x16x32_bf16 v[80:83], v[218:221], v[178:181], v[80:83]
	v_mfma_f32_16x16x32_bf16 v[68:71], v[210:213], v[202:205], v[68:71]
	v_mfma_f32_16x16x32_bf16 v[64:67], v[218:221], v[202:205], v[64:67]
	s_mov_b32 m0, s56
	s_add_u32 s100, s28, s0
	s_addc_u32 s101, s29, s1
	s_barrier
	ds_read_b128 v[158:161], v197 offset:16384
	ds_read_b128 v[162:165], v197 offset:17408
	ds_read_b128 v[166:169], v197 offset:18432
	ds_read_b128 v[170:173], v197 offset:19456
	ds_read_b128 v[174:177], v197 offset:20480
	ds_read_b128 v[178:181], v197 offset:21504
	ds_read_b128 v[198:201], v197 offset:22528
	ds_read_b128 v[202:205], v197 offset:23552
	global_load_lds_dwordx4 v142, s[28:29]
	s_mov_b32 m0, s57
	s_nop 0
	global_load_lds_dwordx4 v138, s[28:29]
	s_barrier
	s_waitcnt lgkmcnt(0)
	v_mfma_f32_16x16x32_bf16 v[60:63], v[128:131], v[158:161], v[60:63]
	v_mfma_f32_16x16x32_bf16 v[56:59], v[150:153], v[158:161], v[56:59]
	v_mfma_f32_16x16x32_bf16 v[44:47], v[128:131], v[166:169], v[44:47]
	v_mfma_f32_16x16x32_bf16 v[40:43], v[150:153], v[166:169], v[40:43]
	v_mfma_f32_16x16x32_bf16 v[28:31], v[128:131], v[174:177], v[28:31]
	v_mfma_f32_16x16x32_bf16 v[24:27], v[150:153], v[174:177], v[24:27]
	v_mfma_f32_16x16x32_bf16 v[12:15], v[128:131], v[198:201], v[12:15]
	v_mfma_f32_16x16x32_bf16 v[8:11], v[150:153], v[198:201], v[8:11]
	v_mfma_f32_16x16x32_bf16 v[60:63], v[132:135], v[162:165], v[60:63]
	v_mfma_f32_16x16x32_bf16 v[56:59], v[154:157], v[162:165], v[56:59]
	v_mfma_f32_16x16x32_bf16 v[44:47], v[132:135], v[170:173], v[44:47]
	v_mfma_f32_16x16x32_bf16 v[40:43], v[154:157], v[170:173], v[40:43]
	v_mfma_f32_16x16x32_bf16 v[28:31], v[132:135], v[178:181], v[28:31]
	v_mfma_f32_16x16x32_bf16 v[24:27], v[154:157], v[178:181], v[24:27]
	v_mfma_f32_16x16x32_bf16 v[12:15], v[132:135], v[202:205], v[12:15]
	v_mfma_f32_16x16x32_bf16 v[8:11], v[154:157], v[202:205], v[8:11]
	s_waitcnt vmcnt(8)
	s_barrier
	s_add_u32 s42, s22, 0x40000
	s_addc_u32 s43, s23, 0
	s_add_i32 s44, s44, s52
	s_mov_b32 m0, s44
	s_nop 0
	global_load_lds_dwordx4 v140, s[42:43]
	s_add_i32 m0, s44, 0x2000
	s_nop 0
	global_load_lds_dwordx4 v136, s[42:43]
	s_waitcnt vmcnt(6)
	s_barrier
	ds_read_b128 v[128:131], v224
	ds_read_b128 v[132:135], v224 offset:1024
	ds_read_b128 v[150:153], v224 offset:2048
	ds_read_b128 v[154:157], v224 offset:3072
	v_mfma_f32_16x16x32_bf16 v[52:55], v[206:209], v[158:161], v[52:55]
	v_mfma_f32_16x16x32_bf16 v[48:51], v[214:217], v[158:161], v[48:51]
	v_mfma_f32_16x16x32_bf16 v[36:39], v[206:209], v[166:169], v[36:39]
	v_mfma_f32_16x16x32_bf16 v[32:35], v[214:217], v[166:169], v[32:35]
	v_mfma_f32_16x16x32_bf16 v[20:23], v[206:209], v[174:177], v[20:23]
	v_mfma_f32_16x16x32_bf16 v[16:19], v[214:217], v[174:177], v[16:19]
	v_mfma_f32_16x16x32_bf16 v[4:7], v[206:209], v[198:201], v[4:7]
	v_mfma_f32_16x16x32_bf16 v[0:3], v[214:217], v[198:201], v[0:3]
	v_mfma_f32_16x16x32_bf16 v[52:55], v[210:213], v[162:165], v[52:55]
	v_mfma_f32_16x16x32_bf16 v[48:51], v[218:221], v[162:165], v[48:51]
	v_mfma_f32_16x16x32_bf16 v[36:39], v[210:213], v[170:173], v[36:39]
	v_mfma_f32_16x16x32_bf16 v[32:35], v[218:221], v[170:173], v[32:35]
	v_mfma_f32_16x16x32_bf16 v[20:23], v[210:213], v[178:181], v[20:23]
	v_mfma_f32_16x16x32_bf16 v[16:19], v[218:221], v[178:181], v[16:19]
	v_mfma_f32_16x16x32_bf16 v[4:7], v[210:213], v[202:205], v[4:7]
	v_mfma_f32_16x16x32_bf16 v[0:3], v[218:221], v[202:205], v[0:3]
	s_add_i32 s42, 0, 0x18000
	s_barrier
	s_add_u32 s28, s28, 0x40000
	s_addc_u32 s29, s29, 0
	s_mov_b32 m0, s58
	ds_read_b128 v[158:161], v197 offset:32768
	ds_read_b128 v[162:165], v197 offset:33792
	ds_read_b128 v[166:169], v197 offset:34816
	ds_read_b128 v[170:173], v197 offset:35840
	ds_read_b128 v[174:177], v197 offset:36864
	ds_read_b128 v[178:181], v197 offset:37888
	ds_read_b128 v[198:201], v197 offset:38912
	ds_read_b128 v[202:205], v197 offset:39936
	global_load_lds_dwordx4 v142, s[28:29]
	s_mov_b32 m0, s59
	s_nop 0
	global_load_lds_dwordx4 v138, s[28:29]
	s_waitcnt lgkmcnt(8)
	s_barrier
	s_waitcnt lgkmcnt(0)
	v_mfma_f32_16x16x32_bf16 v[124:127], v[128:131], v[158:161], v[124:127]
	v_mfma_f32_16x16x32_bf16 v[120:123], v[150:153], v[158:161], v[120:123]
	v_mfma_f32_16x16x32_bf16 v[108:111], v[128:131], v[166:169], v[108:111]
	v_mfma_f32_16x16x32_bf16 v[104:107], v[150:153], v[166:169], v[104:107]
	v_mfma_f32_16x16x32_bf16 v[92:95], v[128:131], v[174:177], v[92:95]
	v_mfma_f32_16x16x32_bf16 v[88:91], v[150:153], v[174:177], v[88:91]
	v_mfma_f32_16x16x32_bf16 v[76:79], v[128:131], v[198:201], v[76:79]
	v_mfma_f32_16x16x32_bf16 v[72:75], v[150:153], v[198:201], v[72:75]
	v_mfma_f32_16x16x32_bf16 v[124:127], v[132:135], v[162:165], v[124:127]
	v_mfma_f32_16x16x32_bf16 v[120:123], v[154:157], v[162:165], v[120:123]
	v_mfma_f32_16x16x32_bf16 v[108:111], v[132:135], v[170:173], v[108:111]
	v_mfma_f32_16x16x32_bf16 v[104:107], v[154:157], v[170:173], v[104:107]
	v_mfma_f32_16x16x32_bf16 v[92:95], v[132:135], v[178:181], v[92:95]
	v_mfma_f32_16x16x32_bf16 v[88:91], v[154:157], v[178:181], v[88:91]
	v_mfma_f32_16x16x32_bf16 v[76:79], v[132:135], v[202:205], v[76:79]
	v_mfma_f32_16x16x32_bf16 v[72:75], v[154:157], v[202:205], v[72:75]
	s_barrier
; #define PG8_STAGE(bufoff, gbase, voff) do { _Pragma("unroll") for (int _i = 0; _i < 2; ++_i) \
;     __builtin_amdgcn_global_load_lds((const unsigned*)((const char*)(gbase) + (voff)[_i]), (LAS unsigned*)(lds + (bufoff) + ldsw + _i * 8192), 16, 0, 0); } while (0)
; #define PG8_LDA(dst, b, h) do { _Pragma("unroll") for (int m = 0; m < 4; ++m) _Pragma("unroll") for (int k = 0; k < 2; ++k) dst[m][k] = *(const LAS bf16x8*)(lds + PG8_SA(b, h) + aoff + m * 2048 + k * 1024); } while (0)
; #define PG8_LDB(dst, b, h) do { _Pragma("unroll") for (int n = 0; n < 2; ++n) _Pragma("unroll") for (int k = 0; k < 2; ++k) dst[n][k] = *(const LAS bf16x8*)(lds + PG8_SB(b, h) + boff + n * 2048 + k * 1024); } while (0)
; #define PG8_MMA(ai, bj, At, Bt) do { __builtin_amdgcn_s_setprio(1); _Pragma("unroll") for (int m = 0; m < 4; ++m) _Pragma("unroll") for (int n = 0; n < 2; ++n) _Pragma("unroll") for (int k = 0; k < 2; ++k) \
;     acc[ai][bj][m][n] = __builtin_amdgcn_mfma_f32_16x16x32_bf16(Bt[n][k], At[m][k], acc[ai][bj][m][n], 0, 0, 0); __builtin_amdgcn_s_setprio(0); } while (0)
; #define PG8_WAIT_V(n) asm volatile("s_waitcnt vmcnt(" #n ")" ::: "memory")
; #define PG8_WAIT_L(n) asm volatile("s_waitcnt lgkmcnt(" #n ")" ::: "memory")
; #define PG8_BAR __builtin_amdgcn_s_barrier()
; #define PG8_SCHED __builtin_amdgcn_sched_barrier(0)
; template <class Epi, class Sched>
; DI void gemm_phase(LAS unsigned char* lds, const Gemm g, const Sched& S, const Epi& E) {
;     ...
;       PG8_LDB(B1, 1, 1); PG8_STAGE(PG8_SB(1, 0), b3, voffB);
;       PG8_BAR; PG8_WAIT_L(0); PG8_MMA(0, 1, At, B1); PG8_BAR;
;       PG8_LDA(At, 1, 1); PG8_STAGE(PG8_SA(1, 0), a3, voffA);
;       PG8_BAR; PG8_WAIT_L(0); PG8_MMA(1, 0, At, B0); PG8_BAR; PG8_SCHED;
;       PG8_STAGE(PG8_SB(1, 1), b3 + hstep, voffB);
;       PG8_WAIT_V(6); PG8_BAR; PG8_MMA(1, 1, At, B1); PG8_BAR;
	s_add_i32 s28, 0, 0x1c000
	s_add_i32 s29, s42, s52
	s_mov_b32 m0, s29
	ds_read_b128 v[206:209], v225
	ds_read_b128 v[210:213], v225 offset:1024
	ds_read_b128 v[214:217], v225 offset:2048
	ds_read_b128 v[218:221], v225 offset:3072
	global_load_lds_dwordx4 v140, vcc
	s_add_i32 m0, s29, 0x2000
	s_nop 0
	global_load_lds_dwordx4 v136, vcc
	s_barrier
	s_waitcnt lgkmcnt(0)
	v_mfma_f32_16x16x32_bf16 v[116:119], v[206:209], v[158:161], v[116:119]
	v_mfma_f32_16x16x32_bf16 v[112:115], v[214:217], v[158:161], v[112:115]
	v_mfma_f32_16x16x32_bf16 v[100:103], v[206:209], v[166:169], v[100:103]
	v_mfma_f32_16x16x32_bf16 v[96:99], v[214:217], v[166:169], v[96:99]
	v_mfma_f32_16x16x32_bf16 v[84:87], v[206:209], v[174:177], v[84:87]
	v_mfma_f32_16x16x32_bf16 v[80:83], v[214:217], v[174:177], v[80:83]
	v_mfma_f32_16x16x32_bf16 v[68:71], v[206:209], v[198:201], v[68:71]
	v_mfma_f32_16x16x32_bf16 v[64:67], v[214:217], v[198:201], v[64:67]
	v_mfma_f32_16x16x32_bf16 v[116:119], v[210:213], v[162:165], v[116:119]
	v_mfma_f32_16x16x32_bf16 v[112:115], v[218:221], v[162:165], v[112:115]
	v_mfma_f32_16x16x32_bf16 v[100:103], v[210:213], v[170:173], v[100:103]
	v_mfma_f32_16x16x32_bf16 v[96:99], v[218:221], v[170:173], v[96:99]
	v_mfma_f32_16x16x32_bf16 v[84:87], v[210:213], v[178:181], v[84:87]
	v_mfma_f32_16x16x32_bf16 v[80:83], v[218:221], v[178:181], v[80:83]
	v_mfma_f32_16x16x32_bf16 v[68:71], v[210:213], v[202:205], v[68:71]
	v_mfma_f32_16x16x32_bf16 v[64:67], v[218:221], v[202:205], v[64:67]
	s_mov_b32 m0, s62
	s_barrier
	ds_read_b128 v[158:161], v197 offset:49152
	ds_read_b128 v[162:165], v197 offset:50176
	ds_read_b128 v[166:169], v197 offset:51200
	ds_read_b128 v[170:173], v197 offset:52224
	ds_read_b128 v[174:177], v197 offset:53248
	ds_read_b128 v[178:181], v197 offset:54272
	ds_read_b128 v[198:201], v197 offset:55296
	ds_read_b128 v[202:205], v197 offset:56320
	global_load_lds_dwordx4 v142, s[100:101]
	s_mov_b32 m0, s63
	s_nop 0
	global_load_lds_dwordx4 v138, s[100:101]
	s_barrier
	s_waitcnt lgkmcnt(0)
	v_mfma_f32_16x16x32_bf16 v[60:63], v[128:131], v[158:161], v[60:63]
	v_mfma_f32_16x16x32_bf16 v[56:59], v[150:153], v[158:161], v[56:59]
	v_mfma_f32_16x16x32_bf16 v[44:47], v[128:131], v[166:169], v[44:47]
	v_mfma_f32_16x16x32_bf16 v[40:43], v[150:153], v[166:169], v[40:43]
	v_mfma_f32_16x16x32_bf16 v[28:31], v[128:131], v[174:177], v[28:31]
	v_mfma_f32_16x16x32_bf16 v[24:27], v[150:153], v[174:177], v[24:27]
	v_mfma_f32_16x16x32_bf16 v[12:15], v[128:131], v[198:201], v[12:15]
	v_mfma_f32_16x16x32_bf16 v[8:11], v[150:153], v[198:201], v[8:11]
	v_mfma_f32_16x16x32_bf16 v[60:63], v[132:135], v[162:165], v[60:63]
	v_mfma_f32_16x16x32_bf16 v[56:59], v[154:157], v[162:165], v[56:59]
	v_mfma_f32_16x16x32_bf16 v[44:47], v[132:135], v[170:173], v[44:47]
	v_mfma_f32_16x16x32_bf16 v[40:43], v[154:157], v[170:173], v[40:43]
	v_mfma_f32_16x16x32_bf16 v[28:31], v[132:135], v[178:181], v[28:31]
	v_mfma_f32_16x16x32_bf16 v[24:27], v[154:157], v[178:181], v[24:27]
	v_mfma_f32_16x16x32_bf16 v[12:15], v[132:135], v[202:205], v[12:15]
	v_mfma_f32_16x16x32_bf16 v[8:11], v[154:157], v[202:205], v[8:11]
	s_waitcnt vmcnt(8)
	s_barrier
	s_add_u32 s22, s22, 0x40080
	s_addc_u32 s23, s23, 0
	s_add_i32 s28, s28, s52
	s_mov_b32 m0, s28
	s_nop 0
	global_load_lds_dwordx4 v140, s[22:23]
	s_add_i32 m0, s28, 0x2000
	s_nop 0
	global_load_lds_dwordx4 v136, s[22:23]
	s_waitcnt vmcnt(6)
	s_barrier
; #define PG8_MMA(ai, bj, At, Bt) do { __builtin_amdgcn_s_setprio(1); _Pragma("unroll") for (int m = 0; m < 4; ++m) _Pragma("unroll") for (int n = 0; n < 2; ++n) _Pragma("unroll") for (int k = 0; k < 2; ++k) \
;     acc[ai][bj][m][n] = __builtin_amdgcn_mfma_f32_16x16x32_bf16(Bt[n][k], At[m][k], acc[ai][bj][m][n], 0, 0, 0); __builtin_amdgcn_s_setprio(0); } while (0)
; #define PG8_WAIT_V(n) asm volatile("s_waitcnt vmcnt(" #n ")" ::: "memory")
; #define PG8_BAR __builtin_amdgcn_s_barrier()
; template <class Epi, class Sched>
; DI void gemm_phase(LAS unsigned char* lds, const Gemm g, const Sched& S, const Epi& E) {
;     ...
;       PG8_WAIT_V(6); PG8_BAR; PG8_MMA(1, 1, At, B1); PG8_BAR;
;     }
;     E(acc, cur, wr, wc, fr, fq);
;   DI void operator()(const f32x4 (&acc)[2][2][4][2], const pg8::Unit& u, int wr, int wc, int fr_, int fq_) const {
;     ...
;             if (EPI == EPI_ABIN) {
;               if (n == 0) {
;                 const int gb = u.pn * 256 + bj * 128 + wc * 32; const int f8 = gb + 8 * fq;
;                 const f32x4 v1 = acc[ai][bj][m][1];
;                 if (gb < 384) st_bf8((u16*)(big + E_CQ) + (size_t)token * 384 + f8, v, v1, rinv);
;                 else if (gb < 640) st_bf8((u16*)(big + E_CKV) + (size_t)token * 256 + (f8 - 384), v, v1, rinv);
;                 else if (gb < 672) {
;                   f32x4 a0 = v, a1 = v1;
;                   rope_perm(a0, a1, fq, t_ & 63, tcos, tsin, token & (S_ - 1));
;                   st_bf8((u16*)(big + E_KPE) + (size_t)token * 32 + 8 * fq, a0, a1, rinv);
;                 }
;                 else if (gb < 1184) st_bf8((u16*)(big + E_QNA) + (size_t)token * 512 + (f8 - 672), v, v1, rinv * (0.125f * LOG2E));
;                 else if (gb < 1696) st_bf8((u16*)(big + E_KNA) + (size_t)token * 512 + (f8 - 1184), v, v1, rinv);
;                 else if (gb < 2208) st_bf8((u16*)(big + E_VNAT) + (size_t)token * 512 + (f8 - 1696), v, v1, rinv);
;               }
	ds_read_b128 v[128:131], v222
	ds_read_b128 v[132:135], v222 offset:1024
	ds_read_b128 v[150:153], v222 offset:2048
	ds_read_b128 v[154:157], v222 offset:3072
	v_mfma_f32_16x16x32_bf16 v[52:55], v[206:209], v[158:161], v[52:55]
	v_mfma_f32_16x16x32_bf16 v[48:51], v[214:217], v[158:161], v[48:51]
	v_mfma_f32_16x16x32_bf16 v[36:39], v[206:209], v[166:169], v[36:39]
	v_mfma_f32_16x16x32_bf16 v[32:35], v[214:217], v[166:169], v[32:35]
	v_mfma_f32_16x16x32_bf16 v[20:23], v[206:209], v[174:177], v[20:23]
	v_mfma_f32_16x16x32_bf16 v[16:19], v[214:217], v[174:177], v[16:19]
	v_mfma_f32_16x16x32_bf16 v[4:7], v[206:209], v[198:201], v[4:7]
	v_mfma_f32_16x16x32_bf16 v[0:3], v[214:217], v[198:201], v[0:3]
	v_mfma_f32_16x16x32_bf16 v[52:55], v[210:213], v[162:165], v[52:55]
	v_mfma_f32_16x16x32_bf16 v[48:51], v[218:221], v[162:165], v[48:51]
	v_mfma_f32_16x16x32_bf16 v[36:39], v[210:213], v[170:173], v[36:39]
	v_mfma_f32_16x16x32_bf16 v[32:35], v[218:221], v[170:173], v[32:35]
	v_mfma_f32_16x16x32_bf16 v[20:23], v[210:213], v[178:181], v[20:23]
	v_mfma_f32_16x16x32_bf16 v[16:19], v[218:221], v[178:181], v[16:19]
	v_mfma_f32_16x16x32_bf16 v[4:7], v[210:213], v[202:205], v[4:7]
	v_mfma_f32_16x16x32_bf16 v[0:3], v[218:221], v[202:205], v[0:3]
	s_add_i32 s41, s41, 2
	s_add_u32 s20, s20, 0x100
	s_addc_u32 s21, s21, 0
	s_add_u32 s39, s39, 0x100
	s_addc_u32 s40, s40, 0
	s_cmp_gt_u32 s41, 13
	s_barrier
	s_cbranch_scc0 .LBB0_689
	s_waitcnt lgkmcnt(0)
	v_mov_b32_e32 v128, v182
	s_lshl_b32 s20, s34, 10
	v_bfe_u32 v129, v128, 4, 2
	v_and_or_b32 v201, v128, 15, s60
	s_lshl_b32 s13, s35, 8
	v_lshlrev_b32_e32 v128, 2, v128
	s_movk_i32 s21, 0x80
	s_add_i32 s20, s20, 0
	s_lshl_b32 s15, s36, 8
	v_bitop3_b32 v198, v128, s21, v190 bitop3:0x6c
	v_lshl_add_u32 v128, v201, 2, s20
	s_or_b32 s20, s13, s61
	v_add_u32_e32 v200, 0x20000, v128
	s_cmpk_gt_i32 s20, 0x17f
	ds_read_b32 v156, v200
	s_cselect_b64 s[28:29], -1, 0
	s_cmpk_gt_u32 s13, 0x27f
	s_cselect_b64 s[46:47], -1, 0
	s_cmpk_gt_u32 s20, 0x29f
	s_cselect_b64 s[40:41], -1, 0
	s_cmpk_gt_u32 s20, 0x49f
	v_lshlrev_b32_e32 v144, 3, v129
	v_add_u32_e32 v154, s15, v201
	s_cselect_b64 s[34:35], -1, 0
	s_cmpk_gt_u32 s20, 0x69f
	v_ashrrev_i32_e32 v155, 31, v154
	v_lshlrev_b32_e32 v128, 4, v154
	v_or_b32_e32 v150, s20, v144
	s_cselect_b64 s[22:23], -1, 0
	s_cmpk_lt_u32 s20, 0x8a0
	v_and_b32_e32 v199, 8, v144
	v_cmp_lt_u32_e64 s[92:93], 1, v129
	v_lshlrev_b64 v[164:165], 10, v[154:155]
	s_waitcnt lgkmcnt(0)
	v_mul_f32_e32 v162, 0x3e38aa3b, v156
	v_and_b32_e32 v157, 0xfcf0, v128
	v_lshlrev_b64 v[160:161], 6, v[154:155]
	v_lshlrev_b64 v[158:159], 9, v[154:155]
	s_cselect_b64 s[20:21], -1, 0
	v_mov_b32_e32 v152, v150
	v_mov_b32_e32 v153, v145
	s_mov_b64 s[36:37], -1
	s_and_b64 vcc, exec, s[28:29]
	s_cbranch_vccz .LBB0_714
	s_and_b64 vcc, exec, s[46:47]
	s_cbranch_vccz .LBB0_711
	s_and_b64 vcc, exec, s[40:41]
	s_cbranch_vccz .LBB0_704
	s_and_b64 vcc, exec, s[34:35]
	s_cbranch_vccz .LBB0_701
	s_and_b64 vcc, exec, s[22:23]
	s_cbranch_vccz .LBB0_698
	s_andn2_b64 vcc, exec, s[20:21]
	s_cbranch_vccnz .LBB0_697
	v_lshl_add_u64 v[128:129], s[2:3], 0, v[164:165]
	v_lshl_add_u64 v[132:133], v[152:153], 1, v[128:129]
	v_pk_mul_f32 v[128:129], v[124:125], v[156:157] op_sel_hi:[1,0]
	v_pk_mul_f32 v[130:131], v[126:127], v[156:157] op_sel_hi:[1,0]
	v_cvt_pk_bf16_f32 v128, v128, v129
	v_cvt_pk_bf16_f32 v129, v130, v131
	v_pk_mul_f32 v[130:131], v[120:121], v[156:157] op_sel_hi:[1,0]
	v_pk_mul_f32 v[134:135], v[122:123], v[156:157] op_sel_hi:[1,0]
	v_add_co_u32_e32 v132, vcc, 0x69ff000, v132
	v_cvt_pk_bf16_f32 v130, v130, v131
	v_cvt_pk_bf16_f32 v131, v134, v135
	v_addc_co_u32_e32 v133, vcc, 0, v133, vcc
	global_store_dwordx4 v[132:133], v[128:131], off offset:704

; #define PG8_STAGE(bufoff, gbase, voff) do { _Pragma("unroll") for (int _i = 0; _i < 2; ++_i) \
;     __builtin_amdgcn_global_load_lds((const unsigned*)((const char*)(gbase) + (voff)[_i]), (LAS unsigned*)(lds + (bufoff) + ldsw + _i * 8192), 16, 0, 0); } while (0)
; #define PG8_LDA(dst, b, h) do { _Pragma("unroll") for (int m = 0; m < 4; ++m) _Pragma("unroll") for (int k = 0; k < 2; ++k) dst[m][k] = *(const LAS bf16x8*)(lds + PG8_SA(b, h) + aoff + m * 2048 + k * 1024); } while (0)
; #define PG8_LDB(dst, b, h) do { _Pragma("unroll") for (int n = 0; n < 2; ++n) _Pragma("unroll") for (int k = 0; k < 2; ++k) dst[n][k] = *(const LAS bf16x8*)(lds + PG8_SB(b, h) + boff + n * 2048 + k * 1024); } while (0)
; #define PG8_WAIT_V(n) asm volatile("s_waitcnt vmcnt(" #n ")" ::: "memory")
; #define PG8_WAIT_L(n) asm volatile("s_waitcnt lgkmcnt(" #n ")" ::: "memory")
; template <class Epi, class Sched>
; DI void gemm_phase(LAS unsigned char* lds, const Gemm g, const Sched& S, const Epi& E) {
;     ...
;     for (int t = 0; t < nt; t += 2) {
;       const bool last = (t == nt - 2);
;       const char* a1 = cA + (size_t)(t + 1) * kstep;
;       const char* a2 = last ? nA : cA + (size_t)(t + 2) * kstep; const char* b2 = last ? nB : cB + (size_t)(t + 2) * kstep;
;       const char* a3 = a2 + kstep; const char* b3 = b2 + kstep;
;       PG8_LDB(B0, 0, 0); PG8_SCHED; PG8_LDA(At, 0, 0); PG8_STAGE(PG8_SA(1, 1), a1 + hstep, voffA);
;       PG8_WAIT_L(8); PG8_BAR; PG8_WAIT_L(0); PG8_MMA(0, 0, At, B0); PG8_BAR; PG8_SCHED;
;       PG8_LDB(B1, 0, 1); PG8_STAGE(PG8_SB(0, 0), b2, voffB);
;       PG8_BAR; PG8_WAIT_L(0); PG8_MMA(0, 1, At, B1); PG8_BAR;
;       PG8_LDA(At, 0, 1); PG8_STAGE(PG8_SA(0, 0), a2, voffA);
;       PG8_BAR; PG8_WAIT_L(0); PG8_MMA(1, 0, At, B0); PG8_BAR; PG8_SCHED;
;       PG8_STAGE(PG8_SB(0, 1), b2 + hstep, voffB);
;       PG8_WAIT_V(6); PG8_BAR; PG8_MMA(1, 1, At, B1); PG8_BAR;
;       PG8_LDB(B0, 1, 0); PG8_SCHED; PG8_LDA(At, 1, 0); PG8_STAGE(PG8_SA(0, 1), a2 + hstep, voffA);
;       PG8_WAIT_L(8); PG8_BAR; PG8_WAIT_L(0); PG8_MMA(0, 0, At, B0); PG8_BAR; PG8_SCHED;
;     ...
; #pragma unroll
;     for (int a = 0; a < 2; ++a)
; #pragma unroll
;       for (int b = 0; b < 2; ++b)
; #pragma unroll
;         for (int m = 0; m < 4; ++m)
; #pragma unroll
;           for (int n = 0; n < 2; ++n) acc[a][b][m][n] = (f32x4){0.f, 0.f, 0.f, 0.f};
;     cur = nxt; cA = nA; cB = nB; ++ui;
.LBB0_1201:
	s_add_u32 s52, s20, 0x100
	v_mov_b32_e32 v0, 0
	s_addc_u32 s53, s21, 0
	s_mov_b32 s54, -2
	v_mov_b32_e32 v1, v0
	v_mov_b64_e32 v[2:3], v[0:1]
	v_mov_b64_e32 v[4:5], v[0:1]
	v_mov_b64_e32 v[6:7], v[0:1]
	v_mov_b64_e32 v[8:9], v[0:1]
	v_mov_b64_e32 v[10:11], v[0:1]
	v_mov_b64_e32 v[12:13], v[0:1]
	v_mov_b64_e32 v[14:15], v[0:1]
	v_mov_b64_e32 v[16:17], v[0:1]
	v_mov_b64_e32 v[18:19], v[0:1]
	v_mov_b64_e32 v[20:21], v[0:1]
	v_mov_b64_e32 v[22:23], v[0:1]
	v_mov_b64_e32 v[24:25], v[0:1]
	v_mov_b64_e32 v[26:27], v[0:1]
	v_mov_b64_e32 v[28:29], v[0:1]
	v_mov_b64_e32 v[30:31], v[0:1]
	v_mov_b64_e32 v[32:33], v[0:1]
	v_mov_b64_e32 v[34:35], v[0:1]
	v_mov_b64_e32 v[36:37], v[0:1]
	v_mov_b64_e32 v[38:39], v[0:1]
	v_mov_b64_e32 v[40:41], v[0:1]
	v_mov_b64_e32 v[42:43], v[0:1]
	v_mov_b64_e32 v[44:45], v[0:1]
	v_mov_b64_e32 v[46:47], v[0:1]
	v_mov_b64_e32 v[48:49], v[0:1]
	v_mov_b64_e32 v[50:51], v[0:1]
	v_mov_b64_e32 v[52:53], v[0:1]
	v_mov_b64_e32 v[54:55], v[0:1]
	v_mov_b64_e32 v[56:57], v[0:1]
	v_mov_b64_e32 v[58:59], v[0:1]
	v_mov_b64_e32 v[60:61], v[0:1]
	v_mov_b64_e32 v[62:63], v[0:1]
	v_mov_b64_e32 v[64:65], v[0:1]
	v_mov_b64_e32 v[66:67], v[0:1]
	v_mov_b64_e32 v[68:69], v[0:1]
	v_mov_b64_e32 v[70:71], v[0:1]
	v_mov_b64_e32 v[72:73], v[0:1]
	v_mov_b64_e32 v[74:75], v[0:1]
	v_mov_b64_e32 v[76:77], v[0:1]
	v_mov_b64_e32 v[78:79], v[0:1]
	v_mov_b64_e32 v[80:81], v[0:1]
	v_mov_b64_e32 v[82:83], v[0:1]
	v_mov_b64_e32 v[84:85], v[0:1]
	v_mov_b64_e32 v[86:87], v[0:1]
	v_mov_b64_e32 v[88:89], v[0:1]
	v_mov_b64_e32 v[90:91], v[0:1]
	v_mov_b64_e32 v[92:93], v[0:1]
	v_mov_b64_e32 v[94:95], v[0:1]
	v_mov_b64_e32 v[96:97], v[0:1]
	v_mov_b64_e32 v[98:99], v[0:1]
	v_mov_b64_e32 v[100:101], v[0:1]
	v_mov_b64_e32 v[102:103], v[0:1]
	v_mov_b64_e32 v[104:105], v[0:1]
	v_mov_b64_e32 v[106:107], v[0:1]
	v_mov_b64_e32 v[108:109], v[0:1]
	v_mov_b64_e32 v[110:111], v[0:1]
	v_mov_b64_e32 v[112:113], v[0:1]
	v_mov_b64_e32 v[114:115], v[0:1]
	v_mov_b64_e32 v[116:117], v[0:1]
	v_mov_b64_e32 v[118:119], v[0:1]
	v_mov_b64_e32 v[120:121], v[0:1]
	v_mov_b64_e32 v[122:123], v[0:1]
	v_mov_b64_e32 v[124:125], v[0:1]
	v_mov_b64_e32 v[126:127], v[0:1]
	v_add_u32_e32 v224, 0x10000, v162
	v_add_u32_e32 v225, 0x14000, v162
	v_add_u32_e32 v226, 0x18000, v162
	v_add_u32_e32 v227, 0x1c000, v162
	ds_read_b128 v[140:143], v224
	ds_read_b128 v[146:149], v224 offset:1024
	ds_read_b128 v[150:153], v224 offset:2048
	ds_read_b128 v[154:157], v224 offset:3072
.LBB0_1202:
	s_add_u32 s20, s18, 0x100
	s_addc_u32 s21, s19, 0
	s_add_i32 s55, 0, 0x10000
	s_cmp_eq_u32 s54, 2
	s_cselect_b32 s29, s3, s21
	s_cselect_b32 s28, s2, s20
	s_cselect_b32 s23, s5, s53
	s_cselect_b32 s22, s4, s52
	s_add_i32 m0, s38, 0xc000
	ds_read_b128 v[158:161], v163
	ds_read_b128 v[164:167], v163 offset:1024
	ds_read_b128 v[168:171], v163 offset:2048
	ds_read_b128 v[172:175], v163 offset:3072
	ds_read_b128 v[176:179], v163 offset:4096
	ds_read_b128 v[196:199], v163 offset:5120
	ds_read_b128 v[200:203], v163 offset:6144
	ds_read_b128 v[204:207], v163 offset:7168
	global_load_lds_dwordx4 v136, s[18:19]
	s_add_i32 m0, s38, 0xe000
	s_nop 0
	global_load_lds_dwordx4 v138, s[18:19]
	s_waitcnt lgkmcnt(8)
	s_barrier
	s_waitcnt lgkmcnt(0)
	v_mfma_f32_16x16x32_bf16 v[124:127], v[140:143], v[158:161], v[124:127]
	v_mfma_f32_16x16x32_bf16 v[120:123], v[150:153], v[158:161], v[120:123]
	v_mfma_f32_16x16x32_bf16 v[108:111], v[140:143], v[168:171], v[108:111]
	v_mfma_f32_16x16x32_bf16 v[104:107], v[150:153], v[168:171], v[104:107]
	v_mfma_f32_16x16x32_bf16 v[92:95], v[140:143], v[176:179], v[92:95]
	v_mfma_f32_16x16x32_bf16 v[88:91], v[150:153], v[176:179], v[88:91]
	v_mfma_f32_16x16x32_bf16 v[76:79], v[140:143], v[200:203], v[76:79]
	v_mfma_f32_16x16x32_bf16 v[72:75], v[150:153], v[200:203], v[72:75]
	v_mfma_f32_16x16x32_bf16 v[124:127], v[146:149], v[164:167], v[124:127]
	v_mfma_f32_16x16x32_bf16 v[120:123], v[154:157], v[164:167], v[120:123]
	v_mfma_f32_16x16x32_bf16 v[108:111], v[146:149], v[172:175], v[108:111]
	v_mfma_f32_16x16x32_bf16 v[104:107], v[154:157], v[172:175], v[104:107]
	v_mfma_f32_16x16x32_bf16 v[92:95], v[146:149], v[196:199], v[92:95]
	v_mfma_f32_16x16x32_bf16 v[88:91], v[154:157], v[196:199], v[88:91]
	v_mfma_f32_16x16x32_bf16 v[76:79], v[146:149], v[204:207], v[76:79]
	v_mfma_f32_16x16x32_bf16 v[72:75], v[154:157], v[204:207], v[72:75]
	s_barrier
	s_add_i32 s56, 0, 0x14000
	s_add_i32 s18, s55, s35
	s_add_u32 vcc_lo, s22, s0
	s_addc_u32 vcc_hi, s23, s1
	s_mov_b32 m0, s18
	ds_read_b128 v[208:211], v225
	ds_read_b128 v[212:215], v225 offset:1024
	ds_read_b128 v[216:219], v225 offset:2048
	ds_read_b128 v[220:223], v225 offset:3072
	global_load_lds_dwordx4 v130, s[22:23]
	s_add_i32 m0, s18, 0x2000
	s_nop 0
	global_load_lds_dwordx4 v134, s[22:23]
	s_barrier
	s_waitcnt lgkmcnt(0)
	v_mfma_f32_16x16x32_bf16 v[116:119], v[208:211], v[158:161], v[116:119]
	v_mfma_f32_16x16x32_bf16 v[112:115], v[216:219], v[158:161], v[112:115]
	v_mfma_f32_16x16x32_bf16 v[100:103], v[208:211], v[168:171], v[100:103]
	v_mfma_f32_16x16x32_bf16 v[96:99], v[216:219], v[168:171], v[96:99]
	v_mfma_f32_16x16x32_bf16 v[84:87], v[208:211], v[176:179], v[84:87]
	v_mfma_f32_16x16x32_bf16 v[80:83], v[216:219], v[176:179], v[80:83]
	v_mfma_f32_16x16x32_bf16 v[68:71], v[208:211], v[200:203], v[68:71]
	v_mfma_f32_16x16x32_bf16 v[64:67], v[216:219], v[200:203], v[64:67]
	v_mfma_f32_16x16x32_bf16 v[116:119], v[212:215], v[164:167], v[116:119]
	v_mfma_f32_16x16x32_bf16 v[112:115], v[220:223], v[164:167], v[112:115]
	v_mfma_f32_16x16x32_bf16 v[100:103], v[212:215], v[172:175], v[100:103]
	v_mfma_f32_16x16x32_bf16 v[96:99], v[220:223], v[172:175], v[96:99]
	v_mfma_f32_16x16x32_bf16 v[84:87], v[212:215], v[196:199], v[84:87]
	v_mfma_f32_16x16x32_bf16 v[80:83], v[220:223], v[196:199], v[80:83]
	v_mfma_f32_16x16x32_bf16 v[68:71], v[212:215], v[204:207], v[68:71]
	v_mfma_f32_16x16x32_bf16 v[64:67], v[220:223], v[204:207], v[64:67]
	s_mov_b32 m0, s38
	s_add_u32 s100, s28, s0
	s_addc_u32 s101, s29, s1
	s_barrier
; #define PG8_STAGE(bufoff, gbase, voff) do { _Pragma("unroll") for (int _i = 0; _i < 2; ++_i) \
;     __builtin_amdgcn_global_load_lds((const unsigned*)((const char*)(gbase) + (voff)[_i]), (LAS unsigned*)(lds + (bufoff) + ldsw + _i * 8192), 16, 0, 0); } while (0)
; #define PG8_LDA(dst, b, h) do { _Pragma("unroll") for (int m = 0; m < 4; ++m) _Pragma("unroll") for (int k = 0; k < 2; ++k) dst[m][k] = *(const LAS bf16x8*)(lds + PG8_SA(b, h) + aoff + m * 2048 + k * 1024); } while (0)
; #define PG8_LDB(dst, b, h) do { _Pragma("unroll") for (int n = 0; n < 2; ++n) _Pragma("unroll") for (int k = 0; k < 2; ++k) dst[n][k] = *(const LAS bf16x8*)(lds + PG8_SB(b, h) + boff + n * 2048 + k * 1024); } while (0)
; #define PG8_MMA(ai, bj, At, Bt) do { __builtin_amdgcn_s_setprio(1); _Pragma("unroll") for (int m = 0; m < 4; ++m) _Pragma("unroll") for (int n = 0; n < 2; ++n) _Pragma("unroll") for (int k = 0; k < 2; ++k) \
;     acc[ai][bj][m][n] = __builtin_amdgcn_mfma_f32_16x16x32_bf16(Bt[n][k], At[m][k], acc[ai][bj][m][n], 0, 0, 0); __builtin_amdgcn_s_setprio(0); } while (0)
; #define PG8_WAIT_V(n) asm volatile("s_waitcnt vmcnt(" #n ")" ::: "memory")
; #define PG8_WAIT_L(n) asm volatile("s_waitcnt lgkmcnt(" #n ")" ::: "memory")
; #define PG8_BAR __builtin_amdgcn_s_barrier()
; #define PG8_SCHED __builtin_amdgcn_sched_barrier(0)
; template <class Epi, class Sched>
; DI void gemm_phase(LAS unsigned char* lds, const Gemm g, const Sched& S, const Epi& E) {
;     ...
;       PG8_LDA(At, 0, 1); PG8_STAGE(PG8_SA(0, 0), a2, voffA);
;       PG8_BAR; PG8_WAIT_L(0); PG8_MMA(1, 0, At, B0); PG8_BAR; PG8_SCHED;
;       PG8_STAGE(PG8_SB(0, 1), b2 + hstep, voffB);
;       PG8_WAIT_V(6); PG8_BAR; PG8_MMA(1, 1, At, B1); PG8_BAR;
;       PG8_LDB(B0, 1, 0); PG8_SCHED; PG8_LDA(At, 1, 0); PG8_STAGE(PG8_SA(0, 1), a2 + hstep, voffA);
;       PG8_WAIT_L(8); PG8_BAR; PG8_WAIT_L(0); PG8_MMA(0, 0, At, B0); PG8_BAR; PG8_SCHED;
;       PG8_LDB(B1, 1, 1); PG8_STAGE(PG8_SB(1, 0), b3, voffB);
	ds_read_b128 v[158:161], v163 offset:16384
	ds_read_b128 v[164:167], v163 offset:17408
	ds_read_b128 v[168:171], v163 offset:18432
	ds_read_b128 v[172:175], v163 offset:19456
	ds_read_b128 v[176:179], v163 offset:20480
	ds_read_b128 v[196:199], v163 offset:21504
	ds_read_b128 v[200:203], v163 offset:22528
	ds_read_b128 v[204:207], v163 offset:23552
	global_load_lds_dwordx4 v128, s[28:29]
	s_mov_b32 m0, s39
	s_nop 0
	global_load_lds_dwordx4 v132, s[28:29]
	s_barrier
	s_waitcnt lgkmcnt(0)
	v_mfma_f32_16x16x32_bf16 v[60:63], v[140:143], v[158:161], v[60:63]
	v_mfma_f32_16x16x32_bf16 v[56:59], v[150:153], v[158:161], v[56:59]
	v_mfma_f32_16x16x32_bf16 v[44:47], v[140:143], v[168:171], v[44:47]
	v_mfma_f32_16x16x32_bf16 v[40:43], v[150:153], v[168:171], v[40:43]
	v_mfma_f32_16x16x32_bf16 v[28:31], v[140:143], v[176:179], v[28:31]
	v_mfma_f32_16x16x32_bf16 v[24:27], v[150:153], v[176:179], v[24:27]
	v_mfma_f32_16x16x32_bf16 v[12:15], v[140:143], v[200:203], v[12:15]
	v_mfma_f32_16x16x32_bf16 v[8:11], v[150:153], v[200:203], v[8:11]
	v_mfma_f32_16x16x32_bf16 v[60:63], v[146:149], v[164:167], v[60:63]
	v_mfma_f32_16x16x32_bf16 v[56:59], v[154:157], v[164:167], v[56:59]
	v_mfma_f32_16x16x32_bf16 v[44:47], v[146:149], v[172:175], v[44:47]
	v_mfma_f32_16x16x32_bf16 v[40:43], v[154:157], v[172:175], v[40:43]
	v_mfma_f32_16x16x32_bf16 v[28:31], v[146:149], v[196:199], v[28:31]
	v_mfma_f32_16x16x32_bf16 v[24:27], v[154:157], v[196:199], v[24:27]
	v_mfma_f32_16x16x32_bf16 v[12:15], v[146:149], v[204:207], v[12:15]
	v_mfma_f32_16x16x32_bf16 v[8:11], v[154:157], v[204:207], v[8:11]
	s_waitcnt vmcnt(8)
	s_barrier
	s_add_u32 s18, s22, 0x18000
	s_addc_u32 s19, s23, 0
	s_add_i32 s55, s56, s35
	s_mov_b32 m0, s55
	s_nop 0
	global_load_lds_dwordx4 v130, s[18:19]
	s_add_i32 m0, s55, 0x2000
	s_nop 0
	global_load_lds_dwordx4 v134, s[18:19]
	s_waitcnt vmcnt(6)
	s_barrier
	ds_read_b128 v[140:143], v226
	ds_read_b128 v[146:149], v226 offset:1024
	ds_read_b128 v[150:153], v226 offset:2048
	ds_read_b128 v[154:157], v226 offset:3072
	v_mfma_f32_16x16x32_bf16 v[52:55], v[208:211], v[158:161], v[52:55]
	v_mfma_f32_16x16x32_bf16 v[48:51], v[216:219], v[158:161], v[48:51]
	v_mfma_f32_16x16x32_bf16 v[36:39], v[208:211], v[168:171], v[36:39]
	v_mfma_f32_16x16x32_bf16 v[32:35], v[216:219], v[168:171], v[32:35]
	v_mfma_f32_16x16x32_bf16 v[20:23], v[208:211], v[176:179], v[20:23]
	v_mfma_f32_16x16x32_bf16 v[16:19], v[216:219], v[176:179], v[16:19]
	v_mfma_f32_16x16x32_bf16 v[4:7], v[208:211], v[200:203], v[4:7]
	v_mfma_f32_16x16x32_bf16 v[0:3], v[216:219], v[200:203], v[0:3]
	v_mfma_f32_16x16x32_bf16 v[52:55], v[212:215], v[164:167], v[52:55]
	v_mfma_f32_16x16x32_bf16 v[48:51], v[220:223], v[164:167], v[48:51]
	v_mfma_f32_16x16x32_bf16 v[36:39], v[212:215], v[172:175], v[36:39]
	v_mfma_f32_16x16x32_bf16 v[32:35], v[220:223], v[172:175], v[32:35]
	v_mfma_f32_16x16x32_bf16 v[20:23], v[212:215], v[196:199], v[20:23]
	v_mfma_f32_16x16x32_bf16 v[16:19], v[220:223], v[196:199], v[16:19]
	v_mfma_f32_16x16x32_bf16 v[4:7], v[212:215], v[204:207], v[4:7]
	v_mfma_f32_16x16x32_bf16 v[0:3], v[220:223], v[204:207], v[0:3]
	s_add_i32 s55, 0, 0x18000
	s_barrier
	s_add_u32 s18, s28, 0x18000
	s_addc_u32 s19, s29, 0
	s_mov_b32 m0, s40
	ds_read_b128 v[158:161], v163 offset:32768
	ds_read_b128 v[164:167], v163 offset:33792
	ds_read_b128 v[168:171], v163 offset:34816
	ds_read_b128 v[172:175], v163 offset:35840
	ds_read_b128 v[176:179], v163 offset:36864
	ds_read_b128 v[196:199], v163 offset:37888
	ds_read_b128 v[200:203], v163 offset:38912
	ds_read_b128 v[204:207], v163 offset:39936
	global_load_lds_dwordx4 v128, s[18:19]
	s_mov_b32 m0, s41
	s_nop 0
	global_load_lds_dwordx4 v132, s[18:19]
	s_waitcnt lgkmcnt(8)
	s_barrier
	s_waitcnt lgkmcnt(0)
	v_mfma_f32_16x16x32_bf16 v[124:127], v[140:143], v[158:161], v[124:127]
	v_mfma_f32_16x16x32_bf16 v[120:123], v[150:153], v[158:161], v[120:123]
	v_mfma_f32_16x16x32_bf16 v[108:111], v[140:143], v[168:171], v[108:111]
	v_mfma_f32_16x16x32_bf16 v[104:107], v[150:153], v[168:171], v[104:107]
	v_mfma_f32_16x16x32_bf16 v[92:95], v[140:143], v[176:179], v[92:95]
	v_mfma_f32_16x16x32_bf16 v[88:91], v[150:153], v[176:179], v[88:91]
	v_mfma_f32_16x16x32_bf16 v[76:79], v[140:143], v[200:203], v[76:79]
	v_mfma_f32_16x16x32_bf16 v[72:75], v[150:153], v[200:203], v[72:75]
	v_mfma_f32_16x16x32_bf16 v[124:127], v[146:149], v[164:167], v[124:127]
	v_mfma_f32_16x16x32_bf16 v[120:123], v[154:157], v[164:167], v[120:123]
	v_mfma_f32_16x16x32_bf16 v[108:111], v[146:149], v[172:175], v[108:111]
	v_mfma_f32_16x16x32_bf16 v[104:107], v[154:157], v[172:175], v[104:107]
	v_mfma_f32_16x16x32_bf16 v[92:95], v[146:149], v[196:199], v[92:95]
	v_mfma_f32_16x16x32_bf16 v[88:91], v[154:157], v[196:199], v[88:91]
	v_mfma_f32_16x16x32_bf16 v[76:79], v[146:149], v[204:207], v[76:79]
	v_mfma_f32_16x16x32_bf16 v[72:75], v[154:157], v[204:207], v[72:75]
	s_barrier
	s_add_i32 s28, 0, 0x1c000
	s_add_i32 s18, s55, s35
	s_mov_b32 m0, s18
	ds_read_b128 v[208:211], v227
	ds_read_b128 v[212:215], v227 offset:1024
	ds_read_b128 v[216:219], v227 offset:2048
	ds_read_b128 v[220:223], v227 offset:3072
	global_load_lds_dwordx4 v130, vcc
	s_add_i32 m0, s18, 0x2000
	s_nop 0
	global_load_lds_dwordx4 v134, vcc
	s_barrier
; #define PG8_STAGE(bufoff, gbase, voff) do { _Pragma("unroll") for (int _i = 0; _i < 2; ++_i) \
;     __builtin_amdgcn_global_load_lds((const unsigned*)((const char*)(gbase) + (voff)[_i]), (LAS unsigned*)(lds + (bufoff) + ldsw + _i * 8192), 16, 0, 0); } while (0)
; #define PG8_LDA(dst, b, h) do { _Pragma("unroll") for (int m = 0; m < 4; ++m) _Pragma("unroll") for (int k = 0; k < 2; ++k) dst[m][k] = *(const LAS bf16x8*)(lds + PG8_SA(b, h) + aoff + m * 2048 + k * 1024); } while (0)
; #define PG8_MMA(ai, bj, At, Bt) do { __builtin_amdgcn_s_setprio(1); _Pragma("unroll") for (int m = 0; m < 4; ++m) _Pragma("unroll") for (int n = 0; n < 2; ++n) _Pragma("unroll") for (int k = 0; k < 2; ++k) \
;     acc[ai][bj][m][n] = __builtin_amdgcn_mfma_f32_16x16x32_bf16(Bt[n][k], At[m][k], acc[ai][bj][m][n], 0, 0, 0); __builtin_amdgcn_s_setprio(0); } while (0)
; #define PG8_WAIT_L(n) asm volatile("s_waitcnt lgkmcnt(" #n ")" ::: "memory")
; #define PG8_BAR __builtin_amdgcn_s_barrier()
; #define PG8_SCHED __builtin_amdgcn_sched_barrier(0)
; template <class Epi, class Sched>
; DI void gemm_phase(LAS unsigned char* lds, const Gemm g, const Sched& S, const Epi& E) {
;     ...
;       PG8_BAR; PG8_WAIT_L(0); PG8_MMA(0, 1, At, B1); PG8_BAR;
;       PG8_LDA(At, 1, 1); PG8_STAGE(PG8_SA(1, 0), a3, voffA);
;       PG8_BAR; PG8_WAIT_L(0); PG8_MMA(1, 0, At, B0); PG8_BAR; PG8_SCHED;
;       PG8_STAGE(PG8_SB(1, 1), b3 + hstep, voffB);
	s_waitcnt lgkmcnt(0)
	v_mfma_f32_16x16x32_bf16 v[116:119], v[208:211], v[158:161], v[116:119]
	v_mfma_f32_16x16x32_bf16 v[112:115], v[216:219], v[158:161], v[112:115]
	v_mfma_f32_16x16x32_bf16 v[100:103], v[208:211], v[168:171], v[100:103]
	v_mfma_f32_16x16x32_bf16 v[96:99], v[216:219], v[168:171], v[96:99]
	v_mfma_f32_16x16x32_bf16 v[84:87], v[208:211], v[176:179], v[84:87]
	v_mfma_f32_16x16x32_bf16 v[80:83], v[216:219], v[176:179], v[80:83]
	v_mfma_f32_16x16x32_bf16 v[68:71], v[208:211], v[200:203], v[68:71]
	v_mfma_f32_16x16x32_bf16 v[64:67], v[216:219], v[200:203], v[64:67]
	v_mfma_f32_16x16x32_bf16 v[116:119], v[212:215], v[164:167], v[116:119]
	v_mfma_f32_16x16x32_bf16 v[112:115], v[220:223], v[164:167], v[112:115]
	v_mfma_f32_16x16x32_bf16 v[100:103], v[212:215], v[172:175], v[100:103]
	v_mfma_f32_16x16x32_bf16 v[96:99], v[220:223], v[172:175], v[96:99]
	v_mfma_f32_16x16x32_bf16 v[84:87], v[212:215], v[196:199], v[84:87]
	v_mfma_f32_16x16x32_bf16 v[80:83], v[220:223], v[196:199], v[80:83]
	v_mfma_f32_16x16x32_bf16 v[68:71], v[212:215], v[204:207], v[68:71]
	v_mfma_f32_16x16x32_bf16 v[64:67], v[220:223], v[204:207], v[64:67]
	s_mov_b32 m0, s44
	s_barrier
	ds_read_b128 v[158:161], v163 offset:49152
	ds_read_b128 v[164:167], v163 offset:50176
	ds_read_b128 v[168:171], v163 offset:51200
	ds_read_b128 v[172:175], v163 offset:52224
	ds_read_b128 v[176:179], v163 offset:53248
	ds_read_b128 v[196:199], v163 offset:54272
	ds_read_b128 v[200:203], v163 offset:55296
	ds_read_b128 v[204:207], v163 offset:56320
	global_load_lds_dwordx4 v128, s[100:101]
	s_mov_b32 m0, s45
	s_nop 0
	global_load_lds_dwordx4 v132, s[100:101]
	s_barrier
	s_waitcnt lgkmcnt(0)
	v_mfma_f32_16x16x32_bf16 v[60:63], v[140:143], v[158:161], v[60:63]
	v_mfma_f32_16x16x32_bf16 v[56:59], v[150:153], v[158:161], v[56:59]
	v_mfma_f32_16x16x32_bf16 v[44:47], v[140:143], v[168:171], v[44:47]
	v_mfma_f32_16x16x32_bf16 v[40:43], v[150:153], v[168:171], v[40:43]
	v_mfma_f32_16x16x32_bf16 v[28:31], v[140:143], v[176:179], v[28:31]
	v_mfma_f32_16x16x32_bf16 v[24:27], v[150:153], v[176:179], v[24:27]
	v_mfma_f32_16x16x32_bf16 v[12:15], v[140:143], v[200:203], v[12:15]
	v_mfma_f32_16x16x32_bf16 v[8:11], v[150:153], v[200:203], v[8:11]
	v_mfma_f32_16x16x32_bf16 v[60:63], v[146:149], v[164:167], v[60:63]
	v_mfma_f32_16x16x32_bf16 v[56:59], v[154:157], v[164:167], v[56:59]
	v_mfma_f32_16x16x32_bf16 v[44:47], v[146:149], v[172:175], v[44:47]
	v_mfma_f32_16x16x32_bf16 v[40:43], v[154:157], v[172:175], v[40:43]
	v_mfma_f32_16x16x32_bf16 v[28:31], v[146:149], v[196:199], v[28:31]
	v_mfma_f32_16x16x32_bf16 v[24:27], v[154:157], v[196:199], v[24:27]
	v_mfma_f32_16x16x32_bf16 v[12:15], v[146:149], v[204:207], v[12:15]
	v_mfma_f32_16x16x32_bf16 v[8:11], v[154:157], v[204:207], v[8:11]
	s_waitcnt vmcnt(8)
	s_barrier
	s_add_u32 s18, s22, 0x18080
	s_addc_u32 s19, s23, 0
	s_add_i32 s22, s28, s35
	s_mov_b32 m0, s22
	s_nop 0
	global_load_lds_dwordx4 v130, s[18:19]
	s_add_i32 m0, s22, 0x2000
	s_nop 0
	global_load_lds_dwordx4 v134, s[18:19]
	s_waitcnt vmcnt(6)
	s_barrier
; #define PG8_MMA(ai, bj, At, Bt) do { __builtin_amdgcn_s_setprio(1); _Pragma("unroll") for (int m = 0; m < 4; ++m) _Pragma("unroll") for (int n = 0; n < 2; ++n) _Pragma("unroll") for (int k = 0; k < 2; ++k) \
;     acc[ai][bj][m][n] = __builtin_amdgcn_mfma_f32_16x16x32_bf16(Bt[n][k], At[m][k], acc[ai][bj][m][n], 0, 0, 0); __builtin_amdgcn_s_setprio(0); } while (0)
; #define PG8_WAIT_V(n) asm volatile("s_waitcnt vmcnt(" #n ")" ::: "memory")
; #define PG8_BAR __builtin_amdgcn_s_barrier()
; template <class Epi, class Sched>
; DI void gemm_phase(LAS unsigned char* lds, const Gemm g, const Sched& S, const Epi& E) {
;     ...
;       PG8_WAIT_V(6); PG8_BAR; PG8_MMA(1, 1, At, B1); PG8_BAR;
;     }
;     E(acc, cur, wr, wc, fr, fq);
;   DI void operator()(const f32x4 (&acc)[2][2][4][2], const pg8::Unit& u, int wr, int wc, int fr_, int fq_) const {
;     ...
;             } else if (EPI == EPI_UQ) {
;               if (n == 0) {
;                 const float sc = rinv * (0.10206207261596575f * LOG2E);
;                 const int gb = u.pn * 256 + bj * 128 + wc * 32;
;                 const int hd = gb / 96; const int within = gb - hd * 96;
;                 f32x4 a0 = v, a1 = acc[ai][bj][m][1];
;                 if (within == 64) rope_perm(a0, a1, fq, t_ & 63, tcos, tsin, token & (S_ - 1));
;                 st_bf8((u16*)(big + E_QMLA) + (size_t)token * 768 + gb + 8 * fq, a0, a1, sc);
;               }
	ds_read_b128 v[140:143], v224
	ds_read_b128 v[146:149], v224 offset:1024
	ds_read_b128 v[150:153], v224 offset:2048
	ds_read_b128 v[154:157], v224 offset:3072
	v_mfma_f32_16x16x32_bf16 v[52:55], v[208:211], v[158:161], v[52:55]
	v_mfma_f32_16x16x32_bf16 v[48:51], v[216:219], v[158:161], v[48:51]
	v_mfma_f32_16x16x32_bf16 v[36:39], v[208:211], v[168:171], v[36:39]
	v_mfma_f32_16x16x32_bf16 v[32:35], v[216:219], v[168:171], v[32:35]
	v_mfma_f32_16x16x32_bf16 v[20:23], v[208:211], v[176:179], v[20:23]
	v_mfma_f32_16x16x32_bf16 v[16:19], v[216:219], v[176:179], v[16:19]
	v_mfma_f32_16x16x32_bf16 v[4:7], v[208:211], v[200:203], v[4:7]
	v_mfma_f32_16x16x32_bf16 v[0:3], v[216:219], v[200:203], v[0:3]
	v_mfma_f32_16x16x32_bf16 v[52:55], v[212:215], v[164:167], v[52:55]
	v_mfma_f32_16x16x32_bf16 v[48:51], v[220:223], v[164:167], v[48:51]
	v_mfma_f32_16x16x32_bf16 v[36:39], v[212:215], v[172:175], v[36:39]
	v_mfma_f32_16x16x32_bf16 v[32:35], v[220:223], v[172:175], v[32:35]
	v_mfma_f32_16x16x32_bf16 v[20:23], v[212:215], v[196:199], v[20:23]
	v_mfma_f32_16x16x32_bf16 v[16:19], v[220:223], v[196:199], v[16:19]
	v_mfma_f32_16x16x32_bf16 v[4:7], v[212:215], v[204:207], v[4:7]
	v_mfma_f32_16x16x32_bf16 v[0:3], v[220:223], v[204:207], v[0:3]
	s_add_i32 s54, s54, 2
	s_add_u32 s52, s52, 0x100
	s_addc_u32 s53, s53, 0
	s_cmp_gt_u32 s54, 3
	s_mov_b64 s[18:19], s[20:21]
	s_barrier
	s_cbranch_scc0 .LBB0_1202
	s_waitcnt lgkmcnt(0)
	v_mov_b32_e32 v140, v182
	s_lshl_b32 s19, s51, 10
	s_lshl_b32 s18, s49, 8
	s_or_b32 s18, s18, s43
	v_and_or_b32 v167, v140, 15, s42
	v_lshlrev_b32_e32 v141, 2, v140
	s_movk_i32 s20, 0x80
	s_add_i32 s19, s19, 0
	v_bitop3_b32 v164, v141, s20, v190 bitop3:0x6c
	v_lshl_add_u32 v141, v167, 2, s19
	s_mul_hi_i32 s19, s18, 0x2aaaaaab
	v_add_u32_e32 v166, 0x20000, v141
	s_lshr_b32 s20, s19, 31
	s_lshr_b32 s19, s19, 4
	s_lshl_b32 s50, s50, 8
	ds_read_b32 v144, v166
	s_add_i32 s19, s19, s20
	v_add_u32_e32 v165, s50, v167
	s_mulk_i32 s19, 0x60
	v_bfe_u32 v168, v140, 4, 2
	v_lshrrev_b32_e32 v140, 1, v140
	v_lshlrev_b32_e32 v141, 4, v165
	s_sub_i32 s19, s18, s19
	v_and_b32_e32 v140, 8, v140
	v_and_b32_e32 v141, 0xfcf0, v141
	s_cmp_eq_u32 s19, 64
	v_cmp_lt_u32_e64 s[78:79], 1, v168
	s_cselect_b64 s[20:21], -1, 0
	s_cmp_lg_u32 s19, 64
	v_lshlrev_b32_e32 v142, 2, v141
	v_lshlrev_b32_e32 v140, 2, v140
	s_cbranch_scc1 .LBB0_1209
	v_mov_b32_e32 v143, v145
	v_lshl_add_u64 v[146:147], s[12:13], 0, v[142:143]
	v_mov_b32_e32 v141, v145
	v_lshl_add_u64 v[152:153], s[14:15], 0, v[142:143]
	v_lshl_add_u64 v[146:147], v[146:147], 0, v[140:141]
	v_lshl_add_u64 v[152:153], v[152:153], 0, v[140:141]
	global_load_dwordx4 v[148:151], v[146:147], off
	global_load_dwordx4 v[154:157], v[152:153], off
	global_load_dwordx4 v[170:173], v[152:153], off offset:16
	global_load_dwordx4 v[174:177], v[146:147], off offset:16
	ds_bpermute_b32 v152, v164, v124
	ds_bpermute_b32 v160, v164, v120
	ds_bpermute_b32 v153, v164, v125
	ds_bpermute_b32 v161, v164, v121
	ds_bpermute_b32 v158, v164, v126
	ds_bpermute_b32 v178, v164, v122
	ds_bpermute_b32 v159, v164, v127
	ds_bpermute_b32 v179, v164, v123
	s_waitcnt vmcnt(0) lgkmcnt(0)
	v_pk_mul_f32 v[154:155], v[154:155], v[152:153]
	v_pk_mul_f32 v[146:147], v[126:127], v[150:151]
	v_pk_mul_f32 v[150:151], v[124:125], v[148:149]
	v_pk_mul_f32 v[158:159], v[156:157], v[158:159]
	v_pk_mul_f32 v[148:149], v[170:171], v[160:161]
	v_pk_mul_f32 v[152:153], v[172:173], v[178:179]
	v_pk_mul_f32 v[156:157], v[122:123], v[176:177]
	v_pk_mul_f32 v[160:161], v[120:121], v[174:175]
	s_and_saveexec_b64 s[22:23], s[78:79]
	s_xor_b64 s[22:23], exec, s[22:23]
	v_pk_add_f32 v[126:127], v[146:147], v[158:159]
	v_pk_add_f32 v[124:125], v[150:151], v[154:155]
	v_pk_add_f32 v[122:123], v[156:157], v[152:153]
	v_pk_add_f32 v[120:121], v[160:161], v[148:149]
	s_andn2_saveexec_b64 s[22:23], s[22:23]
	v_sub_f32_e32 v127, v147, v159
	v_sub_f32_e32 v126, v146, v158
	v_sub_f32_e32 v125, v151, v155
	v_sub_f32_e32 v124, v150, v154
	v_sub_f32_e32 v123, v157, v153
	v_sub_f32_e32 v122, v156, v152
	v_sub_f32_e32 v121, v161, v149
	v_sub_f32_e32 v120, v160, v148
	s_or_b64 exec, exec, s[22:23]

; #define PG8_STAGE(bufoff, gbase, voff) do { _Pragma("unroll") for (int _i = 0; _i < 2; ++_i) \
;     __builtin_amdgcn_global_load_lds((const unsigned*)((const char*)(gbase) + (voff)[_i]), (LAS unsigned*)(lds + (bufoff) + ldsw + _i * 8192), 16, 0, 0); } while (0)
; #define PG8_LDA(dst, b, h) do { _Pragma("unroll") for (int m = 0; m < 4; ++m) _Pragma("unroll") for (int k = 0; k < 2; ++k) dst[m][k] = *(const LAS bf16x8*)(lds + PG8_SA(b, h) + aoff + m * 2048 + k * 1024); } while (0)
; #define PG8_LDB(dst, b, h) do { _Pragma("unroll") for (int n = 0; n < 2; ++n) _Pragma("unroll") for (int k = 0; k < 2; ++k) dst[n][k] = *(const LAS bf16x8*)(lds + PG8_SB(b, h) + boff + n * 2048 + k * 1024); } while (0)
; #define PG8_MMA(ai, bj, At, Bt) do { __builtin_amdgcn_s_setprio(1); _Pragma("unroll") for (int m = 0; m < 4; ++m) _Pragma("unroll") for (int n = 0; n < 2; ++n) _Pragma("unroll") for (int k = 0; k < 2; ++k) \
;     acc[ai][bj][m][n] = __builtin_amdgcn_mfma_f32_16x16x32_bf16(Bt[n][k], At[m][k], acc[ai][bj][m][n], 0, 0, 0); __builtin_amdgcn_s_setprio(0); } while (0)
; #define PG8_WAIT_L(n) asm volatile("s_waitcnt lgkmcnt(" #n ")" ::: "memory")
; #define PG8_BAR __builtin_amdgcn_s_barrier()
; #define PG8_SCHED __builtin_amdgcn_sched_barrier(0)
; template <class Epi, class Sched>
; DI void gemm_phase(LAS unsigned char* lds, const Gemm g, const Sched& S, const Epi& E) {
;     ...
;     for (int t = 0; t < nt; t += 2) {
;       const bool last = (t == nt - 2);
;       const char* a1 = cA + (size_t)(t + 1) * kstep;
;       const char* a2 = last ? nA : cA + (size_t)(t + 2) * kstep; const char* b2 = last ? nB : cB + (size_t)(t + 2) * kstep;
;       const char* a3 = a2 + kstep; const char* b3 = b2 + kstep;
;       PG8_LDB(B0, 0, 0); PG8_SCHED; PG8_LDA(At, 0, 0); PG8_STAGE(PG8_SA(1, 1), a1 + hstep, voffA);
;       PG8_WAIT_L(8); PG8_BAR; PG8_WAIT_L(0); PG8_MMA(0, 0, At, B0); PG8_BAR; PG8_SCHED;
;     ...
; #pragma unroll
;     for (int a = 0; a < 2; ++a)
; #pragma unroll
;       for (int b = 0; b < 2; ++b)
; #pragma unroll
;         for (int m = 0; m < 4; ++m)
; #pragma unroll
;           for (int n = 0; n < 2; ++n) acc[a][b][m][n] = (f32x4){0.f, 0.f, 0.f, 0.f};
;     cur = nxt; cA = nA; cB = nB; ++ui;
.LBB0_1345:
	v_mov_b64_e32 v[0:1], s[30:31]
	s_ashr_i32 s15, s14, 31
	v_cmp_lt_i64_e32 vcc, s[16:17], v[0:1]
	s_lshl_b64 s[16:17], s[14:15], 17
	s_add_u32 s16, s52, s16
	s_addc_u32 s17, s53, s17
	s_and_b64 s[18:19], vcc, exec
	s_cselect_b32 s15, s17, s29
	s_cselect_b32 s21, s16, s28
	s_ashr_i32 s13, s12, 31
	s_lshl_b64 s[18:19], s[12:13], 17
	s_add_u32 s18, s54, s18
	s_addc_u32 s19, s55, s19
	s_and_b64 s[34:35], vcc, exec
	v_mov_b32_e32 v0, 0
	s_cselect_b32 s13, s19, s23
	s_cselect_b32 s24, s18, s22
	s_mov_b64 s[40:41], 0
	s_mov_b64 s[34:35], -1
	s_mov_b64 s[36:37], 0
	v_mov_b32_e32 v1, v0
	v_mov_b64_e32 v[2:3], v[0:1]
	v_mov_b64_e32 v[4:5], v[0:1]
	v_mov_b64_e32 v[6:7], v[0:1]
	v_mov_b64_e32 v[8:9], v[0:1]
	v_mov_b64_e32 v[10:11], v[0:1]
	v_mov_b64_e32 v[12:13], v[0:1]
	v_mov_b64_e32 v[14:15], v[0:1]
	v_mov_b64_e32 v[16:17], v[0:1]
	v_mov_b64_e32 v[18:19], v[0:1]
	v_mov_b64_e32 v[20:21], v[0:1]
	v_mov_b64_e32 v[22:23], v[0:1]
	v_mov_b64_e32 v[24:25], v[0:1]
	v_mov_b64_e32 v[26:27], v[0:1]
	v_mov_b64_e32 v[28:29], v[0:1]
	v_mov_b64_e32 v[30:31], v[0:1]
	v_mov_b64_e32 v[32:33], v[0:1]
	v_mov_b64_e32 v[34:35], v[0:1]
	v_mov_b64_e32 v[36:37], v[0:1]
	v_mov_b64_e32 v[38:39], v[0:1]
	v_mov_b64_e32 v[40:41], v[0:1]
	v_mov_b64_e32 v[42:43], v[0:1]
	v_mov_b64_e32 v[44:45], v[0:1]
	v_mov_b64_e32 v[46:47], v[0:1]
	v_mov_b64_e32 v[48:49], v[0:1]
	v_mov_b64_e32 v[50:51], v[0:1]
	v_mov_b64_e32 v[52:53], v[0:1]
	v_mov_b64_e32 v[54:55], v[0:1]
	v_mov_b64_e32 v[56:57], v[0:1]
	v_mov_b64_e32 v[58:59], v[0:1]
	v_mov_b64_e32 v[60:61], v[0:1]
	v_mov_b64_e32 v[62:63], v[0:1]
	v_mov_b64_e32 v[64:65], v[0:1]
	v_mov_b64_e32 v[66:67], v[0:1]
	v_mov_b64_e32 v[68:69], v[0:1]
	v_mov_b64_e32 v[70:71], v[0:1]
	v_mov_b64_e32 v[72:73], v[0:1]
	v_mov_b64_e32 v[74:75], v[0:1]
	v_mov_b64_e32 v[76:77], v[0:1]
	v_mov_b64_e32 v[78:79], v[0:1]
	v_mov_b64_e32 v[80:81], v[0:1]
	v_mov_b64_e32 v[82:83], v[0:1]
	v_mov_b64_e32 v[84:85], v[0:1]
	v_mov_b64_e32 v[86:87], v[0:1]
	v_mov_b64_e32 v[88:89], v[0:1]
	v_mov_b64_e32 v[90:91], v[0:1]
	v_mov_b64_e32 v[92:93], v[0:1]
	v_mov_b64_e32 v[94:95], v[0:1]
	v_mov_b64_e32 v[96:97], v[0:1]
	v_mov_b64_e32 v[98:99], v[0:1]
	v_mov_b64_e32 v[100:101], v[0:1]
	v_mov_b64_e32 v[102:103], v[0:1]
	v_mov_b64_e32 v[104:105], v[0:1]
	v_mov_b64_e32 v[106:107], v[0:1]
	v_mov_b64_e32 v[108:109], v[0:1]
	v_mov_b64_e32 v[110:111], v[0:1]
	v_mov_b64_e32 v[112:113], v[0:1]
	v_mov_b64_e32 v[114:115], v[0:1]
	v_mov_b64_e32 v[116:117], v[0:1]
	v_mov_b64_e32 v[118:119], v[0:1]
	v_mov_b64_e32 v[120:121], v[0:1]
	v_mov_b64_e32 v[122:123], v[0:1]
	v_mov_b64_e32 v[124:125], v[0:1]
	v_mov_b64_e32 v[126:127], v[0:1]
	v_add_u32_e32 v220, 0x10000, v142
	v_add_u32_e32 v221, 0x14000, v142
	v_add_u32_e32 v222, 0x18000, v142
	v_add_u32_e32 v223, 0x1c000, v142
	ds_read_b128 v[136:139], v220
	ds_read_b128 v[146:149], v220 offset:1024
	ds_read_b128 v[150:153], v220 offset:2048
	ds_read_b128 v[154:157], v220 offset:3072
.LBB0_1346:
	s_add_u32 s48, s28, s40
	s_addc_u32 s49, s29, s41
	s_add_u32 s44, s48, 0x100
	s_addc_u32 s45, s49, 0
	s_and_b64 s[42:43], s[36:37], exec
	s_cselect_b32 s45, s15, s45
	s_cselect_b32 s44, s21, s44
	s_add_u32 s40, s22, s40
	s_addc_u32 s41, s23, s41
	s_add_u32 s40, s40, 0x100
	s_addc_u32 s41, s41, 0
	s_add_i32 s70, 0, 0x10000
	s_and_b64 s[36:37], s[36:37], exec
	s_cselect_b32 s47, s13, s41
	s_cselect_b32 s46, s24, s40
	s_add_u32 s48, s48, 0x10080
	s_addc_u32 s49, s49, 0
	s_add_i32 s74, s70, s51
	s_add_i32 m0, s56, 0xc000
	s_add_i32 s75, s56, 0xe000
	s_add_i32 s73, 0, 0x14000
	s_add_i32 s72, s74, 0x2000
	s_add_u32 s42, s46, 0x10000
	s_addc_u32 s43, s47, 0
	s_add_i32 s69, s73, s51
	s_add_i32 s68, s69, 0x2000
	s_add_i32 s67, 0, 0x18000
	s_add_u32 s40, s44, 0x10000
	s_addc_u32 s41, s45, 0
	s_add_i32 s66, s67, s51
	s_add_i32 s65, 0, 0x1c000
	s_add_i32 s64, s66, 0x2000
	s_add_u32 s36, s46, 0x10080
	s_addc_u32 s37, s47, 0
	s_add_i32 s71, s65, s51
	s_add_i32 s70, s71, 0x2000
	ds_read_b128 v[158:161], v143
	ds_read_b128 v[162:165], v143 offset:1024
	ds_read_b128 v[166:169], v143 offset:2048
	ds_read_b128 v[170:173], v143 offset:3072
	ds_read_b128 v[174:177], v143 offset:4096
	ds_read_b128 v[178:181], v143 offset:5120
	ds_read_b128 v[196:199], v143 offset:6144
	ds_read_b128 v[200:203], v143 offset:7168
	global_load_lds_dwordx4 v128, s[48:49]
	s_mov_b32 m0, s75
	s_nop 0
	global_load_lds_dwordx4 v132, s[48:49]
	s_waitcnt lgkmcnt(8)
	s_barrier
	s_waitcnt lgkmcnt(0)
	v_mfma_f32_16x16x32_bf16 v[124:127], v[136:139], v[158:161], v[124:127]
	v_mfma_f32_16x16x32_bf16 v[120:123], v[150:153], v[158:161], v[120:123]
	v_mfma_f32_16x16x32_bf16 v[108:111], v[136:139], v[166:169], v[108:111]
	v_mfma_f32_16x16x32_bf16 v[104:107], v[150:153], v[166:169], v[104:107]
	v_mfma_f32_16x16x32_bf16 v[92:95], v[136:139], v[174:177], v[92:95]
	v_mfma_f32_16x16x32_bf16 v[88:91], v[150:153], v[174:177], v[88:91]
	v_mfma_f32_16x16x32_bf16 v[76:79], v[136:139], v[196:199], v[76:79]
	v_mfma_f32_16x16x32_bf16 v[72:75], v[150:153], v[196:199], v[72:75]
	v_mfma_f32_16x16x32_bf16 v[124:127], v[146:149], v[162:165], v[124:127]
	v_mfma_f32_16x16x32_bf16 v[120:123], v[154:157], v[162:165], v[120:123]
	v_mfma_f32_16x16x32_bf16 v[108:111], v[146:149], v[170:173], v[108:111]
	v_mfma_f32_16x16x32_bf16 v[104:107], v[154:157], v[170:173], v[104:107]
	v_mfma_f32_16x16x32_bf16 v[92:95], v[146:149], v[178:181], v[92:95]
	v_mfma_f32_16x16x32_bf16 v[88:91], v[154:157], v[178:181], v[88:91]
	v_mfma_f32_16x16x32_bf16 v[76:79], v[146:149], v[200:203], v[76:79]
	v_mfma_f32_16x16x32_bf16 v[72:75], v[154:157], v[200:203], v[72:75]
	s_barrier
; #define PG8_STAGE(bufoff, gbase, voff) do { _Pragma("unroll") for (int _i = 0; _i < 2; ++_i) \
;     __builtin_amdgcn_global_load_lds((const unsigned*)((const char*)(gbase) + (voff)[_i]), (LAS unsigned*)(lds + (bufoff) + ldsw + _i * 8192), 16, 0, 0); } while (0)
; #define PG8_LDA(dst, b, h) do { _Pragma("unroll") for (int m = 0; m < 4; ++m) _Pragma("unroll") for (int k = 0; k < 2; ++k) dst[m][k] = *(const LAS bf16x8*)(lds + PG8_SA(b, h) + aoff + m * 2048 + k * 1024); } while (0)
; #define PG8_LDB(dst, b, h) do { _Pragma("unroll") for (int n = 0; n < 2; ++n) _Pragma("unroll") for (int k = 0; k < 2; ++k) dst[n][k] = *(const LAS bf16x8*)(lds + PG8_SB(b, h) + boff + n * 2048 + k * 1024); } while (0)
; #define PG8_MMA(ai, bj, At, Bt) do { __builtin_amdgcn_s_setprio(1); _Pragma("unroll") for (int m = 0; m < 4; ++m) _Pragma("unroll") for (int n = 0; n < 2; ++n) _Pragma("unroll") for (int k = 0; k < 2; ++k) \
;     acc[ai][bj][m][n] = __builtin_amdgcn_mfma_f32_16x16x32_bf16(Bt[n][k], At[m][k], acc[ai][bj][m][n], 0, 0, 0); __builtin_amdgcn_s_setprio(0); } while (0)
; #define PG8_WAIT_V(n) asm volatile("s_waitcnt vmcnt(" #n ")" ::: "memory")
; #define PG8_WAIT_L(n) asm volatile("s_waitcnt lgkmcnt(" #n ")" ::: "memory")
; #define PG8_BAR __builtin_amdgcn_s_barrier()
; #define PG8_SCHED __builtin_amdgcn_sched_barrier(0)
; template <class Epi, class Sched>
; DI void gemm_phase(LAS unsigned char* lds, const Gemm g, const Sched& S, const Epi& E) {
;     ...
;       PG8_LDB(B1, 0, 1); PG8_STAGE(PG8_SB(0, 0), b2, voffB);
;       PG8_BAR; PG8_WAIT_L(0); PG8_MMA(0, 1, At, B1); PG8_BAR;
;       PG8_LDA(At, 0, 1); PG8_STAGE(PG8_SA(0, 0), a2, voffA);
;       PG8_BAR; PG8_WAIT_L(0); PG8_MMA(1, 0, At, B0); PG8_BAR; PG8_SCHED;
;       PG8_STAGE(PG8_SB(0, 1), b2 + hstep, voffB);
;       PG8_WAIT_V(6); PG8_BAR; PG8_MMA(1, 1, At, B1); PG8_BAR;
;       PG8_LDB(B0, 1, 0); PG8_SCHED; PG8_LDA(At, 1, 0); PG8_STAGE(PG8_SA(0, 1), a2 + hstep, voffA);
;       PG8_WAIT_L(8); PG8_BAR; PG8_WAIT_L(0); PG8_MMA(0, 0, At, B0); PG8_BAR; PG8_SCHED;
	s_mov_b32 m0, s74
	ds_read_b128 v[204:207], v221
	ds_read_b128 v[208:211], v221 offset:1024
	ds_read_b128 v[212:215], v221 offset:2048
	ds_read_b128 v[216:219], v221 offset:3072
	s_add_u32 vcc_lo, s46, s0
	s_addc_u32 vcc_hi, s47, s1
	global_load_lds_dwordx4 v130, s[46:47]
	s_mov_b32 m0, s72
	s_nop 0
	global_load_lds_dwordx4 v134, s[46:47]
	s_barrier
	s_waitcnt lgkmcnt(0)
	v_mfma_f32_16x16x32_bf16 v[116:119], v[204:207], v[158:161], v[116:119]
	v_mfma_f32_16x16x32_bf16 v[112:115], v[212:215], v[158:161], v[112:115]
	v_mfma_f32_16x16x32_bf16 v[100:103], v[204:207], v[166:169], v[100:103]
	v_mfma_f32_16x16x32_bf16 v[96:99], v[212:215], v[166:169], v[96:99]
	v_mfma_f32_16x16x32_bf16 v[84:87], v[204:207], v[174:177], v[84:87]
	v_mfma_f32_16x16x32_bf16 v[80:83], v[212:215], v[174:177], v[80:83]
	v_mfma_f32_16x16x32_bf16 v[68:71], v[204:207], v[196:199], v[68:71]
	v_mfma_f32_16x16x32_bf16 v[64:67], v[212:215], v[196:199], v[64:67]
	v_mfma_f32_16x16x32_bf16 v[116:119], v[208:211], v[162:165], v[116:119]
	v_mfma_f32_16x16x32_bf16 v[112:115], v[216:219], v[162:165], v[112:115]
	v_mfma_f32_16x16x32_bf16 v[100:103], v[208:211], v[170:173], v[100:103]
	v_mfma_f32_16x16x32_bf16 v[96:99], v[216:219], v[170:173], v[96:99]
	v_mfma_f32_16x16x32_bf16 v[84:87], v[208:211], v[178:181], v[84:87]
	v_mfma_f32_16x16x32_bf16 v[80:83], v[216:219], v[178:181], v[80:83]
	v_mfma_f32_16x16x32_bf16 v[68:71], v[208:211], v[200:203], v[68:71]
	v_mfma_f32_16x16x32_bf16 v[64:67], v[216:219], v[200:203], v[64:67]
	s_mov_b32 m0, s56
	s_add_u32 s100, s44, s0
	s_addc_u32 s101, s45, s1
	s_barrier
	ds_read_b128 v[158:161], v143 offset:16384
	ds_read_b128 v[162:165], v143 offset:17408
	ds_read_b128 v[166:169], v143 offset:18432
	ds_read_b128 v[170:173], v143 offset:19456
	ds_read_b128 v[174:177], v143 offset:20480
	ds_read_b128 v[178:181], v143 offset:21504
	ds_read_b128 v[196:199], v143 offset:22528
	ds_read_b128 v[200:203], v143 offset:23552
	global_load_lds_dwordx4 v128, s[44:45]
	s_mov_b32 m0, s57
	s_nop 0
	global_load_lds_dwordx4 v132, s[44:45]
	s_barrier
	s_waitcnt lgkmcnt(0)
	v_mfma_f32_16x16x32_bf16 v[60:63], v[136:139], v[158:161], v[60:63]
	v_mfma_f32_16x16x32_bf16 v[56:59], v[150:153], v[158:161], v[56:59]
	v_mfma_f32_16x16x32_bf16 v[44:47], v[136:139], v[166:169], v[44:47]
	v_mfma_f32_16x16x32_bf16 v[40:43], v[150:153], v[166:169], v[40:43]
	v_mfma_f32_16x16x32_bf16 v[28:31], v[136:139], v[174:177], v[28:31]
	v_mfma_f32_16x16x32_bf16 v[24:27], v[150:153], v[174:177], v[24:27]
	v_mfma_f32_16x16x32_bf16 v[12:15], v[136:139], v[196:199], v[12:15]
	v_mfma_f32_16x16x32_bf16 v[8:11], v[150:153], v[196:199], v[8:11]
	v_mfma_f32_16x16x32_bf16 v[60:63], v[146:149], v[162:165], v[60:63]
	v_mfma_f32_16x16x32_bf16 v[56:59], v[154:157], v[162:165], v[56:59]
	v_mfma_f32_16x16x32_bf16 v[44:47], v[146:149], v[170:173], v[44:47]
	v_mfma_f32_16x16x32_bf16 v[40:43], v[154:157], v[170:173], v[40:43]
	v_mfma_f32_16x16x32_bf16 v[28:31], v[146:149], v[178:181], v[28:31]
	v_mfma_f32_16x16x32_bf16 v[24:27], v[154:157], v[178:181], v[24:27]
	v_mfma_f32_16x16x32_bf16 v[12:15], v[146:149], v[200:203], v[12:15]
	v_mfma_f32_16x16x32_bf16 v[8:11], v[154:157], v[200:203], v[8:11]
	s_waitcnt vmcnt(8)
	s_barrier
	s_mov_b32 m0, s69
	s_nop 0
	global_load_lds_dwordx4 v130, s[42:43]
	s_mov_b32 m0, s68
	s_nop 0
	global_load_lds_dwordx4 v134, s[42:43]
	s_waitcnt vmcnt(6)
	s_barrier
	ds_read_b128 v[136:139], v222
	ds_read_b128 v[146:149], v222 offset:1024
	ds_read_b128 v[150:153], v222 offset:2048
	ds_read_b128 v[154:157], v222 offset:3072
	v_mfma_f32_16x16x32_bf16 v[52:55], v[204:207], v[158:161], v[52:55]
	v_mfma_f32_16x16x32_bf16 v[48:51], v[212:215], v[158:161], v[48:51]
	v_mfma_f32_16x16x32_bf16 v[36:39], v[204:207], v[166:169], v[36:39]
	v_mfma_f32_16x16x32_bf16 v[32:35], v[212:215], v[166:169], v[32:35]
	v_mfma_f32_16x16x32_bf16 v[20:23], v[204:207], v[174:177], v[20:23]
	v_mfma_f32_16x16x32_bf16 v[16:19], v[212:215], v[174:177], v[16:19]
	v_mfma_f32_16x16x32_bf16 v[4:7], v[204:207], v[196:199], v[4:7]
	v_mfma_f32_16x16x32_bf16 v[0:3], v[212:215], v[196:199], v[0:3]
	v_mfma_f32_16x16x32_bf16 v[52:55], v[208:211], v[162:165], v[52:55]
	v_mfma_f32_16x16x32_bf16 v[48:51], v[216:219], v[162:165], v[48:51]
	v_mfma_f32_16x16x32_bf16 v[36:39], v[208:211], v[170:173], v[36:39]
	v_mfma_f32_16x16x32_bf16 v[32:35], v[216:219], v[170:173], v[32:35]
	v_mfma_f32_16x16x32_bf16 v[20:23], v[208:211], v[178:181], v[20:23]
	v_mfma_f32_16x16x32_bf16 v[16:19], v[216:219], v[178:181], v[16:19]
	v_mfma_f32_16x16x32_bf16 v[4:7], v[208:211], v[200:203], v[4:7]
	v_mfma_f32_16x16x32_bf16 v[0:3], v[216:219], v[200:203], v[0:3]
	s_barrier
	s_mov_b32 m0, s58
	ds_read_b128 v[158:161], v143 offset:32768
	ds_read_b128 v[162:165], v143 offset:33792
	ds_read_b128 v[166:169], v143 offset:34816
	ds_read_b128 v[170:173], v143 offset:35840
	ds_read_b128 v[174:177], v143 offset:36864
	ds_read_b128 v[178:181], v143 offset:37888
	ds_read_b128 v[196:199], v143 offset:38912
	ds_read_b128 v[200:203], v143 offset:39936
	global_load_lds_dwordx4 v128, s[40:41]
	s_mov_b32 m0, s59
	s_nop 0
	global_load_lds_dwordx4 v132, s[40:41]
	s_waitcnt lgkmcnt(8)
	s_barrier
; #define PG8_STAGE(bufoff, gbase, voff) do { _Pragma("unroll") for (int _i = 0; _i < 2; ++_i) \
;     __builtin_amdgcn_global_load_lds((const unsigned*)((const char*)(gbase) + (voff)[_i]), (LAS unsigned*)(lds + (bufoff) + ldsw + _i * 8192), 16, 0, 0); } while (0)
; #define PG8_LDA(dst, b, h) do { _Pragma("unroll") for (int m = 0; m < 4; ++m) _Pragma("unroll") for (int k = 0; k < 2; ++k) dst[m][k] = *(const LAS bf16x8*)(lds + PG8_SA(b, h) + aoff + m * 2048 + k * 1024); } while (0)
; #define PG8_LDB(dst, b, h) do { _Pragma("unroll") for (int n = 0; n < 2; ++n) _Pragma("unroll") for (int k = 0; k < 2; ++k) dst[n][k] = *(const LAS bf16x8*)(lds + PG8_SB(b, h) + boff + n * 2048 + k * 1024); } while (0)
; #define PG8_MMA(ai, bj, At, Bt) do { __builtin_amdgcn_s_setprio(1); _Pragma("unroll") for (int m = 0; m < 4; ++m) _Pragma("unroll") for (int n = 0; n < 2; ++n) _Pragma("unroll") for (int k = 0; k < 2; ++k) \
;     acc[ai][bj][m][n] = __builtin_amdgcn_mfma_f32_16x16x32_bf16(Bt[n][k], At[m][k], acc[ai][bj][m][n], 0, 0, 0); __builtin_amdgcn_s_setprio(0); } while (0)
; #define PG8_WAIT_L(n) asm volatile("s_waitcnt lgkmcnt(" #n ")" ::: "memory")
; #define PG8_BAR __builtin_amdgcn_s_barrier()
; template <class Epi, class Sched>
; DI void gemm_phase(LAS unsigned char* lds, const Gemm g, const Sched& S, const Epi& E) {
;     ...
;       PG8_LDB(B1, 1, 1); PG8_STAGE(PG8_SB(1, 0), b3, voffB);
;       PG8_BAR; PG8_WAIT_L(0); PG8_MMA(0, 1, At, B1); PG8_BAR;
;       PG8_LDA(At, 1, 1); PG8_STAGE(PG8_SA(1, 0), a3, voffA);
	s_waitcnt lgkmcnt(0)
	v_mfma_f32_16x16x32_bf16 v[124:127], v[136:139], v[158:161], v[124:127]
	v_mfma_f32_16x16x32_bf16 v[120:123], v[150:153], v[158:161], v[120:123]
	v_mfma_f32_16x16x32_bf16 v[108:111], v[136:139], v[166:169], v[108:111]
	v_mfma_f32_16x16x32_bf16 v[104:107], v[150:153], v[166:169], v[104:107]
	v_mfma_f32_16x16x32_bf16 v[92:95], v[136:139], v[174:177], v[92:95]
	v_mfma_f32_16x16x32_bf16 v[88:91], v[150:153], v[174:177], v[88:91]
	v_mfma_f32_16x16x32_bf16 v[76:79], v[136:139], v[196:199], v[76:79]
	v_mfma_f32_16x16x32_bf16 v[72:75], v[150:153], v[196:199], v[72:75]
	v_mfma_f32_16x16x32_bf16 v[124:127], v[146:149], v[162:165], v[124:127]
	v_mfma_f32_16x16x32_bf16 v[120:123], v[154:157], v[162:165], v[120:123]
	v_mfma_f32_16x16x32_bf16 v[108:111], v[146:149], v[170:173], v[108:111]
	v_mfma_f32_16x16x32_bf16 v[104:107], v[154:157], v[170:173], v[104:107]
	v_mfma_f32_16x16x32_bf16 v[92:95], v[146:149], v[178:181], v[92:95]
	v_mfma_f32_16x16x32_bf16 v[88:91], v[154:157], v[178:181], v[88:91]
	v_mfma_f32_16x16x32_bf16 v[76:79], v[146:149], v[200:203], v[76:79]
	v_mfma_f32_16x16x32_bf16 v[72:75], v[154:157], v[200:203], v[72:75]
	s_barrier
	s_mov_b32 m0, s66
	ds_read_b128 v[204:207], v223
	ds_read_b128 v[208:211], v223 offset:1024
	ds_read_b128 v[212:215], v223 offset:2048
	ds_read_b128 v[216:219], v223 offset:3072
	global_load_lds_dwordx4 v130, vcc
	s_mov_b32 m0, s64
	s_nop 0
	global_load_lds_dwordx4 v134, vcc
	s_barrier
	s_waitcnt lgkmcnt(0)
	v_mfma_f32_16x16x32_bf16 v[116:119], v[204:207], v[158:161], v[116:119]
	v_mfma_f32_16x16x32_bf16 v[112:115], v[212:215], v[158:161], v[112:115]
	v_mfma_f32_16x16x32_bf16 v[100:103], v[204:207], v[166:169], v[100:103]
	v_mfma_f32_16x16x32_bf16 v[96:99], v[212:215], v[166:169], v[96:99]
	v_mfma_f32_16x16x32_bf16 v[84:87], v[204:207], v[174:177], v[84:87]
	v_mfma_f32_16x16x32_bf16 v[80:83], v[212:215], v[174:177], v[80:83]
	v_mfma_f32_16x16x32_bf16 v[68:71], v[204:207], v[196:199], v[68:71]
	v_mfma_f32_16x16x32_bf16 v[64:67], v[212:215], v[196:199], v[64:67]
	v_mfma_f32_16x16x32_bf16 v[116:119], v[208:211], v[162:165], v[116:119]
	v_mfma_f32_16x16x32_bf16 v[112:115], v[216:219], v[162:165], v[112:115]
	v_mfma_f32_16x16x32_bf16 v[100:103], v[208:211], v[170:173], v[100:103]
	v_mfma_f32_16x16x32_bf16 v[96:99], v[216:219], v[170:173], v[96:99]
	v_mfma_f32_16x16x32_bf16 v[84:87], v[208:211], v[178:181], v[84:87]
	v_mfma_f32_16x16x32_bf16 v[80:83], v[216:219], v[178:181], v[80:83]
	v_mfma_f32_16x16x32_bf16 v[68:71], v[208:211], v[200:203], v[68:71]
	v_mfma_f32_16x16x32_bf16 v[64:67], v[216:219], v[200:203], v[64:67]
	s_mov_b32 m0, s62
	s_barrier
	ds_read_b128 v[158:161], v143 offset:49152
	ds_read_b128 v[162:165], v143 offset:50176
	ds_read_b128 v[166:169], v143 offset:51200
	ds_read_b128 v[170:173], v143 offset:52224
	ds_read_b128 v[174:177], v143 offset:53248
	ds_read_b128 v[178:181], v143 offset:54272
	ds_read_b128 v[196:199], v143 offset:55296
	ds_read_b128 v[200:203], v143 offset:56320
	global_load_lds_dwordx4 v128, s[100:101]
	s_mov_b32 m0, s63
	s_nop 0
	global_load_lds_dwordx4 v132, s[100:101]
	s_barrier
; #define PG8_STAGE(bufoff, gbase, voff) do { _Pragma("unroll") for (int _i = 0; _i < 2; ++_i) \
;     __builtin_amdgcn_global_load_lds((const unsigned*)((const char*)(gbase) + (voff)[_i]), (LAS unsigned*)(lds + (bufoff) + ldsw + _i * 8192), 16, 0, 0); } while (0)
; #define PG8_MMA(ai, bj, At, Bt) do { __builtin_amdgcn_s_setprio(1); _Pragma("unroll") for (int m = 0; m < 4; ++m) _Pragma("unroll") for (int n = 0; n < 2; ++n) _Pragma("unroll") for (int k = 0; k < 2; ++k) \
;     acc[ai][bj][m][n] = __builtin_amdgcn_mfma_f32_16x16x32_bf16(Bt[n][k], At[m][k], acc[ai][bj][m][n], 0, 0, 0); __builtin_amdgcn_s_setprio(0); } while (0)
; #define PG8_WAIT_V(n) asm volatile("s_waitcnt vmcnt(" #n ")" ::: "memory")
; #define PG8_WAIT_L(n) asm volatile("s_waitcnt lgkmcnt(" #n ")" ::: "memory")
; #define PG8_BAR __builtin_amdgcn_s_barrier()
; #define PG8_SCHED __builtin_amdgcn_sched_barrier(0)
; template <class Epi, class Sched>
; DI void gemm_phase(LAS unsigned char* lds, const Gemm g, const Sched& S, const Epi& E) {
;     ...
;       PG8_BAR; PG8_WAIT_L(0); PG8_MMA(1, 0, At, B0); PG8_BAR; PG8_SCHED;
;       PG8_STAGE(PG8_SB(1, 1), b3 + hstep, voffB);
;       PG8_WAIT_V(6); PG8_BAR; PG8_MMA(1, 1, At, B1); PG8_BAR;
;     }
;     E(acc, cur, wr, wc, fr, fq);
;   DI void operator()(const f32x4 (&acc)[2][2][4][2], const pg8::Unit& u, int wr, int wc, int fr_, int fq_) const {
;     ...
;             } else if (EPI == EPI_UKV) {
;               if (n == 0) {
;                 const int gb = u.pn * 256 + bj * 128 + wc * 32;
;                 const int hd = gb >> 7, within = (gb & 127) + 8 * fq;
;                 const f32x4 v1 = acc[ai][bj][m][1];
;                 if (within < 64) st_bf8((u16*)(big + E_KNOPE) + (size_t)token * 512 + hd * 64 + within, v, v1, rinv);
;                 else st_bf8((u16*)(big + E_VMLAT) + (size_t)token * 512 + hd * 64 + (within - 64), v, v1, rinv);
;               }
	s_waitcnt lgkmcnt(0)
	v_mfma_f32_16x16x32_bf16 v[60:63], v[136:139], v[158:161], v[60:63]
	v_mfma_f32_16x16x32_bf16 v[56:59], v[150:153], v[158:161], v[56:59]
	v_mfma_f32_16x16x32_bf16 v[44:47], v[136:139], v[166:169], v[44:47]
	v_mfma_f32_16x16x32_bf16 v[40:43], v[150:153], v[166:169], v[40:43]
	v_mfma_f32_16x16x32_bf16 v[28:31], v[136:139], v[174:177], v[28:31]
	v_mfma_f32_16x16x32_bf16 v[24:27], v[150:153], v[174:177], v[24:27]
	v_mfma_f32_16x16x32_bf16 v[12:15], v[136:139], v[196:199], v[12:15]
	v_mfma_f32_16x16x32_bf16 v[8:11], v[150:153], v[196:199], v[8:11]
	v_mfma_f32_16x16x32_bf16 v[60:63], v[146:149], v[162:165], v[60:63]
	v_mfma_f32_16x16x32_bf16 v[56:59], v[154:157], v[162:165], v[56:59]
	v_mfma_f32_16x16x32_bf16 v[44:47], v[146:149], v[170:173], v[44:47]
	v_mfma_f32_16x16x32_bf16 v[40:43], v[154:157], v[170:173], v[40:43]
	v_mfma_f32_16x16x32_bf16 v[28:31], v[146:149], v[178:181], v[28:31]
	v_mfma_f32_16x16x32_bf16 v[24:27], v[154:157], v[178:181], v[24:27]
	v_mfma_f32_16x16x32_bf16 v[12:15], v[146:149], v[200:203], v[12:15]
	v_mfma_f32_16x16x32_bf16 v[8:11], v[154:157], v[200:203], v[8:11]
	s_waitcnt vmcnt(8)
	s_barrier
	s_mov_b32 m0, s71
	s_nop 0
	global_load_lds_dwordx4 v130, s[36:37]
	s_mov_b32 m0, s70
	s_nop 0
	global_load_lds_dwordx4 v134, s[36:37]
	s_waitcnt vmcnt(6)
	s_barrier
	ds_read_b128 v[136:139], v220
	ds_read_b128 v[146:149], v220 offset:1024
	ds_read_b128 v[150:153], v220 offset:2048
	ds_read_b128 v[154:157], v220 offset:3072
	v_mfma_f32_16x16x32_bf16 v[52:55], v[204:207], v[158:161], v[52:55]
	v_mfma_f32_16x16x32_bf16 v[48:51], v[212:215], v[158:161], v[48:51]
	v_mfma_f32_16x16x32_bf16 v[36:39], v[204:207], v[166:169], v[36:39]
	v_mfma_f32_16x16x32_bf16 v[32:35], v[212:215], v[166:169], v[32:35]
	v_mfma_f32_16x16x32_bf16 v[20:23], v[204:207], v[174:177], v[20:23]
	v_mfma_f32_16x16x32_bf16 v[16:19], v[212:215], v[174:177], v[16:19]
	v_mfma_f32_16x16x32_bf16 v[4:7], v[204:207], v[196:199], v[4:7]
	v_mfma_f32_16x16x32_bf16 v[0:3], v[212:215], v[196:199], v[0:3]
	v_mfma_f32_16x16x32_bf16 v[52:55], v[208:211], v[162:165], v[52:55]
	v_mfma_f32_16x16x32_bf16 v[48:51], v[216:219], v[162:165], v[48:51]
	v_mfma_f32_16x16x32_bf16 v[36:39], v[208:211], v[170:173], v[36:39]
	v_mfma_f32_16x16x32_bf16 v[32:35], v[216:219], v[170:173], v[32:35]
	v_mfma_f32_16x16x32_bf16 v[20:23], v[208:211], v[178:181], v[20:23]
	v_mfma_f32_16x16x32_bf16 v[16:19], v[216:219], v[178:181], v[16:19]
	v_mfma_f32_16x16x32_bf16 v[4:7], v[208:211], v[200:203], v[4:7]
	v_mfma_f32_16x16x32_bf16 v[0:3], v[216:219], v[200:203], v[0:3]
	s_andn2_b64 vcc, exec, s[34:35]
	s_mov_b64 s[36:37], -1
	s_mov_b64 s[34:35], 0
	s_mov_b64 s[40:41], 0x100
	s_barrier
	s_cbranch_vccz .LBB0_1346
	s_waitcnt lgkmcnt(0)
	v_mov_b32_e32 v136, v182
	s_lshl_b32 s3, s3, 10
	s_add_i32 s3, s3, 0
	v_and_or_b32 v147, v136, 15, s60
	v_lshl_add_u32 v137, v147, 2, s3
	v_add_u32_e32 v146, 0x20000, v137
	ds_read_b32 v138, v146
	s_lshl_b32 s13, s20, 8
	v_lshrrev_b32_e32 v136, 1, v136
	v_and_or_b32 v139, v136, 24, s61
	v_add_u32_e32 v136, s13, v147
	v_ashrrev_i32_e32 v137, 31, v136
	s_waitcnt lgkmcnt(0)
	v_pk_mul_f32 v[124:125], v[124:125], v[138:139] op_sel_hi:[1,0]
	v_pk_mul_f32 v[126:127], v[126:127], v[138:139] op_sel_hi:[1,0]
	v_pk_mul_f32 v[120:121], v[120:121], v[138:139] op_sel_hi:[1,0]
	v_lshlrev_b64 v[140:141], 10, v[136:137]
	s_lshl_b32 s20, s2, 7
	v_cvt_pk_bf16_f32 v124, v124, v125
	v_cvt_pk_bf16_f32 v125, v126, v127
	v_cvt_pk_bf16_f32 v126, v120, v121
	v_pk_mul_f32 v[120:121], v[122:123], v[138:139] op_sel_hi:[1,0]
	s_ashr_i32 s21, s20, 31
	v_cvt_pk_bf16_f32 v127, v120, v121
	v_lshl_add_u64 v[120:121], s[6:7], 0, v[140:141]
	s_mov_b64 s[2:3], -1
	s_and_b64 vcc, exec, s[4:5]
	v_lshl_add_u64 v[120:121], s[20:21], 1, v[120:121]
	v_lshlrev_b32_e32 v144, 1, v139
	s_cbranch_vccz .LBB0_1349
	v_lshl_add_u64 v[122:123], v[120:121], 0, v[144:145]
	v_add_co_u32_e32 v122, vcc, 0xd9ff000, v122
	s_mov_b64 s[2:3], 0
	s_nop 0
	v_addc_co_u32_e32 v123, vcc, 0, v123, vcc
	global_store_dwordx4 v[122:123], v[124:127], off offset:3968

; #define PG8_STAGE(bufoff, gbase, voff) do { _Pragma("unroll") for (int _i = 0; _i < 2; ++_i) \
;     __builtin_amdgcn_global_load_lds((const unsigned*)((const char*)(gbase) + (voff)[_i]), (LAS unsigned*)(lds + (bufoff) + ldsw + _i * 8192), 16, 0, 0); } while (0)
; #define PG8_LDA(dst, b, h) do { _Pragma("unroll") for (int m = 0; m < 4; ++m) _Pragma("unroll") for (int k = 0; k < 2; ++k) dst[m][k] = *(const LAS bf16x8*)(lds + PG8_SA(b, h) + aoff + m * 2048 + k * 1024); } while (0)
; #define PG8_LDB(dst, b, h) do { _Pragma("unroll") for (int n = 0; n < 2; ++n) _Pragma("unroll") for (int k = 0; k < 2; ++k) dst[n][k] = *(const LAS bf16x8*)(lds + PG8_SB(b, h) + boff + n * 2048 + k * 1024); } while (0)
; #define PG8_MMA(ai, bj, At, Bt) do { __builtin_amdgcn_s_setprio(1); _Pragma("unroll") for (int m = 0; m < 4; ++m) _Pragma("unroll") for (int n = 0; n < 2; ++n) _Pragma("unroll") for (int k = 0; k < 2; ++k) \
;     acc[ai][bj][m][n] = __builtin_amdgcn_mfma_f32_16x16x32_bf16(Bt[n][k], At[m][k], acc[ai][bj][m][n], 0, 0, 0); __builtin_amdgcn_s_setprio(0); } while (0)
; #define PG8_WAIT_L(n) asm volatile("s_waitcnt lgkmcnt(" #n ")" ::: "memory")
; #define PG8_BAR __builtin_amdgcn_s_barrier()
; #define PG8_SCHED __builtin_amdgcn_sched_barrier(0)
; template <class Epi, class Sched>
; DI void gemm_phase(LAS unsigned char* lds, const Gemm g, const Sched& S, const Epi& E) {
;     ...
;     for (int t = 0; t < nt; t += 2) {
;       const bool last = (t == nt - 2);
;       const char* a1 = cA + (size_t)(t + 1) * kstep;
;       const char* a2 = last ? nA : cA + (size_t)(t + 2) * kstep; const char* b2 = last ? nB : cB + (size_t)(t + 2) * kstep;
;       const char* a3 = a2 + kstep; const char* b3 = b2 + kstep;
;       PG8_LDB(B0, 0, 0); PG8_SCHED; PG8_LDA(At, 0, 0); PG8_STAGE(PG8_SA(1, 1), a1 + hstep, voffA);
;       PG8_WAIT_L(8); PG8_BAR; PG8_WAIT_L(0); PG8_MMA(0, 0, At, B0); PG8_BAR; PG8_SCHED;
;       PG8_LDB(B1, 0, 1); PG8_STAGE(PG8_SB(0, 0), b2, voffB);
;       PG8_BAR; PG8_WAIT_L(0); PG8_MMA(0, 1, At, B1); PG8_BAR;
;     ...
; #pragma unroll
;     for (int a = 0; a < 2; ++a)
; #pragma unroll
;       for (int b = 0; b < 2; ++b)
; #pragma unroll
;         for (int m = 0; m < 4; ++m)
; #pragma unroll
;           for (int n = 0; n < 2; ++n) acc[a][b][m][n] = (f32x4){0.f, 0.f, 0.f, 0.f};
;     cur = nxt; cA = nA; cB = nB; ++ui;
.LBB0_1643:
	v_mov_b64_e32 v[0:1], s[30:31]
	s_ashr_i32 s19, s18, 31
	v_cmp_lt_i64_e32 vcc, s[20:21], v[0:1]
	s_lshl_b64 s[20:21], s[18:19], 19
	s_add_u32 s20, s36, s20
	s_addc_u32 s21, s37, s21
	s_and_b64 s[22:23], vcc, exec
	s_cselect_b32 s19, s21, s3
	s_cselect_b32 s35, s20, s2
	s_ashr_i32 s17, s16, 31
	s_lshl_b64 s[22:23], s[16:17], 19
	s_add_u32 s22, s38, s22
	s_addc_u32 s23, s39, s23
	s_and_b64 s[28:29], vcc, exec
	s_cselect_b32 s17, s23, s5
	s_cselect_b32 s51, s22, s4
	s_add_u32 s2, s2, 0x40080
	s_addc_u32 s3, s3, 0
	s_add_u32 s52, s4, 0x100
	v_mov_b32_e32 v0, 0
	s_addc_u32 s53, s5, 0
	s_mov_b32 s54, -2
	v_mov_b32_e32 v1, v0
	v_mov_b64_e32 v[2:3], v[0:1]
	v_mov_b64_e32 v[4:5], v[0:1]
	v_mov_b64_e32 v[6:7], v[0:1]
	v_mov_b64_e32 v[8:9], v[0:1]
	v_mov_b64_e32 v[10:11], v[0:1]
	v_mov_b64_e32 v[12:13], v[0:1]
	v_mov_b64_e32 v[14:15], v[0:1]
	v_mov_b64_e32 v[16:17], v[0:1]
	v_mov_b64_e32 v[18:19], v[0:1]
	v_mov_b64_e32 v[20:21], v[0:1]
	v_mov_b64_e32 v[22:23], v[0:1]
	v_mov_b64_e32 v[24:25], v[0:1]
	v_mov_b64_e32 v[26:27], v[0:1]
	v_mov_b64_e32 v[28:29], v[0:1]
	v_mov_b64_e32 v[30:31], v[0:1]
	v_mov_b64_e32 v[32:33], v[0:1]
	v_mov_b64_e32 v[34:35], v[0:1]
	v_mov_b64_e32 v[36:37], v[0:1]
	v_mov_b64_e32 v[38:39], v[0:1]
	v_mov_b64_e32 v[40:41], v[0:1]
	v_mov_b64_e32 v[42:43], v[0:1]
	v_mov_b64_e32 v[44:45], v[0:1]
	v_mov_b64_e32 v[46:47], v[0:1]
	v_mov_b64_e32 v[48:49], v[0:1]
	v_mov_b64_e32 v[50:51], v[0:1]
	v_mov_b64_e32 v[52:53], v[0:1]
	v_mov_b64_e32 v[54:55], v[0:1]
	v_mov_b64_e32 v[56:57], v[0:1]
	v_mov_b64_e32 v[58:59], v[0:1]
	v_mov_b64_e32 v[60:61], v[0:1]
	v_mov_b64_e32 v[62:63], v[0:1]
	v_mov_b64_e32 v[64:65], v[0:1]
	v_mov_b64_e32 v[66:67], v[0:1]
	v_mov_b64_e32 v[68:69], v[0:1]
	v_mov_b64_e32 v[70:71], v[0:1]
	v_mov_b64_e32 v[72:73], v[0:1]
	v_mov_b64_e32 v[74:75], v[0:1]
	v_mov_b64_e32 v[76:77], v[0:1]
	v_mov_b64_e32 v[78:79], v[0:1]
	v_mov_b64_e32 v[80:81], v[0:1]
	v_mov_b64_e32 v[82:83], v[0:1]
	v_mov_b64_e32 v[84:85], v[0:1]
	v_mov_b64_e32 v[86:87], v[0:1]
	v_mov_b64_e32 v[88:89], v[0:1]
	v_mov_b64_e32 v[90:91], v[0:1]
	v_mov_b64_e32 v[92:93], v[0:1]
	v_mov_b64_e32 v[94:95], v[0:1]
	v_mov_b64_e32 v[96:97], v[0:1]
	v_mov_b64_e32 v[98:99], v[0:1]
	v_mov_b64_e32 v[100:101], v[0:1]
	v_mov_b64_e32 v[102:103], v[0:1]
	v_mov_b64_e32 v[104:105], v[0:1]
	v_mov_b64_e32 v[106:107], v[0:1]
	v_mov_b64_e32 v[108:109], v[0:1]
	v_mov_b64_e32 v[110:111], v[0:1]
	v_mov_b64_e32 v[112:113], v[0:1]
	v_mov_b64_e32 v[114:115], v[0:1]
	v_mov_b64_e32 v[116:117], v[0:1]
	v_mov_b64_e32 v[118:119], v[0:1]
	v_mov_b64_e32 v[120:121], v[0:1]
	v_mov_b64_e32 v[122:123], v[0:1]
	v_mov_b64_e32 v[124:125], v[0:1]
	v_mov_b64_e32 v[126:127], v[0:1]
	v_add_u32_e32 v224, 0x10000, v158
	v_add_u32_e32 v225, 0x14000, v158
	v_add_u32_e32 v226, 0x18000, v158
	v_add_u32_e32 v227, 0x1c000, v158
	ds_read_b128 v[128:131], v224
	ds_read_b128 v[132:135], v224 offset:1024
	ds_read_b128 v[148:151], v224 offset:2048
	ds_read_b128 v[152:155], v224 offset:3072
.LBB0_1644:
	s_add_u32 s4, s2, 0xfffc0080
	s_addc_u32 s5, s3, -1
	s_add_i32 s55, 0, 0x10000
	s_cmp_eq_u32 s54, 12
	s_cselect_b32 s29, s19, s5
	s_cselect_b32 s28, s35, s4
	s_cselect_b32 s5, s17, s53
	s_cselect_b32 s4, s51, s52
	s_add_i32 m0, s41, 0xc000
	ds_read_b128 v[160:163], v159
	ds_read_b128 v[164:167], v159 offset:1024
	ds_read_b128 v[168:171], v159 offset:2048
	ds_read_b128 v[172:175], v159 offset:3072
	ds_read_b128 v[176:179], v159 offset:4096
	ds_read_b128 v[196:199], v159 offset:5120
	ds_read_b128 v[200:203], v159 offset:6144
	ds_read_b128 v[204:207], v159 offset:7168
	global_load_lds_dwordx4 v142, s[2:3]
	s_add_i32 m0, s41, 0xe000
	s_nop 0
	global_load_lds_dwordx4 v146, s[2:3]
	s_waitcnt lgkmcnt(8)
	s_barrier
	s_waitcnt lgkmcnt(0)
	v_mfma_f32_16x16x32_bf16 v[124:127], v[128:131], v[160:163], v[124:127]
	v_mfma_f32_16x16x32_bf16 v[120:123], v[148:151], v[160:163], v[120:123]
	v_mfma_f32_16x16x32_bf16 v[108:111], v[128:131], v[168:171], v[108:111]
	v_mfma_f32_16x16x32_bf16 v[104:107], v[148:151], v[168:171], v[104:107]
	v_mfma_f32_16x16x32_bf16 v[92:95], v[128:131], v[176:179], v[92:95]
	v_mfma_f32_16x16x32_bf16 v[88:91], v[148:151], v[176:179], v[88:91]
	v_mfma_f32_16x16x32_bf16 v[76:79], v[128:131], v[200:203], v[76:79]
	v_mfma_f32_16x16x32_bf16 v[72:75], v[148:151], v[200:203], v[72:75]
	v_mfma_f32_16x16x32_bf16 v[124:127], v[132:135], v[164:167], v[124:127]
	v_mfma_f32_16x16x32_bf16 v[120:123], v[152:155], v[164:167], v[120:123]
	v_mfma_f32_16x16x32_bf16 v[108:111], v[132:135], v[172:175], v[108:111]
	v_mfma_f32_16x16x32_bf16 v[104:107], v[152:155], v[172:175], v[104:107]
	v_mfma_f32_16x16x32_bf16 v[92:95], v[132:135], v[196:199], v[92:95]
	v_mfma_f32_16x16x32_bf16 v[88:91], v[152:155], v[196:199], v[88:91]
	v_mfma_f32_16x16x32_bf16 v[76:79], v[132:135], v[204:207], v[76:79]
	v_mfma_f32_16x16x32_bf16 v[72:75], v[152:155], v[204:207], v[72:75]
	s_barrier
	s_add_i32 s58, 0, 0x14000
	s_add_i32 s55, s55, s40
	ds_read_b128 v[208:211], v225
	ds_read_b128 v[212:215], v225 offset:1024
	ds_read_b128 v[216:219], v225 offset:2048
	ds_read_b128 v[220:223], v225 offset:3072
	s_add_u32 vcc_lo, s4, s0
	s_addc_u32 vcc_hi, s5, s1
	s_mov_b32 m0, s55
	s_nop 0
	global_load_lds_dwordx4 v144, s[4:5]
	s_add_i32 m0, s55, 0x2000
	s_nop 0
	global_load_lds_dwordx4 v136, s[4:5]
	s_barrier
; #define PG8_STAGE(bufoff, gbase, voff) do { _Pragma("unroll") for (int _i = 0; _i < 2; ++_i) \
;     __builtin_amdgcn_global_load_lds((const unsigned*)((const char*)(gbase) + (voff)[_i]), (LAS unsigned*)(lds + (bufoff) + ldsw + _i * 8192), 16, 0, 0); } while (0)
; #define PG8_LDA(dst, b, h) do { _Pragma("unroll") for (int m = 0; m < 4; ++m) _Pragma("unroll") for (int k = 0; k < 2; ++k) dst[m][k] = *(const LAS bf16x8*)(lds + PG8_SA(b, h) + aoff + m * 2048 + k * 1024); } while (0)
; #define PG8_LDB(dst, b, h) do { _Pragma("unroll") for (int n = 0; n < 2; ++n) _Pragma("unroll") for (int k = 0; k < 2; ++k) dst[n][k] = *(const LAS bf16x8*)(lds + PG8_SB(b, h) + boff + n * 2048 + k * 1024); } while (0)
; #define PG8_MMA(ai, bj, At, Bt) do { __builtin_amdgcn_s_setprio(1); _Pragma("unroll") for (int m = 0; m < 4; ++m) _Pragma("unroll") for (int n = 0; n < 2; ++n) _Pragma("unroll") for (int k = 0; k < 2; ++k) \
;     acc[ai][bj][m][n] = __builtin_amdgcn_mfma_f32_16x16x32_bf16(Bt[n][k], At[m][k], acc[ai][bj][m][n], 0, 0, 0); __builtin_amdgcn_s_setprio(0); } while (0)
; #define PG8_WAIT_V(n) asm volatile("s_waitcnt vmcnt(" #n ")" ::: "memory")
; #define PG8_WAIT_L(n) asm volatile("s_waitcnt lgkmcnt(" #n ")" ::: "memory")
; #define PG8_BAR __builtin_amdgcn_s_barrier()
; #define PG8_SCHED __builtin_amdgcn_sched_barrier(0)
; template <class Epi, class Sched>
; DI void gemm_phase(LAS unsigned char* lds, const Gemm g, const Sched& S, const Epi& E) {
;     ...
;       PG8_LDB(B1, 0, 1); PG8_STAGE(PG8_SB(0, 0), b2, voffB);
;       PG8_BAR; PG8_WAIT_L(0); PG8_MMA(0, 1, At, B1); PG8_BAR;
;       PG8_LDA(At, 0, 1); PG8_STAGE(PG8_SA(0, 0), a2, voffA);
;       PG8_BAR; PG8_WAIT_L(0); PG8_MMA(1, 0, At, B0); PG8_BAR; PG8_SCHED;
;       PG8_STAGE(PG8_SB(0, 1), b2 + hstep, voffB);
;       PG8_WAIT_V(6); PG8_BAR; PG8_MMA(1, 1, At, B1); PG8_BAR;
;       PG8_LDB(B0, 1, 0); PG8_SCHED; PG8_LDA(At, 1, 0); PG8_STAGE(PG8_SA(0, 1), a2 + hstep, voffA);
;       PG8_WAIT_L(8); PG8_BAR; PG8_WAIT_L(0); PG8_MMA(0, 0, At, B0); PG8_BAR; PG8_SCHED;
	s_waitcnt lgkmcnt(0)
	v_mfma_f32_16x16x32_bf16 v[116:119], v[208:211], v[160:163], v[116:119]
	v_mfma_f32_16x16x32_bf16 v[112:115], v[216:219], v[160:163], v[112:115]
	v_mfma_f32_16x16x32_bf16 v[100:103], v[208:211], v[168:171], v[100:103]
	v_mfma_f32_16x16x32_bf16 v[96:99], v[216:219], v[168:171], v[96:99]
	v_mfma_f32_16x16x32_bf16 v[84:87], v[208:211], v[176:179], v[84:87]
	v_mfma_f32_16x16x32_bf16 v[80:83], v[216:219], v[176:179], v[80:83]
	v_mfma_f32_16x16x32_bf16 v[68:71], v[208:211], v[200:203], v[68:71]
	v_mfma_f32_16x16x32_bf16 v[64:67], v[216:219], v[200:203], v[64:67]
	v_mfma_f32_16x16x32_bf16 v[116:119], v[212:215], v[164:167], v[116:119]
	v_mfma_f32_16x16x32_bf16 v[112:115], v[220:223], v[164:167], v[112:115]
	v_mfma_f32_16x16x32_bf16 v[100:103], v[212:215], v[172:175], v[100:103]
	v_mfma_f32_16x16x32_bf16 v[96:99], v[220:223], v[172:175], v[96:99]
	v_mfma_f32_16x16x32_bf16 v[84:87], v[212:215], v[196:199], v[84:87]
	v_mfma_f32_16x16x32_bf16 v[80:83], v[220:223], v[196:199], v[80:83]
	v_mfma_f32_16x16x32_bf16 v[68:71], v[212:215], v[204:207], v[68:71]
	v_mfma_f32_16x16x32_bf16 v[64:67], v[220:223], v[204:207], v[64:67]
	s_mov_b32 m0, s41
	s_add_u32 s100, s28, s0
	s_addc_u32 s101, s29, s1
	s_barrier
	ds_read_b128 v[160:163], v159 offset:16384
	ds_read_b128 v[164:167], v159 offset:17408
	ds_read_b128 v[168:171], v159 offset:18432
	ds_read_b128 v[172:175], v159 offset:19456
	ds_read_b128 v[176:179], v159 offset:20480
	ds_read_b128 v[196:199], v159 offset:21504
	ds_read_b128 v[200:203], v159 offset:22528
	ds_read_b128 v[204:207], v159 offset:23552
	global_load_lds_dwordx4 v140, s[28:29]
	s_mov_b32 m0, s42
	s_nop 0
	global_load_lds_dwordx4 v138, s[28:29]
	s_barrier
	s_waitcnt lgkmcnt(0)
	v_mfma_f32_16x16x32_bf16 v[60:63], v[128:131], v[160:163], v[60:63]
	v_mfma_f32_16x16x32_bf16 v[56:59], v[148:151], v[160:163], v[56:59]
	v_mfma_f32_16x16x32_bf16 v[44:47], v[128:131], v[168:171], v[44:47]
	v_mfma_f32_16x16x32_bf16 v[40:43], v[148:151], v[168:171], v[40:43]
	v_mfma_f32_16x16x32_bf16 v[28:31], v[128:131], v[176:179], v[28:31]
	v_mfma_f32_16x16x32_bf16 v[24:27], v[148:151], v[176:179], v[24:27]
	v_mfma_f32_16x16x32_bf16 v[12:15], v[128:131], v[200:203], v[12:15]
	v_mfma_f32_16x16x32_bf16 v[8:11], v[148:151], v[200:203], v[8:11]
	v_mfma_f32_16x16x32_bf16 v[60:63], v[132:135], v[164:167], v[60:63]
	v_mfma_f32_16x16x32_bf16 v[56:59], v[152:155], v[164:167], v[56:59]
	v_mfma_f32_16x16x32_bf16 v[44:47], v[132:135], v[172:175], v[44:47]
	v_mfma_f32_16x16x32_bf16 v[40:43], v[152:155], v[172:175], v[40:43]
	v_mfma_f32_16x16x32_bf16 v[28:31], v[132:135], v[196:199], v[28:31]
	v_mfma_f32_16x16x32_bf16 v[24:27], v[152:155], v[196:199], v[24:27]
	v_mfma_f32_16x16x32_bf16 v[12:15], v[132:135], v[204:207], v[12:15]
	v_mfma_f32_16x16x32_bf16 v[8:11], v[152:155], v[204:207], v[8:11]
	s_waitcnt vmcnt(8)
	s_barrier
	s_add_u32 s56, s4, 0x40000
	s_addc_u32 s57, s5, 0
	s_add_i32 s55, s58, s40
	s_mov_b32 m0, s55
	s_nop 0
	global_load_lds_dwordx4 v144, s[56:57]
	s_add_i32 m0, s55, 0x2000
	s_nop 0
	global_load_lds_dwordx4 v136, s[56:57]
	s_waitcnt vmcnt(6)
	s_barrier
	ds_read_b128 v[128:131], v226
	ds_read_b128 v[132:135], v226 offset:1024
	ds_read_b128 v[148:151], v226 offset:2048
	ds_read_b128 v[152:155], v226 offset:3072
	v_mfma_f32_16x16x32_bf16 v[52:55], v[208:211], v[160:163], v[52:55]
	v_mfma_f32_16x16x32_bf16 v[48:51], v[216:219], v[160:163], v[48:51]
	v_mfma_f32_16x16x32_bf16 v[36:39], v[208:211], v[168:171], v[36:39]
	v_mfma_f32_16x16x32_bf16 v[32:35], v[216:219], v[168:171], v[32:35]
	v_mfma_f32_16x16x32_bf16 v[20:23], v[208:211], v[176:179], v[20:23]
	v_mfma_f32_16x16x32_bf16 v[16:19], v[216:219], v[176:179], v[16:19]
	v_mfma_f32_16x16x32_bf16 v[4:7], v[208:211], v[200:203], v[4:7]
	v_mfma_f32_16x16x32_bf16 v[0:3], v[216:219], v[200:203], v[0:3]
	v_mfma_f32_16x16x32_bf16 v[52:55], v[212:215], v[164:167], v[52:55]
	v_mfma_f32_16x16x32_bf16 v[48:51], v[220:223], v[164:167], v[48:51]
	v_mfma_f32_16x16x32_bf16 v[36:39], v[212:215], v[172:175], v[36:39]
	v_mfma_f32_16x16x32_bf16 v[32:35], v[220:223], v[172:175], v[32:35]
	v_mfma_f32_16x16x32_bf16 v[20:23], v[212:215], v[196:199], v[20:23]
	v_mfma_f32_16x16x32_bf16 v[16:19], v[220:223], v[196:199], v[16:19]
	v_mfma_f32_16x16x32_bf16 v[4:7], v[212:215], v[204:207], v[4:7]
	v_mfma_f32_16x16x32_bf16 v[0:3], v[220:223], v[204:207], v[0:3]
	s_add_i32 s55, 0, 0x18000
	s_barrier
	s_add_u32 s28, s28, 0x40000
	s_addc_u32 s29, s29, 0
	s_mov_b32 m0, s43
	ds_read_b128 v[160:163], v159 offset:32768
	ds_read_b128 v[164:167], v159 offset:33792
	ds_read_b128 v[168:171], v159 offset:34816
	ds_read_b128 v[172:175], v159 offset:35840
	ds_read_b128 v[176:179], v159 offset:36864
	ds_read_b128 v[196:199], v159 offset:37888
	ds_read_b128 v[200:203], v159 offset:38912
	ds_read_b128 v[204:207], v159 offset:39936
	global_load_lds_dwordx4 v140, s[28:29]
	s_mov_b32 m0, s44
	s_nop 0
	global_load_lds_dwordx4 v138, s[28:29]
	s_waitcnt lgkmcnt(8)
	s_barrier
	s_waitcnt lgkmcnt(0)
	v_mfma_f32_16x16x32_bf16 v[124:127], v[128:131], v[160:163], v[124:127]
	v_mfma_f32_16x16x32_bf16 v[120:123], v[148:151], v[160:163], v[120:123]
	v_mfma_f32_16x16x32_bf16 v[108:111], v[128:131], v[168:171], v[108:111]
	v_mfma_f32_16x16x32_bf16 v[104:107], v[148:151], v[168:171], v[104:107]
	v_mfma_f32_16x16x32_bf16 v[92:95], v[128:131], v[176:179], v[92:95]
	v_mfma_f32_16x16x32_bf16 v[88:91], v[148:151], v[176:179], v[88:91]
	v_mfma_f32_16x16x32_bf16 v[76:79], v[128:131], v[200:203], v[76:79]
	v_mfma_f32_16x16x32_bf16 v[72:75], v[148:151], v[200:203], v[72:75]
	v_mfma_f32_16x16x32_bf16 v[124:127], v[132:135], v[164:167], v[124:127]
	v_mfma_f32_16x16x32_bf16 v[120:123], v[152:155], v[164:167], v[120:123]
	v_mfma_f32_16x16x32_bf16 v[108:111], v[132:135], v[172:175], v[108:111]
	v_mfma_f32_16x16x32_bf16 v[104:107], v[152:155], v[172:175], v[104:107]
	v_mfma_f32_16x16x32_bf16 v[92:95], v[132:135], v[196:199], v[92:95]
	v_mfma_f32_16x16x32_bf16 v[88:91], v[152:155], v[196:199], v[88:91]
	v_mfma_f32_16x16x32_bf16 v[76:79], v[132:135], v[204:207], v[76:79]
	v_mfma_f32_16x16x32_bf16 v[72:75], v[152:155], v[204:207], v[72:75]
	s_barrier
; DI float bf2f(unsigned v) { return __uint_as_float(v << 16); }
; #define PG8_STAGE(bufoff, gbase, voff) do { _Pragma("unroll") for (int _i = 0; _i < 2; ++_i) \
;     __builtin_amdgcn_global_load_lds((const unsigned*)((const char*)(gbase) + (voff)[_i]), (LAS unsigned*)(lds + (bufoff) + ldsw + _i * 8192), 16, 0, 0); } while (0)
; #define PG8_LDA(dst, b, h) do { _Pragma("unroll") for (int m = 0; m < 4; ++m) _Pragma("unroll") for (int k = 0; k < 2; ++k) dst[m][k] = *(const LAS bf16x8*)(lds + PG8_SA(b, h) + aoff + m * 2048 + k * 1024); } while (0)
; #define PG8_WAIT_V(n) asm volatile("s_waitcnt vmcnt(" #n ")" ::: "memory")
; #define PG8_WAIT_L(n) asm volatile("s_waitcnt lgkmcnt(" #n ")" ::: "memory")
; #define PG8_BAR __builtin_amdgcn_s_barrier()
; template <class Epi, class Sched>
; DI void gemm_phase(LAS unsigned char* lds, const Gemm g, const Sched& S, const Epi& E) {
;     ...
;       PG8_WAIT_V(6); PG8_BAR; PG8_MMA(1, 1, At, B1); PG8_BAR;
;       PG8_LDB(B0, 1, 0); PG8_SCHED; PG8_LDA(At, 1, 0); PG8_STAGE(PG8_SA(0, 1), a2 + hstep, voffA);
;       PG8_WAIT_L(8); PG8_BAR; PG8_WAIT_L(0); PG8_MMA(0, 0, At, B0); PG8_BAR; PG8_SCHED;
;       PG8_LDB(B1, 1, 1); PG8_STAGE(PG8_SB(1, 0), b3, voffB);
;       PG8_BAR; PG8_WAIT_L(0); PG8_MMA(0, 1, At, B1); PG8_BAR;
;       PG8_LDA(At, 1, 1); PG8_STAGE(PG8_SA(1, 0), a3, voffA);
;       PG8_BAR; PG8_WAIT_L(0); PG8_MMA(1, 0, At, B0); PG8_BAR; PG8_SCHED;
;       PG8_STAGE(PG8_SB(1, 1), b3 + hstep, voffB);
;       PG8_WAIT_V(6); PG8_BAR; PG8_MMA(1, 1, At, B1); PG8_BAR;
;   DI void operator()(const f32x4 (&acc)[2][2][4][2], const pg8::Unit& u, int wr, int wc, int fr_, int fq_) const {
;     ...
;             } else if (EPI == EPI_RESID) {
;               if (n == 0) {
;                 const int f8 = u.pn * 256 + bj * 128 + wc * 32 + 8 * fq;
;                 const f32x4 v1 = acc[ai][bj][m][1];
;                 f32x4 r0, r1;
;                 if (rsrc) {
;                   r0 = *(const f32x4*)(rsrc + (size_t)token * 1024 + f8); r1 = *(const f32x4*)(rsrc + (size_t)token * 1024 + f8 + 4);
;                 } else {
;                   const u32x4 xu = *(const u32x4*)(xr + (size_t)token * 1024 + f8);
;                   r0 = (f32x4){bf2f(xu.x & 0xffffu), bf2f(xu.x >> 16), bf2f(xu.y & 0xffffu), bf2f(xu.y >> 16)};
;                   r1 = (f32x4){bf2f(xu.z & 0xffffu), bf2f(xu.z >> 16), bf2f(xu.w & 0xffffu), bf2f(xu.w >> 16)};
;                 }
	s_add_i32 s28, 0, 0x1c000
	s_add_i32 s29, s55, s40
	s_mov_b32 m0, s29
	ds_read_b128 v[208:211], v227
	ds_read_b128 v[212:215], v227 offset:1024
	ds_read_b128 v[216:219], v227 offset:2048
	ds_read_b128 v[220:223], v227 offset:3072
	global_load_lds_dwordx4 v144, vcc
	s_add_i32 m0, s29, 0x2000
	s_nop 0
	global_load_lds_dwordx4 v136, vcc
	s_barrier
	s_waitcnt lgkmcnt(0)
	v_mfma_f32_16x16x32_bf16 v[116:119], v[208:211], v[160:163], v[116:119]
	v_mfma_f32_16x16x32_bf16 v[112:115], v[216:219], v[160:163], v[112:115]
	v_mfma_f32_16x16x32_bf16 v[100:103], v[208:211], v[168:171], v[100:103]
	v_mfma_f32_16x16x32_bf16 v[96:99], v[216:219], v[168:171], v[96:99]
	v_mfma_f32_16x16x32_bf16 v[84:87], v[208:211], v[176:179], v[84:87]
	v_mfma_f32_16x16x32_bf16 v[80:83], v[216:219], v[176:179], v[80:83]
	v_mfma_f32_16x16x32_bf16 v[68:71], v[208:211], v[200:203], v[68:71]
	v_mfma_f32_16x16x32_bf16 v[64:67], v[216:219], v[200:203], v[64:67]
	v_mfma_f32_16x16x32_bf16 v[116:119], v[212:215], v[164:167], v[116:119]
	v_mfma_f32_16x16x32_bf16 v[112:115], v[220:223], v[164:167], v[112:115]
	v_mfma_f32_16x16x32_bf16 v[100:103], v[212:215], v[172:175], v[100:103]
	v_mfma_f32_16x16x32_bf16 v[96:99], v[220:223], v[172:175], v[96:99]
	v_mfma_f32_16x16x32_bf16 v[84:87], v[212:215], v[196:199], v[84:87]
	v_mfma_f32_16x16x32_bf16 v[80:83], v[220:223], v[196:199], v[80:83]
	v_mfma_f32_16x16x32_bf16 v[68:71], v[212:215], v[204:207], v[68:71]
	v_mfma_f32_16x16x32_bf16 v[64:67], v[220:223], v[204:207], v[64:67]
	s_mov_b32 m0, s49
	s_barrier
	ds_read_b128 v[160:163], v159 offset:49152
	ds_read_b128 v[164:167], v159 offset:50176
	ds_read_b128 v[168:171], v159 offset:51200
	ds_read_b128 v[172:175], v159 offset:52224
	ds_read_b128 v[176:179], v159 offset:53248
	ds_read_b128 v[196:199], v159 offset:54272
	ds_read_b128 v[200:203], v159 offset:55296
	ds_read_b128 v[204:207], v159 offset:56320
	global_load_lds_dwordx4 v140, s[100:101]
	s_mov_b32 m0, s50
	s_nop 0
	global_load_lds_dwordx4 v138, s[100:101]
	s_barrier
	s_waitcnt lgkmcnt(0)
	v_mfma_f32_16x16x32_bf16 v[60:63], v[128:131], v[160:163], v[60:63]
	v_mfma_f32_16x16x32_bf16 v[56:59], v[148:151], v[160:163], v[56:59]
	v_mfma_f32_16x16x32_bf16 v[44:47], v[128:131], v[168:171], v[44:47]
	v_mfma_f32_16x16x32_bf16 v[40:43], v[148:151], v[168:171], v[40:43]
	v_mfma_f32_16x16x32_bf16 v[28:31], v[128:131], v[176:179], v[28:31]
	v_mfma_f32_16x16x32_bf16 v[24:27], v[148:151], v[176:179], v[24:27]
	v_mfma_f32_16x16x32_bf16 v[12:15], v[128:131], v[200:203], v[12:15]
	v_mfma_f32_16x16x32_bf16 v[8:11], v[148:151], v[200:203], v[8:11]
	v_mfma_f32_16x16x32_bf16 v[60:63], v[132:135], v[164:167], v[60:63]
	v_mfma_f32_16x16x32_bf16 v[56:59], v[152:155], v[164:167], v[56:59]
	v_mfma_f32_16x16x32_bf16 v[44:47], v[132:135], v[172:175], v[44:47]
	v_mfma_f32_16x16x32_bf16 v[40:43], v[152:155], v[172:175], v[40:43]
	v_mfma_f32_16x16x32_bf16 v[28:31], v[132:135], v[196:199], v[28:31]
	v_mfma_f32_16x16x32_bf16 v[24:27], v[152:155], v[196:199], v[24:27]
	v_mfma_f32_16x16x32_bf16 v[12:15], v[132:135], v[204:207], v[12:15]
	v_mfma_f32_16x16x32_bf16 v[8:11], v[152:155], v[204:207], v[8:11]
	s_waitcnt vmcnt(8)
	s_barrier
	s_add_u32 s4, s4, 0x40080
	s_addc_u32 s5, s5, 0
	s_add_i32 s28, s28, s40
	s_mov_b32 m0, s28
	s_nop 0
	global_load_lds_dwordx4 v144, s[4:5]
	s_add_i32 m0, s28, 0x2000
	s_nop 0
	global_load_lds_dwordx4 v136, s[4:5]
	s_waitcnt vmcnt(6)
	s_barrier
	ds_read_b128 v[128:131], v224
	ds_read_b128 v[132:135], v224 offset:1024
	ds_read_b128 v[148:151], v224 offset:2048
	ds_read_b128 v[152:155], v224 offset:3072
	v_mfma_f32_16x16x32_bf16 v[52:55], v[208:211], v[160:163], v[52:55]
	v_mfma_f32_16x16x32_bf16 v[48:51], v[216:219], v[160:163], v[48:51]
	v_mfma_f32_16x16x32_bf16 v[36:39], v[208:211], v[168:171], v[36:39]
	v_mfma_f32_16x16x32_bf16 v[32:35], v[216:219], v[168:171], v[32:35]
	v_mfma_f32_16x16x32_bf16 v[20:23], v[208:211], v[176:179], v[20:23]
	v_mfma_f32_16x16x32_bf16 v[16:19], v[216:219], v[176:179], v[16:19]
	v_mfma_f32_16x16x32_bf16 v[4:7], v[208:211], v[200:203], v[4:7]
	v_mfma_f32_16x16x32_bf16 v[0:3], v[216:219], v[200:203], v[0:3]
	v_mfma_f32_16x16x32_bf16 v[52:55], v[212:215], v[164:167], v[52:55]
	v_mfma_f32_16x16x32_bf16 v[48:51], v[220:223], v[164:167], v[48:51]
	v_mfma_f32_16x16x32_bf16 v[36:39], v[212:215], v[172:175], v[36:39]
	v_mfma_f32_16x16x32_bf16 v[32:35], v[220:223], v[172:175], v[32:35]
	v_mfma_f32_16x16x32_bf16 v[20:23], v[212:215], v[196:199], v[20:23]
	v_mfma_f32_16x16x32_bf16 v[16:19], v[220:223], v[196:199], v[16:19]
	v_mfma_f32_16x16x32_bf16 v[4:7], v[212:215], v[204:207], v[4:7]
	v_mfma_f32_16x16x32_bf16 v[0:3], v[220:223], v[204:207], v[0:3]
	s_add_i32 s54, s54, 2
	s_add_u32 s2, s2, 0x100
	s_addc_u32 s3, s3, 0
	s_add_u32 s52, s52, 0x100
	s_addc_u32 s53, s53, 0
	s_cmp_gt_u32 s54, 13
	s_barrier
	s_cbranch_scc0 .LBB0_1644
	s_waitcnt lgkmcnt(0)
	s_lshl_b32 s2, s34, 8
	v_mov_b32_e32 v161, v182
	s_add_i32 s2, s2, s47
	v_cndmask_b32_e64 v130, 0, 1, s[14:15]
	v_and_or_b32 v150, v161, 15, s2
	s_lshl_b32 s2, s24, 8
	v_bfe_u32 v160, v161, 4, 2
	s_or_b32 s2, s2, s48
	v_ashrrev_i32_e32 v151, 31, v150
	v_lshl_or_b32 v148, v160, 3, s2
	v_lshlrev_b64 v[128:129], 12, v[150:151]
	v_ashrrev_i32_e32 v149, 31, v148
	v_lshl_add_u64 v[128:129], s[6:7], 0, v[128:129]
	v_cmp_ne_u32_e64 s[2:3], 1, v130
	s_andn2_b64 vcc, exec, s[14:15]
	v_lshl_add_u64 v[154:155], v[148:149], 2, v[128:129]
	s_cbranch_vccnz .LBB0_1647
	global_load_dwordx4 v[132:135], v[154:155], off offset:16
	global_load_dwordx4 v[128:131], v[154:155], off
	s_mov_b64 s[4:5], 0
	s_branch .LBB0_1648

; #define PG8_STAGE(bufoff, gbase, voff) do { _Pragma("unroll") for (int _i = 0; _i < 2; ++_i) \
;     __builtin_amdgcn_global_load_lds((const unsigned*)((const char*)(gbase) + (voff)[_i]), (LAS unsigned*)(lds + (bufoff) + ldsw + _i * 8192), 16, 0, 0); } while (0)
; #define PG8_LDA(dst, b, h) do { _Pragma("unroll") for (int m = 0; m < 4; ++m) _Pragma("unroll") for (int k = 0; k < 2; ++k) dst[m][k] = *(const LAS bf16x8*)(lds + PG8_SA(b, h) + aoff + m * 2048 + k * 1024); } while (0)
; #define PG8_LDB(dst, b, h) do { _Pragma("unroll") for (int n = 0; n < 2; ++n) _Pragma("unroll") for (int k = 0; k < 2; ++k) dst[n][k] = *(const LAS bf16x8*)(lds + PG8_SB(b, h) + boff + n * 2048 + k * 1024); } while (0)
; #define PG8_MMA(ai, bj, At, Bt) do { __builtin_amdgcn_s_setprio(1); _Pragma("unroll") for (int m = 0; m < 4; ++m) _Pragma("unroll") for (int n = 0; n < 2; ++n) _Pragma("unroll") for (int k = 0; k < 2; ++k) \
;     acc[ai][bj][m][n] = __builtin_amdgcn_mfma_f32_16x16x32_bf16(Bt[n][k], At[m][k], acc[ai][bj][m][n], 0, 0, 0); __builtin_amdgcn_s_setprio(0); } while (0)
; template <class Epi, class Sched>
; DI void gemm_phase(LAS unsigned char* lds, const Gemm g, const Sched& S, const Epi& E) {
;     ...
;     const bool has_next = S.next(ui + 1, nxt);
;     const char* nA = has_next ? (const char*)g.A + (size_t)nxt.pm * tstep : cA; const char* nB = has_next ? (const char*)g.Bt + (size_t)nxt.pn * tstep : cB;
; #pragma unroll 1
;     for (int t = 0; t < nt; t += 2) {
;       const bool last = (t == nt - 2);
;       const char* a1 = cA + (size_t)(t + 1) * kstep;
;       const char* a2 = last ? nA : cA + (size_t)(t + 2) * kstep; const char* b2 = last ? nB : cB + (size_t)(t + 2) * kstep;
;       const char* a3 = a2 + kstep; const char* b3 = b2 + kstep;
;       PG8_LDB(B0, 0, 0); PG8_SCHED; PG8_LDA(At, 0, 0); PG8_STAGE(PG8_SA(1, 1), a1 + hstep, voffA);
;       PG8_WAIT_L(8); PG8_BAR; PG8_WAIT_L(0); PG8_MMA(0, 0, At, B0); PG8_BAR; PG8_SCHED;
;       PG8_LDB(B1, 0, 1); PG8_STAGE(PG8_SB(0, 0), b2, voffB);
;       PG8_BAR; PG8_WAIT_L(0); PG8_MMA(0, 1, At, B1); PG8_BAR;
;     ...
; #pragma unroll
;     for (int a = 0; a < 2; ++a)
; #pragma unroll
;       for (int b = 0; b < 2; ++b)
; #pragma unroll
;         for (int m = 0; m < 4; ++m)
; #pragma unroll
;           for (int n = 0; n < 2; ++n) acc[a][b][m][n] = (f32x4){0.f, 0.f, 0.f, 0.f};
;     cur = nxt; cA = nA; cB = nB; ++ui;
.LBB0_1828:
	v_readlane_b32 s12, v238, 61
	v_readlane_b32 s13, v238, 62
	s_ashr_i32 s7, s6, 31
	s_mov_b32 s50, -2
	v_mov_b64_e32 v[0:1], s[12:13]
	v_cmp_lt_i64_e32 vcc, s[10:11], v[0:1]
	s_lshl_b64 s[10:11], s[6:7], 19
	s_add_u32 s10, s21, s10
	s_addc_u32 s11, s22, s11
	s_and_b64 s[12:13], vcc, exec
	s_cselect_b32 s7, s11, s15
	s_cselect_b32 s46, s10, s14
	s_ashr_i32 s5, s4, 31
	s_lshl_b64 s[12:13], s[4:5], 19
	s_add_u32 s12, s23, s12
	s_addc_u32 s13, s28, s13
	s_and_b64 s[18:19], vcc, exec
	s_cselect_b32 s5, s13, s17
	s_cselect_b32 s47, s12, s16
	s_add_u32 s14, s14, 0x40080
	s_addc_u32 s15, s15, 0
	s_add_u32 s48, s16, 0x100
	v_mov_b32_e32 v0, 0
	s_addc_u32 s49, s17, 0
	v_mov_b32_e32 v1, v0
	v_mov_b64_e32 v[2:3], v[0:1]
	v_mov_b64_e32 v[4:5], v[0:1]
	v_mov_b64_e32 v[6:7], v[0:1]
	v_mov_b64_e32 v[8:9], v[0:1]
	v_mov_b64_e32 v[10:11], v[0:1]
	v_mov_b64_e32 v[12:13], v[0:1]
	v_mov_b64_e32 v[14:15], v[0:1]
	v_mov_b64_e32 v[16:17], v[0:1]
	v_mov_b64_e32 v[18:19], v[0:1]
	v_mov_b64_e32 v[20:21], v[0:1]
	v_mov_b64_e32 v[22:23], v[0:1]
	v_mov_b64_e32 v[24:25], v[0:1]
	v_mov_b64_e32 v[26:27], v[0:1]
	v_mov_b64_e32 v[28:29], v[0:1]
	v_mov_b64_e32 v[30:31], v[0:1]
	v_mov_b64_e32 v[32:33], v[0:1]
	v_mov_b64_e32 v[34:35], v[0:1]
	v_mov_b64_e32 v[36:37], v[0:1]
	v_mov_b64_e32 v[38:39], v[0:1]
	v_mov_b64_e32 v[40:41], v[0:1]
	v_mov_b64_e32 v[42:43], v[0:1]
	v_mov_b64_e32 v[44:45], v[0:1]
	v_mov_b64_e32 v[46:47], v[0:1]
	v_mov_b64_e32 v[48:49], v[0:1]
	v_mov_b64_e32 v[50:51], v[0:1]
	v_mov_b64_e32 v[52:53], v[0:1]
	v_mov_b64_e32 v[54:55], v[0:1]
	v_mov_b64_e32 v[56:57], v[0:1]
	v_mov_b64_e32 v[58:59], v[0:1]
	v_mov_b64_e32 v[60:61], v[0:1]
	v_mov_b64_e32 v[62:63], v[0:1]
	v_mov_b64_e32 v[64:65], v[0:1]
	v_mov_b64_e32 v[66:67], v[0:1]
	v_mov_b64_e32 v[68:69], v[0:1]
	v_mov_b64_e32 v[70:71], v[0:1]
	v_mov_b64_e32 v[72:73], v[0:1]
	v_mov_b64_e32 v[74:75], v[0:1]
	v_mov_b64_e32 v[76:77], v[0:1]
	v_mov_b64_e32 v[78:79], v[0:1]
	v_mov_b64_e32 v[80:81], v[0:1]
	v_mov_b64_e32 v[82:83], v[0:1]
	v_mov_b64_e32 v[84:85], v[0:1]
	v_mov_b64_e32 v[86:87], v[0:1]
	v_mov_b64_e32 v[88:89], v[0:1]
	v_mov_b64_e32 v[90:91], v[0:1]
	v_mov_b64_e32 v[92:93], v[0:1]
	v_mov_b64_e32 v[94:95], v[0:1]
	v_mov_b64_e32 v[96:97], v[0:1]
	v_mov_b64_e32 v[98:99], v[0:1]
	v_mov_b64_e32 v[100:101], v[0:1]
	v_mov_b64_e32 v[102:103], v[0:1]
	v_mov_b64_e32 v[104:105], v[0:1]
	v_mov_b64_e32 v[106:107], v[0:1]
	v_mov_b64_e32 v[108:109], v[0:1]
	v_mov_b64_e32 v[110:111], v[0:1]
	v_mov_b64_e32 v[112:113], v[0:1]
	v_mov_b64_e32 v[114:115], v[0:1]
	v_mov_b64_e32 v[116:117], v[0:1]
	v_mov_b64_e32 v[118:119], v[0:1]
	v_mov_b64_e32 v[120:121], v[0:1]
	v_mov_b64_e32 v[122:123], v[0:1]
	v_mov_b64_e32 v[124:125], v[0:1]
	v_mov_b64_e32 v[126:127], v[0:1]
	v_add_u32_e32 v224, 0x10000, v142
	v_add_u32_e32 v225, 0x14000, v142
	v_add_u32_e32 v226, 0x18000, v142
	v_add_u32_e32 v227, 0x1c000, v142
	ds_read_b128 v[146:149], v224
	ds_read_b128 v[150:153], v224 offset:1024
	ds_read_b128 v[154:157], v224 offset:2048
	ds_read_b128 v[158:161], v224 offset:3072
.LBB0_1829:
	s_add_u32 s16, s14, 0xfffc0080
	s_addc_u32 s17, s15, -1
	s_add_i32 s51, 0, 0x10000
	s_cmp_eq_u32 s50, 12
	s_cselect_b32 s19, s7, s17
	s_cselect_b32 s18, s46, s16
	s_cselect_b32 s17, s5, s49
	s_cselect_b32 s16, s47, s48
	s_add_i32 m0, s29, 0xc000
	ds_read_b128 v[162:165], v143
	ds_read_b128 v[166:169], v143 offset:1024
	ds_read_b128 v[170:173], v143 offset:2048
	ds_read_b128 v[174:177], v143 offset:3072
	ds_read_b128 v[178:181], v143 offset:4096
	ds_read_b128 v[196:199], v143 offset:5120
	ds_read_b128 v[200:203], v143 offset:6144
	ds_read_b128 v[204:207], v143 offset:7168
	global_load_lds_dwordx4 v136, s[14:15]
	s_add_i32 m0, s29, 0xe000
	s_nop 0
	global_load_lds_dwordx4 v138, s[14:15]
	s_waitcnt lgkmcnt(8)
	s_barrier
	s_waitcnt lgkmcnt(0)
	v_mfma_f32_16x16x32_bf16 v[124:127], v[146:149], v[162:165], v[124:127]
	v_mfma_f32_16x16x32_bf16 v[120:123], v[154:157], v[162:165], v[120:123]
	v_mfma_f32_16x16x32_bf16 v[112:115], v[146:149], v[170:173], v[112:115]
	v_mfma_f32_16x16x32_bf16 v[104:107], v[154:157], v[170:173], v[104:107]
	v_mfma_f32_16x16x32_bf16 v[92:95], v[146:149], v[178:181], v[92:95]
	v_mfma_f32_16x16x32_bf16 v[88:91], v[154:157], v[178:181], v[88:91]
	v_mfma_f32_16x16x32_bf16 v[80:83], v[146:149], v[200:203], v[80:83]
	v_mfma_f32_16x16x32_bf16 v[72:75], v[154:157], v[200:203], v[72:75]
	v_mfma_f32_16x16x32_bf16 v[124:127], v[150:153], v[166:169], v[124:127]
	v_mfma_f32_16x16x32_bf16 v[120:123], v[158:161], v[166:169], v[120:123]
	v_mfma_f32_16x16x32_bf16 v[112:115], v[150:153], v[174:177], v[112:115]
	v_mfma_f32_16x16x32_bf16 v[104:107], v[158:161], v[174:177], v[104:107]
	v_mfma_f32_16x16x32_bf16 v[92:95], v[150:153], v[196:199], v[92:95]
	v_mfma_f32_16x16x32_bf16 v[88:91], v[158:161], v[196:199], v[88:91]
	v_mfma_f32_16x16x32_bf16 v[80:83], v[150:153], v[204:207], v[80:83]
	v_mfma_f32_16x16x32_bf16 v[72:75], v[158:161], v[204:207], v[72:75]
	s_barrier
	s_add_i32 s54, 0, 0x14000
	s_add_i32 s51, s51, s20
	ds_read_b128 v[208:211], v225
	ds_read_b128 v[212:215], v225 offset:1024
	ds_read_b128 v[216:219], v225 offset:2048
	ds_read_b128 v[220:223], v225 offset:3072
	s_add_u32 vcc_lo, s16, s0
	s_addc_u32 vcc_hi, s17, s1
	s_mov_b32 m0, s51
	s_nop 0
	global_load_lds_dwordx4 v132, s[16:17]
	s_add_i32 m0, s51, 0x2000
	s_nop 0
	global_load_lds_dwordx4 v128, s[16:17]
	s_barrier
; #define PG8_STAGE(bufoff, gbase, voff) do { _Pragma("unroll") for (int _i = 0; _i < 2; ++_i) \
;     __builtin_amdgcn_global_load_lds((const unsigned*)((const char*)(gbase) + (voff)[_i]), (LAS unsigned*)(lds + (bufoff) + ldsw + _i * 8192), 16, 0, 0); } while (0)
; #define PG8_LDA(dst, b, h) do { _Pragma("unroll") for (int m = 0; m < 4; ++m) _Pragma("unroll") for (int k = 0; k < 2; ++k) dst[m][k] = *(const LAS bf16x8*)(lds + PG8_SA(b, h) + aoff + m * 2048 + k * 1024); } while (0)
; #define PG8_LDB(dst, b, h) do { _Pragma("unroll") for (int n = 0; n < 2; ++n) _Pragma("unroll") for (int k = 0; k < 2; ++k) dst[n][k] = *(const LAS bf16x8*)(lds + PG8_SB(b, h) + boff + n * 2048 + k * 1024); } while (0)
; #define PG8_MMA(ai, bj, At, Bt) do { __builtin_amdgcn_s_setprio(1); _Pragma("unroll") for (int m = 0; m < 4; ++m) _Pragma("unroll") for (int n = 0; n < 2; ++n) _Pragma("unroll") for (int k = 0; k < 2; ++k) \
;     acc[ai][bj][m][n] = __builtin_amdgcn_mfma_f32_16x16x32_bf16(Bt[n][k], At[m][k], acc[ai][bj][m][n], 0, 0, 0); __builtin_amdgcn_s_setprio(0); } while (0)
; #define PG8_WAIT_V(n) asm volatile("s_waitcnt vmcnt(" #n ")" ::: "memory")
; #define PG8_WAIT_L(n) asm volatile("s_waitcnt lgkmcnt(" #n ")" ::: "memory")
; #define PG8_BAR __builtin_amdgcn_s_barrier()
; #define PG8_SCHED __builtin_amdgcn_sched_barrier(0)
; template <class Epi, class Sched>
; DI void gemm_phase(LAS unsigned char* lds, const Gemm g, const Sched& S, const Epi& E) {
;     ...
;       PG8_BAR; PG8_WAIT_L(0); PG8_MMA(0, 1, At, B1); PG8_BAR;
;       PG8_LDA(At, 0, 1); PG8_STAGE(PG8_SA(0, 0), a2, voffA);
;       PG8_BAR; PG8_WAIT_L(0); PG8_MMA(1, 0, At, B0); PG8_BAR; PG8_SCHED;
;       PG8_STAGE(PG8_SB(0, 1), b2 + hstep, voffB);
;       PG8_WAIT_V(6); PG8_BAR; PG8_MMA(1, 1, At, B1); PG8_BAR;
;       PG8_LDB(B0, 1, 0); PG8_SCHED; PG8_LDA(At, 1, 0); PG8_STAGE(PG8_SA(0, 1), a2 + hstep, voffA);
;       PG8_WAIT_L(8); PG8_BAR; PG8_WAIT_L(0); PG8_MMA(0, 0, At, B0); PG8_BAR; PG8_SCHED;
;       PG8_LDB(B1, 1, 1); PG8_STAGE(PG8_SB(1, 0), b3, voffB);
;       PG8_BAR; PG8_WAIT_L(0); PG8_MMA(0, 1, At, B1); PG8_BAR;
;       PG8_LDA(At, 1, 1); PG8_STAGE(PG8_SA(1, 0), a3, voffA);
;       PG8_BAR; PG8_WAIT_L(0); PG8_MMA(1, 0, At, B0); PG8_BAR; PG8_SCHED;
	s_waitcnt lgkmcnt(0)
	v_mfma_f32_16x16x32_bf16 v[116:119], v[208:211], v[162:165], v[116:119]
	v_mfma_f32_16x16x32_bf16 v[108:111], v[216:219], v[162:165], v[108:111]
	v_mfma_f32_16x16x32_bf16 v[100:103], v[208:211], v[170:173], v[100:103]
	v_mfma_f32_16x16x32_bf16 v[96:99], v[216:219], v[170:173], v[96:99]
	v_mfma_f32_16x16x32_bf16 v[84:87], v[208:211], v[178:181], v[84:87]
	v_mfma_f32_16x16x32_bf16 v[76:79], v[216:219], v[178:181], v[76:79]
	v_mfma_f32_16x16x32_bf16 v[68:71], v[208:211], v[200:203], v[68:71]
	v_mfma_f32_16x16x32_bf16 v[64:67], v[216:219], v[200:203], v[64:67]
	v_mfma_f32_16x16x32_bf16 v[116:119], v[212:215], v[166:169], v[116:119]
	v_mfma_f32_16x16x32_bf16 v[108:111], v[220:223], v[166:169], v[108:111]
	v_mfma_f32_16x16x32_bf16 v[100:103], v[212:215], v[174:177], v[100:103]
	v_mfma_f32_16x16x32_bf16 v[96:99], v[220:223], v[174:177], v[96:99]
	v_mfma_f32_16x16x32_bf16 v[84:87], v[212:215], v[196:199], v[84:87]
	v_mfma_f32_16x16x32_bf16 v[76:79], v[220:223], v[196:199], v[76:79]
	v_mfma_f32_16x16x32_bf16 v[68:71], v[212:215], v[204:207], v[68:71]
	v_mfma_f32_16x16x32_bf16 v[64:67], v[220:223], v[204:207], v[64:67]
	s_mov_b32 m0, s29
	s_add_u32 s100, s18, s0
	s_addc_u32 s101, s19, s1
	s_barrier
	ds_read_b128 v[162:165], v143 offset:16384
	ds_read_b128 v[166:169], v143 offset:17408
	ds_read_b128 v[170:173], v143 offset:18432
	ds_read_b128 v[174:177], v143 offset:19456
	ds_read_b128 v[178:181], v143 offset:20480
	ds_read_b128 v[196:199], v143 offset:21504
	ds_read_b128 v[200:203], v143 offset:22528
	ds_read_b128 v[204:207], v143 offset:23552
	global_load_lds_dwordx4 v134, s[18:19]
	s_mov_b32 m0, s34
	s_nop 0
	global_load_lds_dwordx4 v130, s[18:19]
	s_barrier
	s_waitcnt lgkmcnt(0)
	v_mfma_f32_16x16x32_bf16 v[60:63], v[146:149], v[162:165], v[60:63]
	v_mfma_f32_16x16x32_bf16 v[56:59], v[154:157], v[162:165], v[56:59]
	v_mfma_f32_16x16x32_bf16 v[48:51], v[146:149], v[170:173], v[48:51]
	v_mfma_f32_16x16x32_bf16 v[40:43], v[154:157], v[170:173], v[40:43]
	v_mfma_f32_16x16x32_bf16 v[28:31], v[146:149], v[178:181], v[28:31]
	v_mfma_f32_16x16x32_bf16 v[24:27], v[154:157], v[178:181], v[24:27]
	v_mfma_f32_16x16x32_bf16 v[16:19], v[146:149], v[200:203], v[16:19]
	v_mfma_f32_16x16x32_bf16 v[8:11], v[154:157], v[200:203], v[8:11]
	v_mfma_f32_16x16x32_bf16 v[60:63], v[150:153], v[166:169], v[60:63]
	v_mfma_f32_16x16x32_bf16 v[56:59], v[158:161], v[166:169], v[56:59]
	v_mfma_f32_16x16x32_bf16 v[48:51], v[150:153], v[174:177], v[48:51]
	v_mfma_f32_16x16x32_bf16 v[40:43], v[158:161], v[174:177], v[40:43]
	v_mfma_f32_16x16x32_bf16 v[28:31], v[150:153], v[196:199], v[28:31]
	v_mfma_f32_16x16x32_bf16 v[24:27], v[158:161], v[196:199], v[24:27]
	v_mfma_f32_16x16x32_bf16 v[16:19], v[150:153], v[204:207], v[16:19]
	v_mfma_f32_16x16x32_bf16 v[8:11], v[158:161], v[204:207], v[8:11]
	s_waitcnt vmcnt(8)
	s_barrier
	s_add_u32 s52, s16, 0x40000
	s_addc_u32 s53, s17, 0
	s_add_i32 s51, s54, s20
	s_mov_b32 m0, s51
	s_nop 0
	global_load_lds_dwordx4 v132, s[52:53]
	s_add_i32 m0, s51, 0x2000
	s_nop 0
	global_load_lds_dwordx4 v128, s[52:53]
	s_waitcnt vmcnt(6)
	s_barrier
	ds_read_b128 v[146:149], v226
	ds_read_b128 v[150:153], v226 offset:1024
	ds_read_b128 v[154:157], v226 offset:2048
	ds_read_b128 v[158:161], v226 offset:3072
	v_mfma_f32_16x16x32_bf16 v[52:55], v[208:211], v[162:165], v[52:55]
	v_mfma_f32_16x16x32_bf16 v[44:47], v[216:219], v[162:165], v[44:47]
	v_mfma_f32_16x16x32_bf16 v[36:39], v[208:211], v[170:173], v[36:39]
	v_mfma_f32_16x16x32_bf16 v[32:35], v[216:219], v[170:173], v[32:35]
	v_mfma_f32_16x16x32_bf16 v[20:23], v[208:211], v[178:181], v[20:23]
	v_mfma_f32_16x16x32_bf16 v[12:15], v[216:219], v[178:181], v[12:15]
	v_mfma_f32_16x16x32_bf16 v[4:7], v[208:211], v[200:203], v[4:7]
	v_mfma_f32_16x16x32_bf16 v[0:3], v[216:219], v[200:203], v[0:3]
	v_mfma_f32_16x16x32_bf16 v[52:55], v[212:215], v[166:169], v[52:55]
	v_mfma_f32_16x16x32_bf16 v[44:47], v[220:223], v[166:169], v[44:47]
	v_mfma_f32_16x16x32_bf16 v[36:39], v[212:215], v[174:177], v[36:39]
	v_mfma_f32_16x16x32_bf16 v[32:35], v[220:223], v[174:177], v[32:35]
	v_mfma_f32_16x16x32_bf16 v[20:23], v[212:215], v[196:199], v[20:23]
	v_mfma_f32_16x16x32_bf16 v[12:15], v[220:223], v[196:199], v[12:15]
	v_mfma_f32_16x16x32_bf16 v[4:7], v[212:215], v[204:207], v[4:7]
	v_mfma_f32_16x16x32_bf16 v[0:3], v[220:223], v[204:207], v[0:3]
	s_add_i32 s51, 0, 0x18000
	s_barrier
	s_add_u32 s18, s18, 0x40000
	s_addc_u32 s19, s19, 0
	s_mov_b32 m0, s35
	ds_read_b128 v[162:165], v143 offset:32768
	ds_read_b128 v[166:169], v143 offset:33792
	ds_read_b128 v[170:173], v143 offset:34816
	ds_read_b128 v[174:177], v143 offset:35840
	ds_read_b128 v[178:181], v143 offset:36864
	ds_read_b128 v[196:199], v143 offset:37888
	ds_read_b128 v[200:203], v143 offset:38912
	ds_read_b128 v[204:207], v143 offset:39936
	global_load_lds_dwordx4 v134, s[18:19]
	s_mov_b32 m0, s38
	s_nop 0
	global_load_lds_dwordx4 v130, s[18:19]
	s_waitcnt lgkmcnt(8)
	s_barrier
	s_waitcnt lgkmcnt(0)
	v_mfma_f32_16x16x32_bf16 v[124:127], v[146:149], v[162:165], v[124:127]
	v_mfma_f32_16x16x32_bf16 v[120:123], v[154:157], v[162:165], v[120:123]
	v_mfma_f32_16x16x32_bf16 v[112:115], v[146:149], v[170:173], v[112:115]
	v_mfma_f32_16x16x32_bf16 v[104:107], v[154:157], v[170:173], v[104:107]
	v_mfma_f32_16x16x32_bf16 v[92:95], v[146:149], v[178:181], v[92:95]
	v_mfma_f32_16x16x32_bf16 v[88:91], v[154:157], v[178:181], v[88:91]
	v_mfma_f32_16x16x32_bf16 v[80:83], v[146:149], v[200:203], v[80:83]
	v_mfma_f32_16x16x32_bf16 v[72:75], v[154:157], v[200:203], v[72:75]
	v_mfma_f32_16x16x32_bf16 v[124:127], v[150:153], v[166:169], v[124:127]
	v_mfma_f32_16x16x32_bf16 v[120:123], v[158:161], v[166:169], v[120:123]
	v_mfma_f32_16x16x32_bf16 v[112:115], v[150:153], v[174:177], v[112:115]
	v_mfma_f32_16x16x32_bf16 v[104:107], v[158:161], v[174:177], v[104:107]
	v_mfma_f32_16x16x32_bf16 v[92:95], v[150:153], v[196:199], v[92:95]
	v_mfma_f32_16x16x32_bf16 v[88:91], v[158:161], v[196:199], v[88:91]
	v_mfma_f32_16x16x32_bf16 v[80:83], v[150:153], v[204:207], v[80:83]
	v_mfma_f32_16x16x32_bf16 v[72:75], v[158:161], v[204:207], v[72:75]
	s_barrier
; #define PG8_STAGE(bufoff, gbase, voff) do { _Pragma("unroll") for (int _i = 0; _i < 2; ++_i) \
;     __builtin_amdgcn_global_load_lds((const unsigned*)((const char*)(gbase) + (voff)[_i]), (LAS unsigned*)(lds + (bufoff) + ldsw + _i * 8192), 16, 0, 0); } while (0)
; #define PG8_MMA(ai, bj, At, Bt) do { __builtin_amdgcn_s_setprio(1); _Pragma("unroll") for (int m = 0; m < 4; ++m) _Pragma("unroll") for (int n = 0; n < 2; ++n) _Pragma("unroll") for (int k = 0; k < 2; ++k) \
;     acc[ai][bj][m][n] = __builtin_amdgcn_mfma_f32_16x16x32_bf16(Bt[n][k], At[m][k], acc[ai][bj][m][n], 0, 0, 0); __builtin_amdgcn_s_setprio(0); } while (0)
; #define PG8_WAIT_V(n) asm volatile("s_waitcnt vmcnt(" #n ")" ::: "memory")
; #define PG8_WAIT_L(n) asm volatile("s_waitcnt lgkmcnt(" #n ")" ::: "memory")
; #define PG8_BAR __builtin_amdgcn_s_barrier()
; #define PG8_SCHED __builtin_amdgcn_sched_barrier(0)
; template <class Epi, class Sched>
; DI void gemm_phase(LAS unsigned char* lds, const Gemm g, const Sched& S, const Epi& E) {
;     ...
;       PG8_BAR; PG8_WAIT_L(0); PG8_MMA(1, 0, At, B0); PG8_BAR; PG8_SCHED;
;       PG8_STAGE(PG8_SB(1, 1), b3 + hstep, voffB);
;       PG8_WAIT_V(6); PG8_BAR; PG8_MMA(1, 1, At, B1); PG8_BAR;
;     }
	s_add_i32 s18, 0, 0x1c000
	s_add_i32 s19, s51, s20
	s_mov_b32 m0, s19
	ds_read_b128 v[208:211], v227
	ds_read_b128 v[212:215], v227 offset:1024
	ds_read_b128 v[216:219], v227 offset:2048
	ds_read_b128 v[220:223], v227 offset:3072
	global_load_lds_dwordx4 v132, vcc
	s_add_i32 m0, s19, 0x2000
	s_nop 0
	global_load_lds_dwordx4 v128, vcc
	s_barrier
	s_waitcnt lgkmcnt(0)
	v_mfma_f32_16x16x32_bf16 v[116:119], v[208:211], v[162:165], v[116:119]
	v_mfma_f32_16x16x32_bf16 v[108:111], v[216:219], v[162:165], v[108:111]
	v_mfma_f32_16x16x32_bf16 v[100:103], v[208:211], v[170:173], v[100:103]
	v_mfma_f32_16x16x32_bf16 v[96:99], v[216:219], v[170:173], v[96:99]
	v_mfma_f32_16x16x32_bf16 v[84:87], v[208:211], v[178:181], v[84:87]
	v_mfma_f32_16x16x32_bf16 v[76:79], v[216:219], v[178:181], v[76:79]
	v_mfma_f32_16x16x32_bf16 v[68:71], v[208:211], v[200:203], v[68:71]
	v_mfma_f32_16x16x32_bf16 v[64:67], v[216:219], v[200:203], v[64:67]
	v_mfma_f32_16x16x32_bf16 v[116:119], v[212:215], v[166:169], v[116:119]
	v_mfma_f32_16x16x32_bf16 v[108:111], v[220:223], v[166:169], v[108:111]
	v_mfma_f32_16x16x32_bf16 v[100:103], v[212:215], v[174:177], v[100:103]
	v_mfma_f32_16x16x32_bf16 v[96:99], v[220:223], v[174:177], v[96:99]
	v_mfma_f32_16x16x32_bf16 v[84:87], v[212:215], v[196:199], v[84:87]
	v_mfma_f32_16x16x32_bf16 v[76:79], v[220:223], v[196:199], v[76:79]
	v_mfma_f32_16x16x32_bf16 v[68:71], v[212:215], v[204:207], v[68:71]
	v_mfma_f32_16x16x32_bf16 v[64:67], v[220:223], v[204:207], v[64:67]
	s_mov_b32 m0, s40
	s_barrier
	ds_read_b128 v[162:165], v143 offset:49152
	ds_read_b128 v[166:169], v143 offset:50176
	ds_read_b128 v[170:173], v143 offset:51200
	ds_read_b128 v[174:177], v143 offset:52224
	ds_read_b128 v[178:181], v143 offset:53248
	ds_read_b128 v[196:199], v143 offset:54272
	ds_read_b128 v[200:203], v143 offset:55296
	ds_read_b128 v[204:207], v143 offset:56320
	global_load_lds_dwordx4 v134, s[100:101]
	s_mov_b32 m0, s41
	s_nop 0
	global_load_lds_dwordx4 v130, s[100:101]
	s_barrier
	s_waitcnt lgkmcnt(0)
	v_mfma_f32_16x16x32_bf16 v[60:63], v[146:149], v[162:165], v[60:63]
	v_mfma_f32_16x16x32_bf16 v[56:59], v[154:157], v[162:165], v[56:59]
	v_mfma_f32_16x16x32_bf16 v[48:51], v[146:149], v[170:173], v[48:51]
	v_mfma_f32_16x16x32_bf16 v[40:43], v[154:157], v[170:173], v[40:43]
	v_mfma_f32_16x16x32_bf16 v[28:31], v[146:149], v[178:181], v[28:31]
	v_mfma_f32_16x16x32_bf16 v[24:27], v[154:157], v[178:181], v[24:27]
	v_mfma_f32_16x16x32_bf16 v[16:19], v[146:149], v[200:203], v[16:19]
	v_mfma_f32_16x16x32_bf16 v[8:11], v[154:157], v[200:203], v[8:11]
	v_mfma_f32_16x16x32_bf16 v[60:63], v[150:153], v[166:169], v[60:63]
	v_mfma_f32_16x16x32_bf16 v[56:59], v[158:161], v[166:169], v[56:59]
	v_mfma_f32_16x16x32_bf16 v[48:51], v[150:153], v[174:177], v[48:51]
	v_mfma_f32_16x16x32_bf16 v[40:43], v[158:161], v[174:177], v[40:43]
	v_mfma_f32_16x16x32_bf16 v[28:31], v[150:153], v[196:199], v[28:31]
	v_mfma_f32_16x16x32_bf16 v[24:27], v[158:161], v[196:199], v[24:27]
	v_mfma_f32_16x16x32_bf16 v[16:19], v[150:153], v[204:207], v[16:19]
	v_mfma_f32_16x16x32_bf16 v[8:11], v[158:161], v[204:207], v[8:11]
	s_waitcnt vmcnt(8)
	s_barrier
	s_add_u32 s16, s16, 0x40080
	s_addc_u32 s17, s17, 0
	s_add_i32 s18, s18, s20
	s_mov_b32 m0, s18
	s_nop 0
	global_load_lds_dwordx4 v132, s[16:17]
	s_add_i32 m0, s18, 0x2000
	s_nop 0
	global_load_lds_dwordx4 v128, s[16:17]
	s_waitcnt vmcnt(6)
	s_barrier
	ds_read_b128 v[146:149], v224
	ds_read_b128 v[150:153], v224 offset:1024
	ds_read_b128 v[154:157], v224 offset:2048
	ds_read_b128 v[158:161], v224 offset:3072
	v_mfma_f32_16x16x32_bf16 v[52:55], v[208:211], v[162:165], v[52:55]
	v_mfma_f32_16x16x32_bf16 v[44:47], v[216:219], v[162:165], v[44:47]
	v_mfma_f32_16x16x32_bf16 v[36:39], v[208:211], v[170:173], v[36:39]
	v_mfma_f32_16x16x32_bf16 v[32:35], v[216:219], v[170:173], v[32:35]
	v_mfma_f32_16x16x32_bf16 v[20:23], v[208:211], v[178:181], v[20:23]
	v_mfma_f32_16x16x32_bf16 v[12:15], v[216:219], v[178:181], v[12:15]
	v_mfma_f32_16x16x32_bf16 v[4:7], v[208:211], v[200:203], v[4:7]
	v_mfma_f32_16x16x32_bf16 v[0:3], v[216:219], v[200:203], v[0:3]
	v_mfma_f32_16x16x32_bf16 v[52:55], v[212:215], v[166:169], v[52:55]
	v_mfma_f32_16x16x32_bf16 v[44:47], v[220:223], v[166:169], v[44:47]
	v_mfma_f32_16x16x32_bf16 v[36:39], v[212:215], v[174:177], v[36:39]
	v_mfma_f32_16x16x32_bf16 v[32:35], v[220:223], v[174:177], v[32:35]
	v_mfma_f32_16x16x32_bf16 v[20:23], v[212:215], v[196:199], v[20:23]
	v_mfma_f32_16x16x32_bf16 v[12:15], v[220:223], v[196:199], v[12:15]
	v_mfma_f32_16x16x32_bf16 v[4:7], v[212:215], v[204:207], v[4:7]
	v_mfma_f32_16x16x32_bf16 v[0:3], v[220:223], v[204:207], v[0:3]
	s_add_i32 s50, s50, 2
	s_add_u32 s14, s14, 0x100
	s_addc_u32 s15, s15, 0
	s_add_u32 s48, s48, 0x100
	s_addc_u32 s49, s49, 0
	s_cmp_gt_u32 s50, 13
	s_barrier
	s_cbranch_scc0 .LBB0_1829
;   DI void operator()(const f32x4 (&acc)[2][2][4][2], const pg8::Unit& u, int wr, int wc, int fr_, int fq_) const {
;     ...
;             } else {
;               if (n == 0) {
;                 const f32x4 v1 = acc[ai][bj][m][1];
;                 u32x4 o4;
;                 { const float t0 = fmaxf(v[0], 0.f) * rinv, t1 = fmaxf(v[1], 0.f) * rinv, t2 = fmaxf(v[2], 0.f) * rinv, t3 = fmaxf(v[3], 0.f) * rinv;
;                   o4.x = pack2(t0 * t0, t1 * t1); o4.y = pack2(t2 * t2, t3 * t3); }
;                 { const float t0 = fmaxf(v1[0], 0.f) * rinv, t1 = fmaxf(v1[1], 0.f) * rinv, t2 = fmaxf(v1[2], 0.f) * rinv, t3 = fmaxf(v1[3], 0.f) * rinv;
;                   o4.z = pack2(t0 * t0, t1 * t1); o4.w = pack2(t2 * t2, t3 * t3); }
;                 *(u32x4*)((u16*)big + (size_t)token * 4096 + u.pn * 256 + bj * 128 + wc * 32 + 8 * fq) = o4;
;               }
	s_waitcnt lgkmcnt(0)
	v_mov_b32_e32 v144, v182
	s_lshl_b32 s5, s43, 10
	s_add_i32 s5, s5, 0
	v_and_or_b32 v141, v144, 15, s39
	v_lshl_add_u32 v140, s44, 8, v141
	v_lshl_add_u32 v141, v141, 2, s5
	v_add_u32_e32 v146, 0x20000, v141
	ds_read2_b32 v[148:149], v146 offset1:16
	v_max_f32_e32 v124, 0, v124
	v_max_f32_e32 v125, 0, v125
	v_max_f32_e32 v126, 0, v126
	v_max_f32_e32 v127, 0, v127
	v_max_f32_e32 v120, 0, v120
	v_max_f32_e32 v121, 0, v121
	s_waitcnt lgkmcnt(0)
	v_pk_mul_f32 v[124:125], v[124:125], v[148:149] op_sel_hi:[1,0]
	v_pk_mul_f32 v[126:127], v[126:127], v[148:149] op_sel_hi:[1,0]
	v_pk_mul_f32 v[120:121], v[120:121], v[148:149] op_sel_hi:[1,0]
	v_pk_mul_f32 v[124:125], v[124:125], v[124:125]
	v_pk_mul_f32 v[126:127], v[126:127], v[126:127]
	v_max_f32_e32 v122, 0, v122
	v_max_f32_e32 v123, 0, v123
	v_pk_mul_f32 v[120:121], v[120:121], v[120:121]
	v_max_f32_e32 v116, 0, v116
	v_max_f32_e32 v117, 0, v117
	v_max_f32_e32 v118, 0, v118
	v_max_f32_e32 v119, 0, v119
	v_max_f32_e32 v108, 0, v108
	v_max_f32_e32 v109, 0, v109
	s_lshl_b32 s14, s45, 8
	v_ashrrev_i32_e32 v141, 31, v140
	v_cvt_pk_bf16_f32 v124, v124, v125
	v_cvt_pk_bf16_f32 v125, v126, v127
	v_cvt_pk_bf16_f32 v126, v120, v121
	v_pk_mul_f32 v[120:121], v[122:123], v[148:149] op_sel_hi:[1,0]
	v_pk_mul_f32 v[116:117], v[116:117], v[148:149] op_sel_hi:[1,0]
	v_pk_mul_f32 v[118:119], v[118:119], v[148:149] op_sel_hi:[1,0]
	v_pk_mul_f32 v[108:109], v[108:109], v[148:149] op_sel_hi:[1,0]
	s_ashr_i32 s15, s14, 31
	v_lshlrev_b64 v[150:151], 13, v[140:141]
	v_pk_mul_f32 v[120:121], v[120:121], v[120:121]
	v_pk_mul_f32 v[116:117], v[116:117], v[116:117]
	v_pk_mul_f32 v[118:119], v[118:119], v[118:119]
	v_max_f32_e32 v110, 0, v110
	v_max_f32_e32 v111, 0, v111
	v_pk_mul_f32 v[108:109], v[108:109], v[108:109]
	v_cvt_pk_bf16_f32 v127, v120, v121
	v_lshl_add_u64 v[120:121], s[2:3], 0, v[150:151]
	s_lshl_b64 s[14:15], s[14:15], 1
	v_cvt_pk_bf16_f32 v116, v116, v117
	v_cvt_pk_bf16_f32 v117, v118, v119
	v_cvt_pk_bf16_f32 v118, v108, v109
	v_pk_mul_f32 v[108:109], v[110:111], v[148:149] op_sel_hi:[1,0]
	v_lshl_add_u64 v[120:121], v[120:121], 0, s[14:15]
	v_pk_mul_f32 v[108:109], v[108:109], v[108:109]
	v_lshl_add_u64 v[120:121], v[120:121], 0, s[24:25]
	v_and_b32_e32 v144, 48, v144
	v_cvt_pk_bf16_f32 v119, v108, v109
	v_add_u32_e32 v108, 16, v140
	v_lshl_add_u64 v[120:121], v[120:121], 0, v[144:145]
	v_ashrrev_i32_e32 v109, 31, v108
	global_store_dwordx4 v[120:121], v[116:119], off offset:256
	v_max_f32_e32 v100, 0, v100
	v_max_f32_e32 v101, 0, v101
	v_lshlrev_b64 v[116:117], 13, v[108:109]
	v_max_f32_e32 v108, v112, v112
	v_mov_b32_e32 v112, v149
	v_max_f32_e32 v102, 0, v102
	v_max_f32_e32 v103, 0, v103
	v_max_f32_e32 v96, 0, v96
	v_max_f32_e32 v97, 0, v97
	v_pk_mul_f32 v[100:101], v[100:101], v[112:113] op_sel_hi:[1,0]
	v_pk_mul_f32 v[102:103], v[102:103], v[112:113] op_sel_hi:[1,0]
	v_pk_mul_f32 v[96:97], v[96:97], v[112:113] op_sel_hi:[1,0]
	v_pk_mul_f32 v[100:101], v[100:101], v[100:101]
	v_pk_mul_f32 v[102:103], v[102:103], v[102:103]
	v_max_f32_e32 v98, 0, v98
	v_max_f32_e32 v99, 0, v99
	v_pk_mul_f32 v[96:97], v[96:97], v[96:97]
	v_cvt_pk_bf16_f32 v100, v100, v101
	v_cvt_pk_bf16_f32 v101, v102, v103
	v_cvt_pk_bf16_f32 v102, v96, v97
	v_pk_mul_f32 v[96:97], v[98:99], v[112:113] op_sel_hi:[1,0]
	ds_read2_b32 v[98:99], v146 offset0:32 offset1:48
	v_max_f32_e32 v92, 0, v92
	v_max_f32_e32 v93, 0, v93
	v_max_f32_e32 v94, 0, v94
	v_max_f32_e32 v95, 0, v95
	v_max_f32_e32 v88, 0, v88
	v_max_f32_e32 v89, 0, v89
	v_pk_mul_f32 v[96:97], v[96:97], v[96:97]
	s_waitcnt lgkmcnt(0)
	v_pk_mul_f32 v[92:93], v[92:93], v[98:99] op_sel_hi:[1,0]
	v_pk_mul_f32 v[94:95], v[94:95], v[98:99] op_sel_hi:[1,0]
	v_pk_mul_f32 v[88:89], v[88:89], v[98:99] op_sel_hi:[1,0]
	v_cvt_pk_bf16_f32 v103, v96, v97
	v_add_u32_e32 v96, 32, v140
	v_pk_mul_f32 v[92:93], v[92:93], v[92:93]
	v_pk_mul_f32 v[94:95], v[94:95], v[94:95]
	v_max_f32_e32 v90, 0, v90
	v_max_f32_e32 v91, 0, v91
	v_pk_mul_f32 v[88:89], v[88:89], v[88:89]
	v_max_f32_e32 v84, 0, v84
	v_max_f32_e32 v85, 0, v85
	v_max_f32_e32 v86, 0, v86
	v_max_f32_e32 v87, 0, v87
	v_max_f32_e32 v76, 0, v76
	v_max_f32_e32 v77, 0, v77
	v_ashrrev_i32_e32 v97, 31, v96
	v_cvt_pk_bf16_f32 v92, v92, v93
	v_cvt_pk_bf16_f32 v93, v94, v95
	v_cvt_pk_bf16_f32 v94, v88, v89
	v_pk_mul_f32 v[88:89], v[90:91], v[98:99] op_sel_hi:[1,0]
	v_pk_mul_f32 v[84:85], v[84:85], v[98:99] op_sel_hi:[1,0]
	v_pk_mul_f32 v[86:87], v[86:87], v[98:99] op_sel_hi:[1,0]
	v_pk_mul_f32 v[76:77], v[76:77], v[98:99] op_sel_hi:[1,0]
	v_lshlrev_b64 v[96:97], 13, v[96:97]
	v_pk_mul_f32 v[88:89], v[88:89], v[88:89]
	v_pk_mul_f32 v[84:85], v[84:85], v[84:85]
	v_pk_mul_f32 v[86:87], v[86:87], v[86:87]
	v_max_f32_e32 v78, 0, v78
	v_max_f32_e32 v79, 0, v79
	v_pk_mul_f32 v[76:77], v[76:77], v[76:77]
	v_cvt_pk_bf16_f32 v95, v88, v89
	v_lshl_add_u64 v[88:89], s[2:3], 0, v[96:97]
	v_cvt_pk_bf16_f32 v84, v84, v85
	v_cvt_pk_bf16_f32 v85, v86, v87
	v_cvt_pk_bf16_f32 v86, v76, v77
	v_pk_mul_f32 v[76:77], v[78:79], v[98:99] op_sel_hi:[1,0]
	v_lshl_add_u64 v[88:89], v[88:89], 0, s[14:15]
	v_pk_mul_f32 v[76:77], v[76:77], v[76:77]
	v_lshl_add_u64 v[88:89], v[88:89], 0, s[24:25]
	v_cvt_pk_bf16_f32 v87, v76, v77
	v_add_u32_e32 v76, 48, v140
	v_lshl_add_u64 v[88:89], v[88:89], 0, v[144:145]
	v_ashrrev_i32_e32 v77, 31, v76
	global_store_dwordx4 v[88:89], v[84:87], off offset:256
	v_max_f32_e32 v68, 0, v68
	v_max_f32_e32 v69, 0, v69
	v_lshlrev_b64 v[84:85], 13, v[76:77]
	v_max_f32_e32 v76, v80, v80
	v_mov_b32_e32 v80, v99
	v_max_f32_e32 v70, 0, v70
	v_max_f32_e32 v71, 0, v71
	v_max_f32_e32 v64, 0, v64
	v_max_f32_e32 v65, 0, v65
	v_pk_mul_f32 v[68:69], v[68:69], v[80:81] op_sel_hi:[1,0]
	v_pk_mul_f32 v[70:71], v[70:71], v[80:81] op_sel_hi:[1,0]
	v_pk_mul_f32 v[64:65], v[64:65], v[80:81] op_sel_hi:[1,0]
	v_pk_mul_f32 v[68:69], v[68:69], v[68:69]
	v_pk_mul_f32 v[70:71], v[70:71], v[70:71]
	v_max_f32_e32 v66, 0, v66
	v_max_f32_e32 v67, 0, v67
	v_pk_mul_f32 v[64:65], v[64:65], v[64:65]
	v_cvt_pk_bf16_f32 v68, v68, v69
	v_cvt_pk_bf16_f32 v69, v70, v71
	v_cvt_pk_bf16_f32 v70, v64, v65
	v_pk_mul_f32 v[64:65], v[66:67], v[80:81] op_sel_hi:[1,0]
	ds_read2_b32 v[66:67], v146 offset0:128 offset1:144
	v_max_f32_e32 v60, 0, v60
	v_max_f32_e32 v61, 0, v61
	v_max_f32_e32 v62, 0, v62
	v_max_f32_e32 v63, 0, v63
	v_max_f32_e32 v56, 0, v56
	v_max_f32_e32 v57, 0, v57
	v_pk_mul_f32 v[64:65], v[64:65], v[64:65]
	s_waitcnt lgkmcnt(0)
;   DI void operator()(const f32x4 (&acc)[2][2][4][2], const pg8::Unit& u, int wr, int wc, int fr_, int fq_) const {
;     ...
;             } else {
;               if (n == 0) {
;                 const f32x4 v1 = acc[ai][bj][m][1];
;                 u32x4 o4;
;                 { const float t0 = fmaxf(v[0], 0.f) * rinv, t1 = fmaxf(v[1], 0.f) * rinv, t2 = fmaxf(v[2], 0.f) * rinv, t3 = fmaxf(v[3], 0.f) * rinv;
;                   o4.x = pack2(t0 * t0, t1 * t1); o4.y = pack2(t2 * t2, t3 * t3); }
;                 { const float t0 = fmaxf(v1[0], 0.f) * rinv, t1 = fmaxf(v1[1], 0.f) * rinv, t2 = fmaxf(v1[2], 0.f) * rinv, t3 = fmaxf(v1[3], 0.f) * rinv;
;                   o4.z = pack2(t0 * t0, t1 * t1); o4.w = pack2(t2 * t2, t3 * t3); }
;                 *(u32x4*)((u16*)big + (size_t)token * 4096 + u.pn * 256 + bj * 128 + wc * 32 + 8 * fq) = o4;
;               }
	v_pk_mul_f32 v[60:61], v[60:61], v[66:67] op_sel_hi:[1,0]
	v_pk_mul_f32 v[62:63], v[62:63], v[66:67] op_sel_hi:[1,0]
	v_pk_mul_f32 v[56:57], v[56:57], v[66:67] op_sel_hi:[1,0]
	v_cvt_pk_bf16_f32 v71, v64, v65
	v_add_u32_e32 v64, 0x80, v140
	v_pk_mul_f32 v[60:61], v[60:61], v[60:61]
	v_pk_mul_f32 v[62:63], v[62:63], v[62:63]
	v_max_f32_e32 v58, 0, v58
	v_max_f32_e32 v59, 0, v59
	v_pk_mul_f32 v[56:57], v[56:57], v[56:57]
	v_max_f32_e32 v52, 0, v52
	v_max_f32_e32 v53, 0, v53
	v_max_f32_e32 v54, 0, v54
	v_max_f32_e32 v55, 0, v55
	v_max_f32_e32 v44, 0, v44
	v_max_f32_e32 v45, 0, v45
	v_ashrrev_i32_e32 v65, 31, v64
	v_cvt_pk_bf16_f32 v60, v60, v61
	v_cvt_pk_bf16_f32 v61, v62, v63
	v_cvt_pk_bf16_f32 v62, v56, v57
	v_pk_mul_f32 v[56:57], v[58:59], v[66:67] op_sel_hi:[1,0]
	v_pk_mul_f32 v[52:53], v[52:53], v[66:67] op_sel_hi:[1,0]
	v_pk_mul_f32 v[54:55], v[54:55], v[66:67] op_sel_hi:[1,0]
	v_pk_mul_f32 v[44:45], v[44:45], v[66:67] op_sel_hi:[1,0]
	v_lshlrev_b64 v[64:65], 13, v[64:65]
	v_pk_mul_f32 v[56:57], v[56:57], v[56:57]
	v_pk_mul_f32 v[52:53], v[52:53], v[52:53]
	v_pk_mul_f32 v[54:55], v[54:55], v[54:55]
	v_max_f32_e32 v46, 0, v46
	v_max_f32_e32 v47, 0, v47
	v_pk_mul_f32 v[44:45], v[44:45], v[44:45]
	v_cvt_pk_bf16_f32 v63, v56, v57
	v_lshl_add_u64 v[56:57], s[2:3], 0, v[64:65]
	v_cvt_pk_bf16_f32 v52, v52, v53
	v_cvt_pk_bf16_f32 v53, v54, v55
	v_cvt_pk_bf16_f32 v54, v44, v45
	v_pk_mul_f32 v[44:45], v[46:47], v[66:67] op_sel_hi:[1,0]
	v_lshl_add_u64 v[56:57], v[56:57], 0, s[14:15]
	v_pk_mul_f32 v[44:45], v[44:45], v[44:45]
	v_lshl_add_u64 v[56:57], v[56:57], 0, s[24:25]
	v_cvt_pk_bf16_f32 v55, v44, v45
	v_add_u32_e32 v44, 0x90, v140
	v_lshl_add_u64 v[56:57], v[56:57], 0, v[144:145]
	v_ashrrev_i32_e32 v45, 31, v44
	global_store_dwordx4 v[56:57], v[52:55], off offset:256
	v_max_f32_e32 v36, 0, v36
	v_max_f32_e32 v37, 0, v37
	v_lshlrev_b64 v[52:53], 13, v[44:45]
	v_max_f32_e32 v44, v48, v48
	v_mov_b32_e32 v48, v67
	v_max_f32_e32 v38, 0, v38
	v_max_f32_e32 v39, 0, v39
	v_max_f32_e32 v32, 0, v32
	v_max_f32_e32 v33, 0, v33
	v_pk_mul_f32 v[36:37], v[36:37], v[48:49] op_sel_hi:[1,0]
	v_pk_mul_f32 v[38:39], v[38:39], v[48:49] op_sel_hi:[1,0]
	v_pk_mul_f32 v[32:33], v[32:33], v[48:49] op_sel_hi:[1,0]
	v_pk_mul_f32 v[36:37], v[36:37], v[36:37]
	v_pk_mul_f32 v[38:39], v[38:39], v[38:39]
	v_max_f32_e32 v34, 0, v34
	v_max_f32_e32 v35, 0, v35
	v_pk_mul_f32 v[32:33], v[32:33], v[32:33]
	v_cvt_pk_bf16_f32 v36, v36, v37
	v_cvt_pk_bf16_f32 v37, v38, v39
	v_cvt_pk_bf16_f32 v38, v32, v33
	v_pk_mul_f32 v[32:33], v[34:35], v[48:49] op_sel_hi:[1,0]
	ds_read2_b32 v[34:35], v146 offset0:160 offset1:176
	v_max_f32_e32 v28, 0, v28
	v_max_f32_e32 v29, 0, v29
	v_max_f32_e32 v30, 0, v30
	v_max_f32_e32 v31, 0, v31
	v_max_f32_e32 v24, 0, v24
	v_max_f32_e32 v25, 0, v25
	v_pk_mul_f32 v[32:33], v[32:33], v[32:33]
	s_waitcnt lgkmcnt(0)
	v_pk_mul_f32 v[28:29], v[28:29], v[34:35] op_sel_hi:[1,0]
	v_pk_mul_f32 v[30:31], v[30:31], v[34:35] op_sel_hi:[1,0]
	v_pk_mul_f32 v[24:25], v[24:25], v[34:35] op_sel_hi:[1,0]
	v_cvt_pk_bf16_f32 v39, v32, v33
	v_add_u32_e32 v32, 0xa0, v140
	v_pk_mul_f32 v[28:29], v[28:29], v[28:29]
	v_pk_mul_f32 v[30:31], v[30:31], v[30:31]
	v_max_f32_e32 v26, 0, v26
	v_max_f32_e32 v27, 0, v27
	v_pk_mul_f32 v[24:25], v[24:25], v[24:25]
	v_max_f32_e32 v20, 0, v20
	v_max_f32_e32 v21, 0, v21
	v_max_f32_e32 v22, 0, v22
	v_max_f32_e32 v23, 0, v23
	v_max_f32_e32 v12, 0, v12
	v_max_f32_e32 v13, 0, v13
	v_ashrrev_i32_e32 v33, 31, v32
	v_cvt_pk_bf16_f32 v28, v28, v29
	v_cvt_pk_bf16_f32 v29, v30, v31
	v_cvt_pk_bf16_f32 v30, v24, v25
	v_pk_mul_f32 v[24:25], v[26:27], v[34:35] op_sel_hi:[1,0]
	v_pk_mul_f32 v[20:21], v[20:21], v[34:35] op_sel_hi:[1,0]
	v_pk_mul_f32 v[22:23], v[22:23], v[34:35] op_sel_hi:[1,0]
	v_pk_mul_f32 v[12:13], v[12:13], v[34:35] op_sel_hi:[1,0]
	v_lshlrev_b64 v[32:33], 13, v[32:33]
	v_pk_mul_f32 v[24:25], v[24:25], v[24:25]
	v_pk_mul_f32 v[20:21], v[20:21], v[20:21]
	v_pk_mul_f32 v[22:23], v[22:23], v[22:23]
	v_max_f32_e32 v14, 0, v14
	v_max_f32_e32 v15, 0, v15
	v_pk_mul_f32 v[12:13], v[12:13], v[12:13]
	v_cvt_pk_bf16_f32 v31, v24, v25
	v_lshl_add_u64 v[24:25], s[2:3], 0, v[32:33]
	v_cvt_pk_bf16_f32 v20, v20, v21
	v_cvt_pk_bf16_f32 v21, v22, v23
	v_cvt_pk_bf16_f32 v22, v12, v13
	v_pk_mul_f32 v[12:13], v[14:15], v[34:35] op_sel_hi:[1,0]
	v_lshl_add_u64 v[24:25], v[24:25], 0, s[14:15]
	v_pk_mul_f32 v[12:13], v[12:13], v[12:13]
	v_lshl_add_u64 v[24:25], v[24:25], 0, s[24:25]
	v_cvt_pk_bf16_f32 v23, v12, v13
	v_add_u32_e32 v12, 0xb0, v140
	v_lshl_add_u64 v[24:25], v[24:25], 0, v[144:145]
	v_ashrrev_i32_e32 v13, 31, v12
	v_max_f32_e32 v109, v113, v113
	v_max_f32_e32 v110, v114, v114
	v_max_f32_e32 v111, v115, v115
	v_max_f32_e32 v77, v81, v81
	v_max_f32_e32 v78, v82, v82
	v_max_f32_e32 v79, v83, v83
	v_max_f32_e32 v45, v49, v49
	v_max_f32_e32 v46, v50, v50
	v_max_f32_e32 v47, v51, v51
	global_store_dwordx4 v[24:25], v[20:23], off offset:256
	v_max_f32_e32 v14, v18, v18
	v_max_f32_e32 v15, v19, v19
	v_lshlrev_b64 v[20:21], 13, v[12:13]
	v_max_f32_e32 v12, v16, v16
	v_max_f32_e32 v13, v17, v17
	v_max_f32_e32 v108, 0, v108
	v_max_f32_e32 v109, 0, v109
	v_max_f32_e32 v110, 0, v110
	v_max_f32_e32 v111, 0, v111
	v_max_f32_e32 v104, 0, v104
	v_max_f32_e32 v105, 0, v105
	v_max_f32_e32 v76, 0, v76
; #define PG8_WAIT_V(n) asm volatile("s_waitcnt vmcnt(" #n ")" ::: "memory")
; #define PG8_BAR __builtin_amdgcn_s_barrier()
; template <class Epi, class Sched>
; DI void gemm_phase(LAS unsigned char* lds, const Gemm g, const Sched& S, const Epi& E) {
;     ...
;   PG8_WAIT_V(0);
;   if (wr == 0) PG8_BAR;
;   PG8_BAR;
;   DI void operator()(const f32x4 (&acc)[2][2][4][2], const pg8::Unit& u, int wr, int wc, int fr_, int fq_) const {
;     ...
;             } else {
;               if (n == 0) {
;                 const f32x4 v1 = acc[ai][bj][m][1];
;                 u32x4 o4;
;                 { const float t0 = fmaxf(v[0], 0.f) * rinv, t1 = fmaxf(v[1], 0.f) * rinv, t2 = fmaxf(v[2], 0.f) * rinv, t3 = fmaxf(v[3], 0.f) * rinv;
;                   o4.x = pack2(t0 * t0, t1 * t1); o4.y = pack2(t2 * t2, t3 * t3); }
;                 { const float t0 = fmaxf(v1[0], 0.f) * rinv, t1 = fmaxf(v1[1], 0.f) * rinv, t2 = fmaxf(v1[2], 0.f) * rinv, t3 = fmaxf(v1[3], 0.f) * rinv;
;                   o4.z = pack2(t0 * t0, t1 * t1); o4.w = pack2(t2 * t2, t3 * t3); }
;                 *(u32x4*)((u16*)big + (size_t)token * 4096 + u.pn * 256 + bj * 128 + wc * 32 + 8 * fq) = o4;
;               }
	v_max_f32_e32 v77, 0, v77
	v_max_f32_e32 v78, 0, v78
	v_max_f32_e32 v79, 0, v79
	v_max_f32_e32 v72, 0, v72
	v_max_f32_e32 v73, 0, v73
	v_max_f32_e32 v44, 0, v44
	v_max_f32_e32 v45, 0, v45
	v_max_f32_e32 v46, 0, v46
	v_max_f32_e32 v47, 0, v47
	v_max_f32_e32 v40, 0, v40
	v_max_f32_e32 v41, 0, v41
	v_max_f32_e32 v12, 0, v12
	v_max_f32_e32 v13, 0, v13
	v_max_f32_e32 v14, 0, v14
	v_max_f32_e32 v15, 0, v15
	v_mov_b32_e32 v16, v35
	v_max_f32_e32 v8, 0, v8
	v_max_f32_e32 v9, 0, v9
	v_pk_mul_f32 v[108:109], v[108:109], v[112:113] op_sel_hi:[1,0]
	v_pk_mul_f32 v[110:111], v[110:111], v[112:113] op_sel_hi:[1,0]
	v_pk_mul_f32 v[104:105], v[104:105], v[112:113] op_sel_hi:[1,0]
	v_pk_mul_f32 v[76:77], v[76:77], v[80:81] op_sel_hi:[1,0]
	v_pk_mul_f32 v[78:79], v[78:79], v[80:81] op_sel_hi:[1,0]
	v_pk_mul_f32 v[72:73], v[72:73], v[80:81] op_sel_hi:[1,0]
	v_pk_mul_f32 v[44:45], v[44:45], v[48:49] op_sel_hi:[1,0]
	v_pk_mul_f32 v[46:47], v[46:47], v[48:49] op_sel_hi:[1,0]
	v_pk_mul_f32 v[40:41], v[40:41], v[48:49] op_sel_hi:[1,0]
	v_pk_mul_f32 v[12:13], v[12:13], v[16:17] op_sel_hi:[1,0]
	v_pk_mul_f32 v[14:15], v[14:15], v[16:17] op_sel_hi:[1,0]
	v_pk_mul_f32 v[8:9], v[8:9], v[16:17] op_sel_hi:[1,0]
	v_pk_mul_f32 v[108:109], v[108:109], v[108:109]
	v_pk_mul_f32 v[110:111], v[110:111], v[110:111]
	v_max_f32_e32 v106, 0, v106
	v_max_f32_e32 v107, 0, v107
	v_pk_mul_f32 v[104:105], v[104:105], v[104:105]
	v_pk_mul_f32 v[76:77], v[76:77], v[76:77]
	v_pk_mul_f32 v[78:79], v[78:79], v[78:79]
	v_max_f32_e32 v74, 0, v74
	v_max_f32_e32 v75, 0, v75
	v_pk_mul_f32 v[72:73], v[72:73], v[72:73]
	v_pk_mul_f32 v[44:45], v[44:45], v[44:45]
	v_pk_mul_f32 v[46:47], v[46:47], v[46:47]
	v_max_f32_e32 v42, 0, v42
	v_max_f32_e32 v43, 0, v43
	v_pk_mul_f32 v[40:41], v[40:41], v[40:41]
	v_pk_mul_f32 v[12:13], v[12:13], v[12:13]
	v_pk_mul_f32 v[14:15], v[14:15], v[14:15]
	v_max_f32_e32 v10, 0, v10
	v_max_f32_e32 v11, 0, v11
	v_pk_mul_f32 v[8:9], v[8:9], v[8:9]
	v_cvt_pk_bf16_f32 v108, v108, v109
	v_cvt_pk_bf16_f32 v109, v110, v111
	v_cvt_pk_bf16_f32 v110, v104, v105
	v_pk_mul_f32 v[104:105], v[106:107], v[112:113] op_sel_hi:[1,0]
	v_cvt_pk_bf16_f32 v76, v76, v77
	v_cvt_pk_bf16_f32 v77, v78, v79
	v_cvt_pk_bf16_f32 v78, v72, v73
	v_pk_mul_f32 v[72:73], v[74:75], v[80:81] op_sel_hi:[1,0]
	v_cvt_pk_bf16_f32 v44, v44, v45
	v_cvt_pk_bf16_f32 v45, v46, v47
	v_cvt_pk_bf16_f32 v46, v40, v41
	v_pk_mul_f32 v[40:41], v[42:43], v[48:49] op_sel_hi:[1,0]
	v_cvt_pk_bf16_f32 v12, v12, v13
	v_cvt_pk_bf16_f32 v13, v14, v15
	v_cvt_pk_bf16_f32 v14, v8, v9
	v_pk_mul_f32 v[8:9], v[10:11], v[16:17] op_sel_hi:[1,0]
	v_max_f32_e32 v4, 0, v4
	v_max_f32_e32 v5, 0, v5
	v_max_f32_e32 v6, 0, v6
	v_max_f32_e32 v7, 0, v7
	v_max_f32_e32 v0, 0, v0
	v_max_f32_e32 v1, 0, v1
	v_pk_mul_f32 v[104:105], v[104:105], v[104:105]
	v_pk_mul_f32 v[72:73], v[72:73], v[72:73]
	v_pk_mul_f32 v[40:41], v[40:41], v[40:41]
	v_pk_mul_f32 v[8:9], v[8:9], v[8:9]
	v_pk_mul_f32 v[4:5], v[4:5], v[16:17] op_sel_hi:[1,0]
	v_pk_mul_f32 v[6:7], v[6:7], v[16:17] op_sel_hi:[1,0]
	v_pk_mul_f32 v[0:1], v[0:1], v[16:17] op_sel_hi:[1,0]
	v_cvt_pk_bf16_f32 v111, v104, v105
	v_lshl_add_u64 v[104:105], s[2:3], 0, v[116:117]
	v_cvt_pk_bf16_f32 v79, v72, v73
	v_lshl_add_u64 v[72:73], s[2:3], 0, v[84:85]
	v_cvt_pk_bf16_f32 v47, v40, v41
	v_lshl_add_u64 v[40:41], s[2:3], 0, v[52:53]
	v_cvt_pk_bf16_f32 v15, v8, v9
	v_lshl_add_u64 v[8:9], s[2:3], 0, v[20:21]
	v_pk_mul_f32 v[4:5], v[4:5], v[4:5]
	v_pk_mul_f32 v[6:7], v[6:7], v[6:7]
	v_max_f32_e32 v2, 0, v2
	v_max_f32_e32 v3, 0, v3
	v_pk_mul_f32 v[0:1], v[0:1], v[0:1]
	v_lshl_add_u64 v[104:105], v[104:105], 0, s[14:15]
	v_lshl_add_u64 v[72:73], v[72:73], 0, s[14:15]
	v_lshl_add_u64 v[40:41], v[40:41], 0, s[14:15]
	v_lshl_add_u64 v[8:9], v[8:9], 0, s[14:15]
	v_cvt_pk_bf16_f32 v4, v4, v5
	v_cvt_pk_bf16_f32 v5, v6, v7
	v_cvt_pk_bf16_f32 v6, v0, v1
	v_pk_mul_f32 v[0:1], v[2:3], v[16:17] op_sel_hi:[1,0]
	v_lshl_add_u64 v[104:105], v[104:105], 0, s[24:25]
	v_lshl_add_u64 v[72:73], v[72:73], 0, s[24:25]
	v_lshl_add_u64 v[40:41], v[40:41], 0, s[24:25]
	v_lshl_add_u64 v[8:9], v[8:9], 0, s[24:25]
	v_pk_mul_f32 v[0:1], v[0:1], v[0:1]
	v_lshl_add_u64 v[104:105], v[104:105], 0, v[144:145]
	v_lshl_add_u64 v[72:73], v[72:73], 0, v[144:145]
	v_lshl_add_u64 v[40:41], v[40:41], 0, v[144:145]
	v_lshl_add_u64 v[8:9], v[8:9], 0, v[144:145]
	v_cvt_pk_bf16_f32 v7, v0, v1
	s_and_b64 vcc, exec, s[36:37]
	s_mov_b32 s43, s42
	s_mov_b32 s45, s4
	s_mov_b32 s44, s6
	s_mov_b64 s[16:17], s[12:13]
	s_mov_b64 s[14:15], s[10:11]
	v_readlane_b32 s51, v237, 11
	global_store_dwordx4 v[120:121], v[124:127], off
	global_store_dwordx4 v[104:105], v[108:111], off
	global_store_dwordx4 v[104:105], v[100:103], off offset:256
	global_store_dwordx4 v[88:89], v[92:95], off
	global_store_dwordx4 v[72:73], v[76:79], off
	global_store_dwordx4 v[72:73], v[68:71], off offset:256
	global_store_dwordx4 v[56:57], v[60:63], off
	global_store_dwordx4 v[40:41], v[44:47], off
	global_store_dwordx4 v[40:41], v[36:39], off offset:256
	global_store_dwordx4 v[24:25], v[28:31], off
	global_store_dwordx4 v[8:9], v[12:15], off
	global_store_dwordx4 v[8:9], v[4:7], off offset:256
	s_cbranch_vccz .LBB0_1822
	s_waitcnt vmcnt(0)
	s_cmpk_gt_u32 s9, 0xff
	s_cbranch_scc1 .LBB0_1833
	s_barrier

; #define PG8_STAGE(bufoff, gbase, voff) do { _Pragma("unroll") for (int _i = 0; _i < 2; ++_i) \
;     __builtin_amdgcn_global_load_lds((const unsigned*)((const char*)(gbase) + (voff)[_i]), (LAS unsigned*)(lds + (bufoff) + ldsw + _i * 8192), 16, 0, 0); } while (0)
; #define PG8_LDA(dst, b, h) do { _Pragma("unroll") for (int m = 0; m < 4; ++m) _Pragma("unroll") for (int k = 0; k < 2; ++k) dst[m][k] = *(const LAS bf16x8*)(lds + PG8_SA(b, h) + aoff + m * 2048 + k * 1024); } while (0)
; #define PG8_LDB(dst, b, h) do { _Pragma("unroll") for (int n = 0; n < 2; ++n) _Pragma("unroll") for (int k = 0; k < 2; ++k) dst[n][k] = *(const LAS bf16x8*)(lds + PG8_SB(b, h) + boff + n * 2048 + k * 1024); } while (0)
; #define PG8_MMA(ai, bj, At, Bt) do { __builtin_amdgcn_s_setprio(1); _Pragma("unroll") for (int m = 0; m < 4; ++m) _Pragma("unroll") for (int n = 0; n < 2; ++n) _Pragma("unroll") for (int k = 0; k < 2; ++k) \
;     acc[ai][bj][m][n] = __builtin_amdgcn_mfma_f32_16x16x32_bf16(Bt[n][k], At[m][k], acc[ai][bj][m][n], 0, 0, 0); __builtin_amdgcn_s_setprio(0); } while (0)
; template <class Epi, class Sched>
; DI void gemm_phase(LAS unsigned char* lds, const Gemm g, const Sched& S, const Epi& E) {
;     ...
;     const bool has_next = S.next(ui + 1, nxt);
;     const char* nA = has_next ? (const char*)g.A + (size_t)nxt.pm * tstep : cA; const char* nB = has_next ? (const char*)g.Bt + (size_t)nxt.pn * tstep : cB;
; #pragma unroll 1
;     for (int t = 0; t < nt; t += 2) {
;       const bool last = (t == nt - 2);
;       const char* a1 = cA + (size_t)(t + 1) * kstep;
;       const char* a2 = last ? nA : cA + (size_t)(t + 2) * kstep; const char* b2 = last ? nB : cB + (size_t)(t + 2) * kstep;
;       const char* a3 = a2 + kstep; const char* b3 = b2 + kstep;
;       PG8_LDB(B0, 0, 0); PG8_SCHED; PG8_LDA(At, 0, 0); PG8_STAGE(PG8_SA(1, 1), a1 + hstep, voffA);
;       PG8_WAIT_L(8); PG8_BAR; PG8_WAIT_L(0); PG8_MMA(0, 0, At, B0); PG8_BAR; PG8_SCHED;
;       PG8_LDB(B1, 0, 1); PG8_STAGE(PG8_SB(0, 0), b2, voffB);
;       PG8_BAR; PG8_WAIT_L(0); PG8_MMA(0, 1, At, B1); PG8_BAR;
;     ...
; #pragma unroll
;     for (int a = 0; a < 2; ++a)
; #pragma unroll
;       for (int b = 0; b < 2; ++b)
; #pragma unroll
;         for (int m = 0; m < 4; ++m)
; #pragma unroll
;           for (int n = 0; n < 2; ++n) acc[a][b][m][n] = (f32x4){0.f, 0.f, 0.f, 0.f};
;     cur = nxt; cA = nA; cB = nB; ++ui;
.LBB0_1904:
	v_mov_b64_e32 v[0:1], s[30:31]
	s_ashr_i32 s11, s10, 31
	v_cmp_lt_i64_e32 vcc, s[12:13], v[0:1]
	s_lshl_b64 s[12:13], s[10:11], 21
	s_add_u32 s12, s34, s12
	s_addc_u32 s13, s35, s13
	s_and_b64 s[14:15], vcc, exec
	s_cselect_b32 s11, s13, s21
	s_cselect_b32 s17, s12, s20
	s_ashr_i32 s7, s6, 31
	s_lshl_b64 s[14:15], s[6:7], 21
	s_add_u32 s14, s36, s14
	s_addc_u32 s15, s37, s15
	s_and_b64 s[28:29], vcc, exec
	s_cselect_b32 s7, s15, s23
	s_cselect_b32 s19, s14, s22
	s_add_u32 s20, s20, 0x100080
	s_addc_u32 s21, s21, 0
	s_add_u32 s24, s22, 0x100
	v_mov_b32_e32 v0, 0
	s_addc_u32 s49, s23, 0
	s_mov_b32 s50, -2
	v_mov_b32_e32 v1, v0
	v_mov_b64_e32 v[2:3], v[0:1]
	v_mov_b64_e32 v[4:5], v[0:1]
	v_mov_b64_e32 v[6:7], v[0:1]
	v_mov_b64_e32 v[8:9], v[0:1]
	v_mov_b64_e32 v[10:11], v[0:1]
	v_mov_b64_e32 v[12:13], v[0:1]
	v_mov_b64_e32 v[14:15], v[0:1]
	v_mov_b64_e32 v[16:17], v[0:1]
	v_mov_b64_e32 v[18:19], v[0:1]
	v_mov_b64_e32 v[20:21], v[0:1]
	v_mov_b64_e32 v[22:23], v[0:1]
	v_mov_b64_e32 v[24:25], v[0:1]
	v_mov_b64_e32 v[26:27], v[0:1]
	v_mov_b64_e32 v[28:29], v[0:1]
	v_mov_b64_e32 v[30:31], v[0:1]
	v_mov_b64_e32 v[32:33], v[0:1]
	v_mov_b64_e32 v[34:35], v[0:1]
	v_mov_b64_e32 v[36:37], v[0:1]
	v_mov_b64_e32 v[38:39], v[0:1]
	v_mov_b64_e32 v[40:41], v[0:1]
	v_mov_b64_e32 v[42:43], v[0:1]
	v_mov_b64_e32 v[44:45], v[0:1]
	v_mov_b64_e32 v[46:47], v[0:1]
	v_mov_b64_e32 v[48:49], v[0:1]
	v_mov_b64_e32 v[50:51], v[0:1]
	v_mov_b64_e32 v[52:53], v[0:1]
	v_mov_b64_e32 v[54:55], v[0:1]
	v_mov_b64_e32 v[56:57], v[0:1]
	v_mov_b64_e32 v[58:59], v[0:1]
	v_mov_b64_e32 v[60:61], v[0:1]
	v_mov_b64_e32 v[62:63], v[0:1]
	v_mov_b64_e32 v[64:65], v[0:1]
	v_mov_b64_e32 v[66:67], v[0:1]
	v_mov_b64_e32 v[68:69], v[0:1]
	v_mov_b64_e32 v[70:71], v[0:1]
	v_mov_b64_e32 v[72:73], v[0:1]
	v_mov_b64_e32 v[74:75], v[0:1]
	v_mov_b64_e32 v[76:77], v[0:1]
	v_mov_b64_e32 v[78:79], v[0:1]
	v_mov_b64_e32 v[80:81], v[0:1]
	v_mov_b64_e32 v[82:83], v[0:1]
	v_mov_b64_e32 v[84:85], v[0:1]
	v_mov_b64_e32 v[86:87], v[0:1]
	v_mov_b64_e32 v[88:89], v[0:1]
	v_mov_b64_e32 v[90:91], v[0:1]
	v_mov_b64_e32 v[92:93], v[0:1]
	v_mov_b64_e32 v[94:95], v[0:1]
	v_mov_b64_e32 v[96:97], v[0:1]
	v_mov_b64_e32 v[98:99], v[0:1]
	v_mov_b64_e32 v[100:101], v[0:1]
	v_mov_b64_e32 v[102:103], v[0:1]
	v_mov_b64_e32 v[104:105], v[0:1]
	v_mov_b64_e32 v[106:107], v[0:1]
	v_mov_b64_e32 v[108:109], v[0:1]
	v_mov_b64_e32 v[110:111], v[0:1]
	v_mov_b64_e32 v[112:113], v[0:1]
	v_mov_b64_e32 v[114:115], v[0:1]
	v_mov_b64_e32 v[116:117], v[0:1]
	v_mov_b64_e32 v[118:119], v[0:1]
	v_mov_b64_e32 v[120:121], v[0:1]
	v_mov_b64_e32 v[122:123], v[0:1]
	v_mov_b64_e32 v[124:125], v[0:1]
	v_mov_b64_e32 v[126:127], v[0:1]
	v_add_u32_e32 v224, 0x10000, v146
	v_add_u32_e32 v225, 0x14000, v146
	v_add_u32_e32 v226, 0x18000, v146
	v_add_u32_e32 v227, 0x1c000, v146
	ds_read_b128 v[138:141], v224
	ds_read_b128 v[148:151], v224 offset:1024
	ds_read_b128 v[152:155], v224 offset:2048
	ds_read_b128 v[156:159], v224 offset:3072
.LBB0_1905:
	s_add_u32 s22, s20, 0xfff00080
	s_addc_u32 s23, s21, -1
	s_add_i32 s51, 0, 0x10000
	s_cmp_eq_u32 s50, 60
	s_cselect_b32 s29, s11, s23
	s_cselect_b32 s28, s17, s22
	s_cselect_b32 s23, s7, s49
	s_cselect_b32 s22, s19, s24
	s_add_i32 m0, s39, 0xc000
	ds_read_b128 v[160:163], v147
	ds_read_b128 v[164:167], v147 offset:1024
	ds_read_b128 v[168:171], v147 offset:2048
	ds_read_b128 v[172:175], v147 offset:3072
	ds_read_b128 v[176:179], v147 offset:4096
	ds_read_b128 v[196:199], v147 offset:5120
	ds_read_b128 v[200:203], v147 offset:6144
	ds_read_b128 v[204:207], v147 offset:7168
	global_load_lds_dwordx4 v134, s[20:21]
	s_add_i32 m0, s39, 0xe000
	s_nop 0
	global_load_lds_dwordx4 v136, s[20:21]
	s_waitcnt lgkmcnt(8)
	s_barrier
	s_waitcnt lgkmcnt(0)
	v_mfma_f32_16x16x32_bf16 v[124:127], v[138:141], v[160:163], v[124:127]
	v_mfma_f32_16x16x32_bf16 v[120:123], v[152:155], v[160:163], v[120:123]
	v_mfma_f32_16x16x32_bf16 v[108:111], v[138:141], v[168:171], v[108:111]
	v_mfma_f32_16x16x32_bf16 v[104:107], v[152:155], v[168:171], v[104:107]
	v_mfma_f32_16x16x32_bf16 v[92:95], v[138:141], v[176:179], v[92:95]
	v_mfma_f32_16x16x32_bf16 v[88:91], v[152:155], v[176:179], v[88:91]
	v_mfma_f32_16x16x32_bf16 v[76:79], v[138:141], v[200:203], v[76:79]
	v_mfma_f32_16x16x32_bf16 v[72:75], v[152:155], v[200:203], v[72:75]
	v_mfma_f32_16x16x32_bf16 v[124:127], v[148:151], v[164:167], v[124:127]
	v_mfma_f32_16x16x32_bf16 v[120:123], v[156:159], v[164:167], v[120:123]
	v_mfma_f32_16x16x32_bf16 v[108:111], v[148:151], v[172:175], v[108:111]
	v_mfma_f32_16x16x32_bf16 v[104:107], v[156:159], v[172:175], v[104:107]
	v_mfma_f32_16x16x32_bf16 v[92:95], v[148:151], v[196:199], v[92:95]
	v_mfma_f32_16x16x32_bf16 v[88:91], v[156:159], v[196:199], v[88:91]
	v_mfma_f32_16x16x32_bf16 v[76:79], v[148:151], v[204:207], v[76:79]
	v_mfma_f32_16x16x32_bf16 v[72:75], v[156:159], v[204:207], v[72:75]
	s_barrier
	s_add_i32 s54, 0, 0x14000
	s_add_i32 s51, s51, s38
	ds_read_b128 v[208:211], v225
	ds_read_b128 v[212:215], v225 offset:1024
	ds_read_b128 v[216:219], v225 offset:2048
	ds_read_b128 v[220:223], v225 offset:3072
	s_add_u32 vcc_lo, s22, s0
	s_addc_u32 vcc_hi, s23, s1
	s_mov_b32 m0, s51
	s_nop 0
	global_load_lds_dwordx4 v144, s[22:23]
	s_add_i32 m0, s51, 0x2000
	s_nop 0
	global_load_lds_dwordx4 v132, s[22:23]
	s_barrier
; #define PG8_STAGE(bufoff, gbase, voff) do { _Pragma("unroll") for (int _i = 0; _i < 2; ++_i) \
;     __builtin_amdgcn_global_load_lds((const unsigned*)((const char*)(gbase) + (voff)[_i]), (LAS unsigned*)(lds + (bufoff) + ldsw + _i * 8192), 16, 0, 0); } while (0)
; #define PG8_LDA(dst, b, h) do { _Pragma("unroll") for (int m = 0; m < 4; ++m) _Pragma("unroll") for (int k = 0; k < 2; ++k) dst[m][k] = *(const LAS bf16x8*)(lds + PG8_SA(b, h) + aoff + m * 2048 + k * 1024); } while (0)
; #define PG8_LDB(dst, b, h) do { _Pragma("unroll") for (int n = 0; n < 2; ++n) _Pragma("unroll") for (int k = 0; k < 2; ++k) dst[n][k] = *(const LAS bf16x8*)(lds + PG8_SB(b, h) + boff + n * 2048 + k * 1024); } while (0)
; #define PG8_MMA(ai, bj, At, Bt) do { __builtin_amdgcn_s_setprio(1); _Pragma("unroll") for (int m = 0; m < 4; ++m) _Pragma("unroll") for (int n = 0; n < 2; ++n) _Pragma("unroll") for (int k = 0; k < 2; ++k) \
;     acc[ai][bj][m][n] = __builtin_amdgcn_mfma_f32_16x16x32_bf16(Bt[n][k], At[m][k], acc[ai][bj][m][n], 0, 0, 0); __builtin_amdgcn_s_setprio(0); } while (0)
; #define PG8_WAIT_V(n) asm volatile("s_waitcnt vmcnt(" #n ")" ::: "memory")
; #define PG8_WAIT_L(n) asm volatile("s_waitcnt lgkmcnt(" #n ")" ::: "memory")
; #define PG8_BAR __builtin_amdgcn_s_barrier()
; #define PG8_SCHED __builtin_amdgcn_sched_barrier(0)
; template <class Epi, class Sched>
; DI void gemm_phase(LAS unsigned char* lds, const Gemm g, const Sched& S, const Epi& E) {
;     ...
;       PG8_BAR; PG8_WAIT_L(0); PG8_MMA(0, 1, At, B1); PG8_BAR;
;       PG8_LDA(At, 0, 1); PG8_STAGE(PG8_SA(0, 0), a2, voffA);
;       PG8_BAR; PG8_WAIT_L(0); PG8_MMA(1, 0, At, B0); PG8_BAR; PG8_SCHED;
;       PG8_STAGE(PG8_SB(0, 1), b2 + hstep, voffB);
;       PG8_WAIT_V(6); PG8_BAR; PG8_MMA(1, 1, At, B1); PG8_BAR;
;       PG8_LDB(B0, 1, 0); PG8_SCHED; PG8_LDA(At, 1, 0); PG8_STAGE(PG8_SA(0, 1), a2 + hstep, voffA);
;       PG8_WAIT_L(8); PG8_BAR; PG8_WAIT_L(0); PG8_MMA(0, 0, At, B0); PG8_BAR; PG8_SCHED;
;       PG8_LDB(B1, 1, 1); PG8_STAGE(PG8_SB(1, 0), b3, voffB);
;       PG8_BAR; PG8_WAIT_L(0); PG8_MMA(0, 1, At, B1); PG8_BAR;
;       PG8_LDA(At, 1, 1); PG8_STAGE(PG8_SA(1, 0), a3, voffA);
;       PG8_BAR; PG8_WAIT_L(0); PG8_MMA(1, 0, At, B0); PG8_BAR; PG8_SCHED;
	s_waitcnt lgkmcnt(0)
	v_mfma_f32_16x16x32_bf16 v[116:119], v[208:211], v[160:163], v[116:119]
	v_mfma_f32_16x16x32_bf16 v[112:115], v[216:219], v[160:163], v[112:115]
	v_mfma_f32_16x16x32_bf16 v[100:103], v[208:211], v[168:171], v[100:103]
	v_mfma_f32_16x16x32_bf16 v[96:99], v[216:219], v[168:171], v[96:99]
	v_mfma_f32_16x16x32_bf16 v[84:87], v[208:211], v[176:179], v[84:87]
	v_mfma_f32_16x16x32_bf16 v[80:83], v[216:219], v[176:179], v[80:83]
	v_mfma_f32_16x16x32_bf16 v[68:71], v[208:211], v[200:203], v[68:71]
	v_mfma_f32_16x16x32_bf16 v[64:67], v[216:219], v[200:203], v[64:67]
	v_mfma_f32_16x16x32_bf16 v[116:119], v[212:215], v[164:167], v[116:119]
	v_mfma_f32_16x16x32_bf16 v[112:115], v[220:223], v[164:167], v[112:115]
	v_mfma_f32_16x16x32_bf16 v[100:103], v[212:215], v[172:175], v[100:103]
	v_mfma_f32_16x16x32_bf16 v[96:99], v[220:223], v[172:175], v[96:99]
	v_mfma_f32_16x16x32_bf16 v[84:87], v[212:215], v[196:199], v[84:87]
	v_mfma_f32_16x16x32_bf16 v[80:83], v[220:223], v[196:199], v[80:83]
	v_mfma_f32_16x16x32_bf16 v[68:71], v[212:215], v[204:207], v[68:71]
	v_mfma_f32_16x16x32_bf16 v[64:67], v[220:223], v[204:207], v[64:67]
	s_mov_b32 m0, s39
	s_add_u32 s100, s28, s0
	s_addc_u32 s101, s29, s1
	s_barrier
	ds_read_b128 v[160:163], v147 offset:16384
	ds_read_b128 v[164:167], v147 offset:17408
	ds_read_b128 v[168:171], v147 offset:18432
	ds_read_b128 v[172:175], v147 offset:19456
	ds_read_b128 v[176:179], v147 offset:20480
	ds_read_b128 v[196:199], v147 offset:21504
	ds_read_b128 v[200:203], v147 offset:22528
	ds_read_b128 v[204:207], v147 offset:23552
	global_load_lds_dwordx4 v128, s[28:29]
	s_mov_b32 m0, s40
	s_nop 0
	global_load_lds_dwordx4 v130, s[28:29]
	s_barrier
	s_waitcnt lgkmcnt(0)
	v_mfma_f32_16x16x32_bf16 v[60:63], v[138:141], v[160:163], v[60:63]
	v_mfma_f32_16x16x32_bf16 v[56:59], v[152:155], v[160:163], v[56:59]
	v_mfma_f32_16x16x32_bf16 v[44:47], v[138:141], v[168:171], v[44:47]
	v_mfma_f32_16x16x32_bf16 v[40:43], v[152:155], v[168:171], v[40:43]
	v_mfma_f32_16x16x32_bf16 v[28:31], v[138:141], v[176:179], v[28:31]
	v_mfma_f32_16x16x32_bf16 v[24:27], v[152:155], v[176:179], v[24:27]
	v_mfma_f32_16x16x32_bf16 v[12:15], v[138:141], v[200:203], v[12:15]
	v_mfma_f32_16x16x32_bf16 v[8:11], v[152:155], v[200:203], v[8:11]
	v_mfma_f32_16x16x32_bf16 v[60:63], v[148:151], v[164:167], v[60:63]
	v_mfma_f32_16x16x32_bf16 v[56:59], v[156:159], v[164:167], v[56:59]
	v_mfma_f32_16x16x32_bf16 v[44:47], v[148:151], v[172:175], v[44:47]
	v_mfma_f32_16x16x32_bf16 v[40:43], v[156:159], v[172:175], v[40:43]
	v_mfma_f32_16x16x32_bf16 v[28:31], v[148:151], v[196:199], v[28:31]
	v_mfma_f32_16x16x32_bf16 v[24:27], v[156:159], v[196:199], v[24:27]
	v_mfma_f32_16x16x32_bf16 v[12:15], v[148:151], v[204:207], v[12:15]
	v_mfma_f32_16x16x32_bf16 v[8:11], v[156:159], v[204:207], v[8:11]
	s_waitcnt vmcnt(8)
	s_barrier
	s_add_u32 s52, s22, 0x100000
	s_addc_u32 s53, s23, 0
	s_add_i32 s51, s54, s38
	s_mov_b32 m0, s51
	s_nop 0
	global_load_lds_dwordx4 v144, s[52:53]
	s_add_i32 m0, s51, 0x2000
	s_nop 0
	global_load_lds_dwordx4 v132, s[52:53]
	s_waitcnt vmcnt(6)
	s_barrier
	ds_read_b128 v[138:141], v226
	ds_read_b128 v[148:151], v226 offset:1024
	ds_read_b128 v[152:155], v226 offset:2048
	ds_read_b128 v[156:159], v226 offset:3072
	v_mfma_f32_16x16x32_bf16 v[52:55], v[208:211], v[160:163], v[52:55]
	v_mfma_f32_16x16x32_bf16 v[48:51], v[216:219], v[160:163], v[48:51]
	v_mfma_f32_16x16x32_bf16 v[36:39], v[208:211], v[168:171], v[36:39]
	v_mfma_f32_16x16x32_bf16 v[32:35], v[216:219], v[168:171], v[32:35]
	v_mfma_f32_16x16x32_bf16 v[20:23], v[208:211], v[176:179], v[20:23]
	v_mfma_f32_16x16x32_bf16 v[16:19], v[216:219], v[176:179], v[16:19]
	v_mfma_f32_16x16x32_bf16 v[4:7], v[208:211], v[200:203], v[4:7]
	v_mfma_f32_16x16x32_bf16 v[0:3], v[216:219], v[200:203], v[0:3]
	v_mfma_f32_16x16x32_bf16 v[52:55], v[212:215], v[164:167], v[52:55]
	v_mfma_f32_16x16x32_bf16 v[48:51], v[220:223], v[164:167], v[48:51]
	v_mfma_f32_16x16x32_bf16 v[36:39], v[212:215], v[172:175], v[36:39]
	v_mfma_f32_16x16x32_bf16 v[32:35], v[220:223], v[172:175], v[32:35]
	v_mfma_f32_16x16x32_bf16 v[20:23], v[212:215], v[196:199], v[20:23]
	v_mfma_f32_16x16x32_bf16 v[16:19], v[220:223], v[196:199], v[16:19]
	v_mfma_f32_16x16x32_bf16 v[4:7], v[212:215], v[204:207], v[4:7]
	v_mfma_f32_16x16x32_bf16 v[0:3], v[220:223], v[204:207], v[0:3]
	s_add_i32 s51, 0, 0x18000
	s_barrier
	s_add_u32 s28, s28, 0x100000
	s_addc_u32 s29, s29, 0
	s_mov_b32 m0, s41
	ds_read_b128 v[160:163], v147 offset:32768
	ds_read_b128 v[164:167], v147 offset:33792
	ds_read_b128 v[168:171], v147 offset:34816
	ds_read_b128 v[172:175], v147 offset:35840
	ds_read_b128 v[176:179], v147 offset:36864
	ds_read_b128 v[196:199], v147 offset:37888
	ds_read_b128 v[200:203], v147 offset:38912
	ds_read_b128 v[204:207], v147 offset:39936
	global_load_lds_dwordx4 v128, s[28:29]
	s_mov_b32 m0, s42
	s_nop 0
	global_load_lds_dwordx4 v130, s[28:29]
	s_waitcnt lgkmcnt(8)
	s_barrier
	s_waitcnt lgkmcnt(0)
	v_mfma_f32_16x16x32_bf16 v[124:127], v[138:141], v[160:163], v[124:127]
	v_mfma_f32_16x16x32_bf16 v[120:123], v[152:155], v[160:163], v[120:123]
	v_mfma_f32_16x16x32_bf16 v[108:111], v[138:141], v[168:171], v[108:111]
	v_mfma_f32_16x16x32_bf16 v[104:107], v[152:155], v[168:171], v[104:107]
	v_mfma_f32_16x16x32_bf16 v[92:95], v[138:141], v[176:179], v[92:95]
	v_mfma_f32_16x16x32_bf16 v[88:91], v[152:155], v[176:179], v[88:91]
	v_mfma_f32_16x16x32_bf16 v[76:79], v[138:141], v[200:203], v[76:79]
	v_mfma_f32_16x16x32_bf16 v[72:75], v[152:155], v[200:203], v[72:75]
	v_mfma_f32_16x16x32_bf16 v[124:127], v[148:151], v[164:167], v[124:127]
	v_mfma_f32_16x16x32_bf16 v[120:123], v[156:159], v[164:167], v[120:123]
	v_mfma_f32_16x16x32_bf16 v[108:111], v[148:151], v[172:175], v[108:111]
	v_mfma_f32_16x16x32_bf16 v[104:107], v[156:159], v[172:175], v[104:107]
	v_mfma_f32_16x16x32_bf16 v[92:95], v[148:151], v[196:199], v[92:95]
	v_mfma_f32_16x16x32_bf16 v[88:91], v[156:159], v[196:199], v[88:91]
	v_mfma_f32_16x16x32_bf16 v[76:79], v[148:151], v[204:207], v[76:79]
	v_mfma_f32_16x16x32_bf16 v[72:75], v[156:159], v[204:207], v[72:75]
	s_barrier
; #define PG8_STAGE(bufoff, gbase, voff) do { _Pragma("unroll") for (int _i = 0; _i < 2; ++_i) \
;     __builtin_amdgcn_global_load_lds((const unsigned*)((const char*)(gbase) + (voff)[_i]), (LAS unsigned*)(lds + (bufoff) + ldsw + _i * 8192), 16, 0, 0); } while (0)
; #define PG8_MMA(ai, bj, At, Bt) do { __builtin_amdgcn_s_setprio(1); _Pragma("unroll") for (int m = 0; m < 4; ++m) _Pragma("unroll") for (int n = 0; n < 2; ++n) _Pragma("unroll") for (int k = 0; k < 2; ++k) \
;     acc[ai][bj][m][n] = __builtin_amdgcn_mfma_f32_16x16x32_bf16(Bt[n][k], At[m][k], acc[ai][bj][m][n], 0, 0, 0); __builtin_amdgcn_s_setprio(0); } while (0)
; #define PG8_WAIT_V(n) asm volatile("s_waitcnt vmcnt(" #n ")" ::: "memory")
; #define PG8_WAIT_L(n) asm volatile("s_waitcnt lgkmcnt(" #n ")" ::: "memory")
; #define PG8_BAR __builtin_amdgcn_s_barrier()
; #define PG8_SCHED __builtin_amdgcn_sched_barrier(0)
; template <class Epi, class Sched>
; DI void gemm_phase(LAS unsigned char* lds, const Gemm g, const Sched& S, const Epi& E) {
;     ...
;       PG8_BAR; PG8_WAIT_L(0); PG8_MMA(1, 0, At, B0); PG8_BAR; PG8_SCHED;
;       PG8_STAGE(PG8_SB(1, 1), b3 + hstep, voffB);
;       PG8_WAIT_V(6); PG8_BAR; PG8_MMA(1, 1, At, B1); PG8_BAR;
	s_add_i32 s28, 0, 0x1c000
	s_add_i32 s29, s51, s38
	s_mov_b32 m0, s29
	ds_read_b128 v[208:211], v227
	ds_read_b128 v[212:215], v227 offset:1024
	ds_read_b128 v[216:219], v227 offset:2048
	ds_read_b128 v[220:223], v227 offset:3072
	global_load_lds_dwordx4 v144, vcc
	s_add_i32 m0, s29, 0x2000
	s_nop 0
	global_load_lds_dwordx4 v132, vcc
	s_barrier
	s_waitcnt lgkmcnt(0)
	v_mfma_f32_16x16x32_bf16 v[116:119], v[208:211], v[160:163], v[116:119]
	v_mfma_f32_16x16x32_bf16 v[112:115], v[216:219], v[160:163], v[112:115]
	v_mfma_f32_16x16x32_bf16 v[100:103], v[208:211], v[168:171], v[100:103]
	v_mfma_f32_16x16x32_bf16 v[96:99], v[216:219], v[168:171], v[96:99]
	v_mfma_f32_16x16x32_bf16 v[84:87], v[208:211], v[176:179], v[84:87]
	v_mfma_f32_16x16x32_bf16 v[80:83], v[216:219], v[176:179], v[80:83]
	v_mfma_f32_16x16x32_bf16 v[68:71], v[208:211], v[200:203], v[68:71]
	v_mfma_f32_16x16x32_bf16 v[64:67], v[216:219], v[200:203], v[64:67]
	v_mfma_f32_16x16x32_bf16 v[116:119], v[212:215], v[164:167], v[116:119]
	v_mfma_f32_16x16x32_bf16 v[112:115], v[220:223], v[164:167], v[112:115]
	v_mfma_f32_16x16x32_bf16 v[100:103], v[212:215], v[172:175], v[100:103]
	v_mfma_f32_16x16x32_bf16 v[96:99], v[220:223], v[172:175], v[96:99]
	v_mfma_f32_16x16x32_bf16 v[84:87], v[212:215], v[196:199], v[84:87]
	v_mfma_f32_16x16x32_bf16 v[80:83], v[220:223], v[196:199], v[80:83]
	v_mfma_f32_16x16x32_bf16 v[68:71], v[212:215], v[204:207], v[68:71]
	v_mfma_f32_16x16x32_bf16 v[64:67], v[220:223], v[204:207], v[64:67]
	s_mov_b32 m0, s46
	s_barrier
	ds_read_b128 v[160:163], v147 offset:49152
	ds_read_b128 v[164:167], v147 offset:50176
	ds_read_b128 v[168:171], v147 offset:51200
	ds_read_b128 v[172:175], v147 offset:52224
	ds_read_b128 v[176:179], v147 offset:53248
	ds_read_b128 v[196:199], v147 offset:54272
	ds_read_b128 v[200:203], v147 offset:55296
	ds_read_b128 v[204:207], v147 offset:56320
	global_load_lds_dwordx4 v128, s[100:101]
	s_mov_b32 m0, s47
	s_nop 0
	global_load_lds_dwordx4 v130, s[100:101]
	s_barrier
	s_waitcnt lgkmcnt(0)
	v_mfma_f32_16x16x32_bf16 v[60:63], v[138:141], v[160:163], v[60:63]
	v_mfma_f32_16x16x32_bf16 v[56:59], v[152:155], v[160:163], v[56:59]
	v_mfma_f32_16x16x32_bf16 v[44:47], v[138:141], v[168:171], v[44:47]
	v_mfma_f32_16x16x32_bf16 v[40:43], v[152:155], v[168:171], v[40:43]
	v_mfma_f32_16x16x32_bf16 v[28:31], v[138:141], v[176:179], v[28:31]
	v_mfma_f32_16x16x32_bf16 v[24:27], v[152:155], v[176:179], v[24:27]
	v_mfma_f32_16x16x32_bf16 v[12:15], v[138:141], v[200:203], v[12:15]
	v_mfma_f32_16x16x32_bf16 v[8:11], v[152:155], v[200:203], v[8:11]
	v_mfma_f32_16x16x32_bf16 v[60:63], v[148:151], v[164:167], v[60:63]
	v_mfma_f32_16x16x32_bf16 v[56:59], v[156:159], v[164:167], v[56:59]
	v_mfma_f32_16x16x32_bf16 v[44:47], v[148:151], v[172:175], v[44:47]
	v_mfma_f32_16x16x32_bf16 v[40:43], v[156:159], v[172:175], v[40:43]
	v_mfma_f32_16x16x32_bf16 v[28:31], v[148:151], v[196:199], v[28:31]
	v_mfma_f32_16x16x32_bf16 v[24:27], v[156:159], v[196:199], v[24:27]
	v_mfma_f32_16x16x32_bf16 v[12:15], v[148:151], v[204:207], v[12:15]
	v_mfma_f32_16x16x32_bf16 v[8:11], v[156:159], v[204:207], v[8:11]
	s_waitcnt vmcnt(8)
	s_barrier
	s_add_u32 s22, s22, 0x100080
	s_addc_u32 s23, s23, 0
	s_add_i32 s28, s28, s38
	s_mov_b32 m0, s28
	s_nop 0
	global_load_lds_dwordx4 v144, s[22:23]
	s_add_i32 m0, s28, 0x2000
	s_nop 0
	global_load_lds_dwordx4 v132, s[22:23]
	s_waitcnt vmcnt(6)
	s_barrier
; #define PG8_BAR __builtin_amdgcn_s_barrier()
; template <class Epi, class Sched>
; DI void gemm_phase(LAS unsigned char* lds, const Gemm g, const Sched& S, const Epi& E) {
;     ...
;       PG8_WAIT_V(6); PG8_BAR; PG8_MMA(1, 1, At, B1); PG8_BAR;
;     }
;   DI void operator()(const f32x4 (&acc)[2][2][4][2], const pg8::Unit& u, int wr, int wc, int fr_, int fq_) const {
;     ...
;             } else if (EPI == EPI_RESID) {
;               if (n == 0) {
;                 const int f8 = u.pn * 256 + bj * 128 + wc * 32 + 8 * fq;
;                 const f32x4 v1 = acc[ai][bj][m][1];
;                 f32x4 r0, r1;
;                 if (rsrc) {
;                   r0 = *(const f32x4*)(rsrc + (size_t)token * 1024 + f8); r1 = *(const f32x4*)(rsrc + (size_t)token * 1024 + f8 + 4);
;                 } else {
;                   const u32x4 xu = *(const u32x4*)(xr + (size_t)token * 1024 + f8);
;                   r0 = (f32x4){bf2f(xu.x & 0xffffu), bf2f(xu.x >> 16), bf2f(xu.y & 0xffffu), bf2f(xu.y >> 16)};
;                   r1 = (f32x4){bf2f(xu.z & 0xffffu), bf2f(xu.z >> 16), bf2f(xu.w & 0xffffu), bf2f(xu.w >> 16)};
;                 }
;                 r0 += v; r1 += v1;
;                 st_bf8(xr + (size_t)token * 1024 + f8, r0, r1, 1.f);
;                 ssq += r0[0] * r0[0] + r0[1] * r0[1] + r0[2] * r0[2] + r0[3] * r0[3] + r1[0] * r1[0] + r1[1] * r1[1] + r1[2] * r1[2] + r1[3] * r1[3];
;               }
;             } else {
;               if (n == 0) {
;                 const f32x4 v1 = acc[ai][bj][m][1];
;                 u32x4 o4;
;                 { const float t0 = fmaxf(v[0], 0.f) * rinv, t1 = fmaxf(v[1], 0.f) * rinv, t2 = fmaxf(v[2], 0.f) * rinv, t3 = fmaxf(v[3], 0.f) * rinv;
;                   o4.x = pack2(t0 * t0, t1 * t1); o4.y = pack2(t2 * t2, t3 * t3); }
;                 { const float t0 = fmaxf(v1[0], 0.f) * rinv, t1 = fmaxf(v1[1], 0.f) * rinv, t2 = fmaxf(v1[2], 0.f) * rinv, t3 = fmaxf(v1[3], 0.f) * rinv;
;                   o4.z = pack2(t0 * t0, t1 * t1); o4.w = pack2(t2 * t2, t3 * t3); }
;                 *(u32x4*)((u16*)big + (size_t)token * 4096 + u.pn * 256 + bj * 128 + wc * 32 + 8 * fq) = o4;
;               }
;             }
;           }
;         if (EPI == EPI_RESID) {
;           ssq += shx(ssq, 16, t_ & 63);
;           ssq += shx(ssq, 32, t_ & 63);
;           if (fq == 0) ss_out[(size_t)token * 16 + u.pn * 4 + wc] = ssq;
;         }
	ds_read_b128 v[138:141], v224
	ds_read_b128 v[148:151], v224 offset:1024
	ds_read_b128 v[152:155], v224 offset:2048
	ds_read_b128 v[156:159], v224 offset:3072
	v_mfma_f32_16x16x32_bf16 v[52:55], v[208:211], v[160:163], v[52:55]
	v_mfma_f32_16x16x32_bf16 v[48:51], v[216:219], v[160:163], v[48:51]
	v_mfma_f32_16x16x32_bf16 v[36:39], v[208:211], v[168:171], v[36:39]
	v_mfma_f32_16x16x32_bf16 v[32:35], v[216:219], v[168:171], v[32:35]
	v_mfma_f32_16x16x32_bf16 v[20:23], v[208:211], v[176:179], v[20:23]
	v_mfma_f32_16x16x32_bf16 v[16:19], v[216:219], v[176:179], v[16:19]
	v_mfma_f32_16x16x32_bf16 v[4:7], v[208:211], v[200:203], v[4:7]
	v_mfma_f32_16x16x32_bf16 v[0:3], v[216:219], v[200:203], v[0:3]
	v_mfma_f32_16x16x32_bf16 v[52:55], v[212:215], v[164:167], v[52:55]
	v_mfma_f32_16x16x32_bf16 v[48:51], v[220:223], v[164:167], v[48:51]
	v_mfma_f32_16x16x32_bf16 v[36:39], v[212:215], v[172:175], v[36:39]
	v_mfma_f32_16x16x32_bf16 v[32:35], v[220:223], v[172:175], v[32:35]
	v_mfma_f32_16x16x32_bf16 v[20:23], v[212:215], v[196:199], v[20:23]
	v_mfma_f32_16x16x32_bf16 v[16:19], v[220:223], v[196:199], v[16:19]
	v_mfma_f32_16x16x32_bf16 v[4:7], v[212:215], v[204:207], v[4:7]
	v_mfma_f32_16x16x32_bf16 v[0:3], v[220:223], v[204:207], v[0:3]
	s_add_i32 s50, s50, 2
	s_add_u32 s20, s20, 0x100
	s_addc_u32 s21, s21, 0
	s_add_u32 s24, s24, 0x100
	s_addc_u32 s49, s49, 0
	s_cmp_gt_u32 s50, 61
	s_barrier
	s_cbranch_scc0 .LBB0_1905
	s_waitcnt lgkmcnt(0)
	s_lshl_b32 s7, s18, 8
	v_mov_b32_e32 v139, v182
	s_add_i32 s7, s7, s44
	s_nop 0
	v_and_or_b32 v140, v139, 15, s7
	s_lshl_b32 s7, s16, 8
	v_bfe_u32 v141, v139, 4, 2
	s_or_b32 s7, s7, s45
	v_lshl_or_b32 v138, v141, 3, s7
	v_cmp_eq_u32_e32 vcc, 0, v141
	v_ashrrev_i32_e32 v141, 31, v140
	v_lshlrev_b32_e32 v139, 2, v139
	s_movk_i32 s7, 0x80
	v_lshlrev_b64 v[142:143], 11, v[140:141]
	v_bitop3_b32 v149, v139, 64, v190 bitop3:0x6c
	v_bitop3_b32 v148, v139, s7, v190 bitop3:0x6c
	v_ashrrev_i32_e32 v139, 31, v138
	v_lshl_add_u64 v[142:143], s[4:5], 0, v[142:143]
	v_lshl_add_u64 v[142:143], v[138:139], 1, v[142:143]
	global_load_dwordx4 v[150:153], v[142:143], off
	s_lshl_b32 s16, s16, 2
	s_ashr_i32 s17, s16, 31
	s_waitcnt vmcnt(0)
	v_lshlrev_b32_e32 v154, 16, v150
	v_and_b32_e32 v155, 0xffff0000, v150
	v_lshlrev_b32_e32 v150, 16, v151
	v_and_b32_e32 v151, 0xffff0000, v151
	v_lshlrev_b32_e32 v156, 16, v152
	v_and_b32_e32 v157, 0xffff0000, v152
	v_lshlrev_b32_e32 v152, 16, v153
	v_and_b32_e32 v153, 0xffff0000, v153
	v_pk_add_f32 v[126:127], v[126:127], v[150:151]
	v_pk_add_f32 v[124:125], v[124:125], v[154:155]
	v_pk_add_f32 v[150:151], v[122:123], v[152:153]
	v_pk_add_f32 v[152:153], v[120:121], v[156:157]
	v_cvt_pk_bf16_f32 v120, v124, v125
	v_cvt_pk_bf16_f32 v121, v126, v127
	v_cvt_pk_bf16_f32 v122, v152, v153
	v_cvt_pk_bf16_f32 v123, v150, v151
	global_store_dwordx4 v[142:143], v[120:123], off
	global_load_dwordx4 v[120:123], v[142:143], off offset:256
	v_mul_f32_e32 v154, v125, v125
	v_fmac_f32_e32 v154, v124, v124
	v_fmac_f32_e32 v154, v126, v126
	v_fmac_f32_e32 v154, v127, v127
	v_fmac_f32_e32 v154, v152, v152
	v_fmac_f32_e32 v154, v153, v153
	v_fmac_f32_e32 v154, v150, v150
	v_fmac_f32_e32 v154, v151, v151
	s_waitcnt vmcnt(0)
	v_lshlrev_b32_e32 v124, 16, v120
	v_and_b32_e32 v125, 0xffff0000, v120
	v_lshlrev_b32_e32 v120, 16, v121
	v_and_b32_e32 v121, 0xffff0000, v121
	v_lshlrev_b32_e32 v126, 16, v122
	v_and_b32_e32 v127, 0xffff0000, v122
	v_lshlrev_b32_e32 v122, 16, v123
	v_and_b32_e32 v123, 0xffff0000, v123
	v_pk_add_f32 v[118:119], v[118:119], v[120:121]
	v_pk_add_f32 v[116:117], v[116:117], v[124:125]
	v_pk_add_f32 v[120:121], v[114:115], v[122:123]
	v_pk_add_f32 v[122:123], v[112:113], v[126:127]
	v_cvt_pk_bf16_f32 v112, v116, v117
	v_cvt_pk_bf16_f32 v113, v118, v119
	v_cvt_pk_bf16_f32 v114, v122, v123
	v_cvt_pk_bf16_f32 v115, v120, v121
	global_store_dwordx4 v[142:143], v[112:115], off offset:256
	s_nop 1
	v_mul_f32_e32 v112, v117, v117
	v_fmac_f32_e32 v112, v116, v116
	v_fmac_f32_e32 v112, v118, v118
	v_fmac_f32_e32 v112, v119, v119
	v_fmac_f32_e32 v112, v122, v122
	v_fmac_f32_e32 v112, v123, v123
	v_fmac_f32_e32 v112, v120, v120
	v_fmac_f32_e32 v112, v121, v121
	v_add_f32_e32 v112, v154, v112
	ds_bpermute_b32 v113, v149, v112
	s_waitcnt lgkmcnt(0)
	v_add_f32_e32 v112, v112, v113
	ds_bpermute_b32 v113, v148, v112
	s_and_saveexec_b64 s[18:19], vcc
	s_cbranch_execz .LBB0_1908
	s_waitcnt lgkmcnt(0)
	v_add_f32_e32 v114, v112, v113
	v_lshlrev_b64 v[112:113], 6, v[140:141]
	v_lshl_add_u64 v[112:113], s[2:3], 0, v[112:113]
	v_lshl_add_u64 v[112:113], s[16:17], 2, v[112:113]
	s_lshl_b32 s24, s43, 2
	v_lshl_add_u64 v[112:113], v[112:113], 0, s[24:25]
	global_store_dword v[112:113], v114, off
